# diff_finish2: xsum32 butterfly stages xor1/2/4/8 as DPP adds (bit-identical) instead of dependent ds_swizzle round trips; the 16 independent row blocks interleaved pairwise on fresh temporaries so two
# speedup vs baseline: 1.0119x; 1.0050x over previous
.LBB0_1174:
	s_or_b64 exec, exec, s[4:5]
	s_waitcnt lgkmcnt(0)
	v_lshlrev_b32_e32 v2, 2, v158
	global_load_dword v249, v2, s[0:1]
	global_load_dword v250, v2, s[0:1] offset:128
	global_load_dword v251, v2, s[0:1] offset:256
	global_load_dword v253, v2, s[0:1] offset:384
	v_add_u32_e32 v10, s19, v148
	s_lshl_b64 s[4:5], s[10:11], 13
	s_add_u32 s4, s86, s4
	s_addc_u32 s5, s87, s5
	s_add_u32 s6, s4, s46
	s_addc_u32 s7, s5, 0
	s_waitcnt vmcnt(0)
	v_mul_f32_e32 v7, v164, v249
	v_mul_f32_e32 v9, v164, v250
	v_mul_f32_e32 v6, v164, v251
	v_mul_f32_e32 v8, v164, v253
	v_lshl_or_b32 v2, v159, 14, v158
	ds_read_b32 v11, v10
	ds_read2st64_b32 v[4:5], v1 offset1:16
	ds_read_b32 v23, v10 offset:4
	ds_read2st64_b32 v[16:17], v1 offset0:1 offset1:17
	s_waitcnt lgkmcnt(0)
	v_fma_f32 v12, v84, v11, -v4
	v_fma_f32 v13, v100, v11, -v5
	ds_read2st64_b32 v[4:5], v1 offset0:32 offset1:48
	v_mul_f32_e32 v14, v13, v13
	v_fmac_f32_e32 v14, v12, v12
	v_fma_f32 v24, v85, v23, -v16
	v_fma_f32 v25, v101, v23, -v17
	ds_read2st64_b32 v[16:17], v1 offset0:33 offset1:49
	v_mul_f32_e32 v26, v25, v25
	v_fmac_f32_e32 v26, v24, v24
	s_waitcnt lgkmcnt(0)
	v_fma_f32 v15, v116, v11, -v4
	v_fmac_f32_e32 v14, v15, v15
	v_fma_f32 v11, v132, v11, -v5
	v_fmac_f32_e32 v14, v11, v11
	s_nop 1
	v_add_f32_dpp v4, v14, v14 quad_perm:[1,0,3,2] row_mask:0xf bank_mask:0xf
	s_nop 1
	v_add_f32_dpp v4, v4, v4 quad_perm:[2,3,0,1] row_mask:0xf bank_mask:0xf
	s_nop 1
	v_add_f32_dpp v4, v4, v4 row_half_mirror row_mask:0xf bank_mask:0xf
	s_nop 1
	v_add_f32_dpp v4, v4, v4 row_mirror row_mask:0xf bank_mask:0xf
	ds_swizzle_b32 v5, v4 offset:swizzle(SWAP,16)
	v_fma_f32 v27, v117, v23, -v16
	v_fmac_f32_e32 v26, v27, v27
	v_fma_f32 v23, v133, v23, -v17
	v_fmac_f32_e32 v26, v23, v23
	s_nop 1
	v_add_f32_dpp v16, v26, v26 quad_perm:[1,0,3,2] row_mask:0xf bank_mask:0xf
	s_nop 1
	v_add_f32_dpp v16, v16, v16 quad_perm:[2,3,0,1] row_mask:0xf bank_mask:0xf
	s_nop 1
	v_add_f32_dpp v16, v16, v16 row_half_mirror row_mask:0xf bank_mask:0xf
	s_nop 1
	v_add_f32_dpp v16, v16, v16 row_mirror row_mask:0xf bank_mask:0xf
	ds_swizzle_b32 v17, v16 offset:swizzle(SWAP,16)
	s_waitcnt lgkmcnt(0)
	v_add_f32_e32 v4, v4, v5
	v_fmamk_f32 v4, v4, 0x3c000000, v254
	s_nop 0
	s_nop 0
	s_nop 0
	s_nop 1
	s_nop 1
	s_nop 0
	v_rsq_f32_e32 v14, v4
	s_nop 0
	v_mul_f32_e32 v4, v12, v14
	v_mul_f32_e32 v5, v13, v14
	v_mul_f32_e32 v4, v7, v4
	v_mul_f32_e32 v5, v9, v5
	v_cvt_pk_bf16_f32 v12, v4, v5
	v_lshl_add_u64 v[4:5], v[2:3], 1, s[6:7]
	global_store_short v[4:5], v12, off
	v_add_u32_e32 v4, 32, v2
	v_mov_b32_e32 v5, v3
	v_lshl_add_u64 v[4:5], v[4:5], 1, s[6:7]
	global_store_short_d16_hi v[4:5], v12, off
	v_mul_f32_e32 v4, v15, v14
	v_mul_f32_e32 v5, v11, v14
	v_mul_f32_e32 v4, v6, v4
	v_mul_f32_e32 v5, v8, v5
	v_cvt_pk_bf16_f32 v11, v4, v5
	v_add_u32_e32 v4, 64, v2
	v_mov_b32_e32 v5, v3
	v_lshl_add_u64 v[4:5], v[4:5], 1, s[6:7]
	global_store_short v[4:5], v11, off
	v_add_u32_e32 v4, 0x60, v2
	v_mov_b32_e32 v5, v3
	v_lshl_add_u64 v[4:5], v[4:5], 1, s[6:7]
	global_store_short_d16_hi v[4:5], v11, off
	v_add_f32_e32 v16, v16, v17
	v_fmamk_f32 v16, v16, 0x3c000000, v254
	s_nop 0
	s_nop 0
	s_nop 0
	s_nop 1
	s_nop 1
	s_nop 0
	v_rsq_f32_e32 v26, v16
	s_nop 0
	v_mul_f32_e32 v17, v24, v26
	v_mul_f32_e32 v24, v25, v26
	v_mul_f32_e32 v17, v7, v17
	v_mul_f32_e32 v24, v9, v24
	v_add_u32_e32 v16, 0x1000, v2
	v_cvt_pk_bf16_f32 v24, v17, v24
	v_mov_b32_e32 v17, v3
	v_lshl_add_u64 v[16:17], v[16:17], 1, s[6:7]
	global_store_short v[16:17], v24, off
	v_add_u32_e32 v16, 0x1020, v2
	v_mov_b32_e32 v17, v3
	v_lshl_add_u64 v[16:17], v[16:17], 1, s[6:7]
	global_store_short_d16_hi v[16:17], v24, off
	v_mul_f32_e32 v16, v27, v26
	v_mul_f32_e32 v17, v23, v26
	v_mul_f32_e32 v16, v6, v16
	v_mul_f32_e32 v17, v8, v17
	v_cvt_pk_bf16_f32 v23, v16, v17
	v_add_u32_e32 v16, 0x1040, v2
	v_mov_b32_e32 v17, v3
	v_lshl_add_u64 v[16:17], v[16:17], 1, s[6:7]
	global_store_short v[16:17], v23, off
	v_add_u32_e32 v16, 0x1060, v2
	v_mov_b32_e32 v17, v3
	v_lshl_add_u64 v[16:17], v[16:17], 1, s[6:7]
	global_store_short_d16_hi v[16:17], v23, off
	ds_read_b32 v11, v10 offset:8
	ds_read2st64_b32 v[4:5], v1 offset0:2 offset1:18
	ds_read_b32 v23, v10 offset:12
	ds_read2st64_b32 v[16:17], v1 offset0:3 offset1:19
	s_waitcnt lgkmcnt(0)
	v_fma_f32 v12, v86, v11, -v4
	v_fma_f32 v13, v102, v11, -v5
	ds_read2st64_b32 v[4:5], v1 offset0:34 offset1:50
	v_mul_f32_e32 v14, v13, v13
	v_fmac_f32_e32 v14, v12, v12
	v_fma_f32 v24, v87, v23, -v16
	v_fma_f32 v25, v103, v23, -v17
	ds_read2st64_b32 v[16:17], v1 offset0:35 offset1:51
	v_mul_f32_e32 v26, v25, v25
	v_fmac_f32_e32 v26, v24, v24
	s_waitcnt lgkmcnt(0)
	v_fma_f32 v15, v118, v11, -v4
	v_fmac_f32_e32 v14, v15, v15
	v_fma_f32 v11, v134, v11, -v5
	v_fmac_f32_e32 v14, v11, v11
	s_nop 1
	v_add_f32_dpp v4, v14, v14 quad_perm:[1,0,3,2] row_mask:0xf bank_mask:0xf
	s_nop 1
	v_add_f32_dpp v4, v4, v4 quad_perm:[2,3,0,1] row_mask:0xf bank_mask:0xf
	s_nop 1
	v_add_f32_dpp v4, v4, v4 row_half_mirror row_mask:0xf bank_mask:0xf
	s_nop 1
	v_add_f32_dpp v4, v4, v4 row_mirror row_mask:0xf bank_mask:0xf
	ds_swizzle_b32 v5, v4 offset:swizzle(SWAP,16)
	v_fma_f32 v27, v119, v23, -v16
	v_fmac_f32_e32 v26, v27, v27
	v_fma_f32 v23, v135, v23, -v17
	v_fmac_f32_e32 v26, v23, v23
	s_nop 1
	v_add_f32_dpp v16, v26, v26 quad_perm:[1,0,3,2] row_mask:0xf bank_mask:0xf
	s_nop 1
	v_add_f32_dpp v16, v16, v16 quad_perm:[2,3,0,1] row_mask:0xf bank_mask:0xf
	s_nop 1
	v_add_f32_dpp v16, v16, v16 row_half_mirror row_mask:0xf bank_mask:0xf
	s_nop 1
	v_add_f32_dpp v16, v16, v16 row_mirror row_mask:0xf bank_mask:0xf
	ds_swizzle_b32 v17, v16 offset:swizzle(SWAP,16)
	s_waitcnt lgkmcnt(0)
	v_add_f32_e32 v4, v4, v5
	v_fmamk_f32 v4, v4, 0x3c000000, v254
	s_nop 0
	s_nop 0
	s_nop 0
	s_nop 1
	s_nop 1
	s_nop 0
	v_rsq_f32_e32 v14, v4
	s_nop 0
	v_mul_f32_e32 v5, v12, v14
	v_mul_f32_e32 v12, v13, v14
	v_mul_f32_e32 v5, v7, v5
	v_mul_f32_e32 v12, v9, v12
	v_add_u32_e32 v4, 0x2000, v2
	v_cvt_pk_bf16_f32 v12, v5, v12
	v_mov_b32_e32 v5, v3
	v_lshl_add_u64 v[4:5], v[4:5], 1, s[6:7]
	global_store_short v[4:5], v12, off
	v_add_u32_e32 v4, 0x2020, v2
	v_mov_b32_e32 v5, v3
	v_lshl_add_u64 v[4:5], v[4:5], 1, s[6:7]
	global_store_short_d16_hi v[4:5], v12, off
	v_mul_f32_e32 v4, v15, v14
	v_mul_f32_e32 v5, v11, v14
	v_mul_f32_e32 v4, v6, v4
	v_mul_f32_e32 v5, v8, v5
	v_cvt_pk_bf16_f32 v11, v4, v5
	v_add_u32_e32 v4, 0x2040, v2
	v_mov_b32_e32 v5, v3
	v_lshl_add_u64 v[4:5], v[4:5], 1, s[6:7]
	global_store_short v[4:5], v11, off
	v_add_u32_e32 v4, 0x2060, v2
	v_mov_b32_e32 v5, v3
	v_lshl_add_u64 v[4:5], v[4:5], 1, s[6:7]
	global_store_short_d16_hi v[4:5], v11, off
	v_add_f32_e32 v16, v16, v17
	v_fmamk_f32 v16, v16, 0x3c000000, v254
	s_nop 0
	s_nop 0
	s_nop 0
	s_nop 1
	s_nop 1
	s_nop 0
	v_rsq_f32_e32 v26, v16
	s_nop 0
	v_mul_f32_e32 v17, v24, v26
	v_mul_f32_e32 v24, v25, v26
	v_mul_f32_e32 v17, v7, v17
	v_mul_f32_e32 v24, v9, v24
	v_add_u32_e32 v16, 0x3000, v2
	v_cvt_pk_bf16_f32 v24, v17, v24
	v_mov_b32_e32 v17, v3
	v_lshl_add_u64 v[16:17], v[16:17], 1, s[6:7]
	global_store_short v[16:17], v24, off
	v_add_u32_e32 v16, 0x3020, v2
	v_mov_b32_e32 v17, v3
	v_lshl_add_u64 v[16:17], v[16:17], 1, s[6:7]
	global_store_short_d16_hi v[16:17], v24, off
	v_mul_f32_e32 v16, v27, v26
	v_mul_f32_e32 v17, v23, v26
	v_mul_f32_e32 v16, v6, v16
	v_mul_f32_e32 v17, v8, v17
	v_cvt_pk_bf16_f32 v23, v16, v17
	v_add_u32_e32 v16, 0x3040, v2
	v_mov_b32_e32 v17, v3
	v_lshl_add_u64 v[16:17], v[16:17], 1, s[6:7]
	global_store_short v[16:17], v23, off
	v_add_u32_e32 v16, 0x3060, v2
	v_mov_b32_e32 v17, v3
	v_lshl_add_u64 v[16:17], v[16:17], 1, s[6:7]
	global_store_short_d16_hi v[16:17], v23, off
	ds_read_b32 v11, v10 offset:32
	ds_read2st64_b32 v[4:5], v1 offset0:4 offset1:20
	ds_read_b32 v23, v10 offset:36
	ds_read2st64_b32 v[16:17], v1 offset0:5 offset1:21
	s_waitcnt lgkmcnt(0)
	v_fma_f32 v12, v88, v11, -v4
	v_fma_f32 v13, v104, v11, -v5
	ds_read2st64_b32 v[4:5], v1 offset0:36 offset1:52
	v_mul_f32_e32 v14, v13, v13
	v_fmac_f32_e32 v14, v12, v12
	v_fma_f32 v24, v89, v23, -v16
	v_fma_f32 v25, v105, v23, -v17
	ds_read2st64_b32 v[16:17], v1 offset0:37 offset1:53
	v_mul_f32_e32 v26, v25, v25
	v_fmac_f32_e32 v26, v24, v24
	s_waitcnt lgkmcnt(0)
	v_fma_f32 v15, v120, v11, -v4
	v_fmac_f32_e32 v14, v15, v15
	v_fma_f32 v11, v136, v11, -v5
	v_fmac_f32_e32 v14, v11, v11
	s_nop 1
	v_add_f32_dpp v4, v14, v14 quad_perm:[1,0,3,2] row_mask:0xf bank_mask:0xf
	s_nop 1
	v_add_f32_dpp v4, v4, v4 quad_perm:[2,3,0,1] row_mask:0xf bank_mask:0xf
	s_nop 1
	v_add_f32_dpp v4, v4, v4 row_half_mirror row_mask:0xf bank_mask:0xf
	s_nop 1
	v_add_f32_dpp v4, v4, v4 row_mirror row_mask:0xf bank_mask:0xf
	ds_swizzle_b32 v5, v4 offset:swizzle(SWAP,16)
	v_fma_f32 v27, v121, v23, -v16
	v_fmac_f32_e32 v26, v27, v27
	v_fma_f32 v23, v137, v23, -v17
	v_fmac_f32_e32 v26, v23, v23
	s_nop 1
	v_add_f32_dpp v16, v26, v26 quad_perm:[1,0,3,2] row_mask:0xf bank_mask:0xf
	s_nop 1
	v_add_f32_dpp v16, v16, v16 quad_perm:[2,3,0,1] row_mask:0xf bank_mask:0xf
	s_nop 1
	v_add_f32_dpp v16, v16, v16 row_half_mirror row_mask:0xf bank_mask:0xf
	s_nop 1
	v_add_f32_dpp v16, v16, v16 row_mirror row_mask:0xf bank_mask:0xf
	ds_swizzle_b32 v17, v16 offset:swizzle(SWAP,16)
	s_waitcnt lgkmcnt(0)
	v_add_f32_e32 v4, v4, v5
	v_fmamk_f32 v4, v4, 0x3c000000, v254
	s_nop 0
	s_nop 0
	s_nop 0
	s_nop 1
	s_nop 1
	s_nop 0
	v_rsq_f32_e32 v14, v4
	s_nop 0
	v_mul_f32_e32 v5, v12, v14
	v_mul_f32_e32 v12, v13, v14
	v_mul_f32_e32 v5, v7, v5
	v_mul_f32_e32 v12, v9, v12
	v_add_u32_e32 v4, 0x8000, v2
	v_cvt_pk_bf16_f32 v12, v5, v12
	v_mov_b32_e32 v5, v3
	v_lshl_add_u64 v[4:5], v[4:5], 1, s[6:7]
	global_store_short v[4:5], v12, off
	v_add_u32_e32 v4, 0x8020, v2
	v_mov_b32_e32 v5, v3
	v_lshl_add_u64 v[4:5], v[4:5], 1, s[6:7]
	global_store_short_d16_hi v[4:5], v12, off
	v_mul_f32_e32 v4, v15, v14
	v_mul_f32_e32 v5, v11, v14
	v_mul_f32_e32 v4, v6, v4
	v_mul_f32_e32 v5, v8, v5
	v_cvt_pk_bf16_f32 v11, v4, v5
	v_add_u32_e32 v4, 0x8040, v2
	v_mov_b32_e32 v5, v3
	v_lshl_add_u64 v[4:5], v[4:5], 1, s[6:7]
	global_store_short v[4:5], v11, off
	v_add_u32_e32 v4, 0x8060, v2
	v_mov_b32_e32 v5, v3
	v_lshl_add_u64 v[4:5], v[4:5], 1, s[6:7]
	global_store_short_d16_hi v[4:5], v11, off
	v_add_f32_e32 v16, v16, v17
	v_fmamk_f32 v16, v16, 0x3c000000, v254
	s_nop 0
	s_nop 0
	s_nop 0
	s_nop 1
	s_nop 1
	s_nop 0
	v_rsq_f32_e32 v26, v16
	s_nop 0
	v_mul_f32_e32 v17, v24, v26
	v_mul_f32_e32 v24, v25, v26
	v_mul_f32_e32 v17, v7, v17
	v_mul_f32_e32 v24, v9, v24
	v_add_u32_e32 v16, 0x9000, v2
	v_cvt_pk_bf16_f32 v24, v17, v24
	v_mov_b32_e32 v17, v3
	v_lshl_add_u64 v[16:17], v[16:17], 1, s[6:7]
	global_store_short v[16:17], v24, off
	v_add_u32_e32 v16, 0x9020, v2
	v_mov_b32_e32 v17, v3
	v_lshl_add_u64 v[16:17], v[16:17], 1, s[6:7]
	global_store_short_d16_hi v[16:17], v24, off
	v_mul_f32_e32 v16, v27, v26
	v_mul_f32_e32 v17, v23, v26
	v_mul_f32_e32 v16, v6, v16
	v_mul_f32_e32 v17, v8, v17
	v_cvt_pk_bf16_f32 v23, v16, v17
	v_add_u32_e32 v16, 0x9040, v2
	v_mov_b32_e32 v17, v3
	v_lshl_add_u64 v[16:17], v[16:17], 1, s[6:7]
	global_store_short v[16:17], v23, off
	v_add_u32_e32 v16, 0x9060, v2
	v_mov_b32_e32 v17, v3
	v_lshl_add_u64 v[16:17], v[16:17], 1, s[6:7]
	global_store_short_d16_hi v[16:17], v23, off
	ds_read_b32 v11, v10 offset:40
	ds_read2st64_b32 v[4:5], v1 offset0:6 offset1:22
	ds_read_b32 v23, v10 offset:44
	ds_read2st64_b32 v[16:17], v1 offset0:7 offset1:23
	s_waitcnt lgkmcnt(0)
	v_fma_f32 v12, v90, v11, -v4
	v_fma_f32 v13, v106, v11, -v5
	ds_read2st64_b32 v[4:5], v1 offset0:38 offset1:54
	v_mul_f32_e32 v14, v13, v13
	v_fmac_f32_e32 v14, v12, v12
	v_fma_f32 v24, v91, v23, -v16
	v_fma_f32 v25, v107, v23, -v17
	ds_read2st64_b32 v[16:17], v1 offset0:39 offset1:55
	v_mul_f32_e32 v26, v25, v25
	v_fmac_f32_e32 v26, v24, v24
	s_waitcnt lgkmcnt(0)
	v_fma_f32 v15, v122, v11, -v4
	v_fmac_f32_e32 v14, v15, v15
	v_fma_f32 v11, v138, v11, -v5
	v_fmac_f32_e32 v14, v11, v11
	s_nop 1
	v_add_f32_dpp v4, v14, v14 quad_perm:[1,0,3,2] row_mask:0xf bank_mask:0xf
	s_nop 1
	v_add_f32_dpp v4, v4, v4 quad_perm:[2,3,0,1] row_mask:0xf bank_mask:0xf
	s_nop 1
	v_add_f32_dpp v4, v4, v4 row_half_mirror row_mask:0xf bank_mask:0xf
	s_nop 1
	v_add_f32_dpp v4, v4, v4 row_mirror row_mask:0xf bank_mask:0xf
	ds_swizzle_b32 v5, v4 offset:swizzle(SWAP,16)
	v_fma_f32 v27, v123, v23, -v16
	v_fmac_f32_e32 v26, v27, v27
	v_fma_f32 v23, v139, v23, -v17
	v_fmac_f32_e32 v26, v23, v23
	s_nop 1
	v_add_f32_dpp v16, v26, v26 quad_perm:[1,0,3,2] row_mask:0xf bank_mask:0xf
	s_nop 1
	v_add_f32_dpp v16, v16, v16 quad_perm:[2,3,0,1] row_mask:0xf bank_mask:0xf
	s_nop 1
	v_add_f32_dpp v16, v16, v16 row_half_mirror row_mask:0xf bank_mask:0xf
	s_nop 1
	v_add_f32_dpp v16, v16, v16 row_mirror row_mask:0xf bank_mask:0xf
	ds_swizzle_b32 v17, v16 offset:swizzle(SWAP,16)
	s_waitcnt lgkmcnt(0)
	v_add_f32_e32 v4, v4, v5
	v_fmamk_f32 v4, v4, 0x3c000000, v254
	s_nop 0
	s_nop 0
	s_nop 0
	s_nop 1
	s_nop 1
	s_nop 0
	v_rsq_f32_e32 v14, v4
	s_nop 0
	v_mul_f32_e32 v5, v12, v14
	v_mul_f32_e32 v12, v13, v14
	v_mul_f32_e32 v5, v7, v5
	v_mul_f32_e32 v12, v9, v12
	v_add_u32_e32 v4, 0xa000, v2
	v_cvt_pk_bf16_f32 v12, v5, v12
	v_mov_b32_e32 v5, v3
	v_lshl_add_u64 v[4:5], v[4:5], 1, s[6:7]
	global_store_short v[4:5], v12, off
	v_add_u32_e32 v4, 0xa020, v2
	v_mov_b32_e32 v5, v3
	v_lshl_add_u64 v[4:5], v[4:5], 1, s[6:7]
	global_store_short_d16_hi v[4:5], v12, off
	v_mul_f32_e32 v4, v15, v14
	v_mul_f32_e32 v5, v11, v14
	v_mul_f32_e32 v4, v6, v4
	v_mul_f32_e32 v5, v8, v5
	v_cvt_pk_bf16_f32 v11, v4, v5
	v_add_u32_e32 v4, 0xa040, v2
	v_mov_b32_e32 v5, v3
	v_lshl_add_u64 v[4:5], v[4:5], 1, s[6:7]
	global_store_short v[4:5], v11, off
	v_add_u32_e32 v4, 0xa060, v2
	v_mov_b32_e32 v5, v3
	v_lshl_add_u64 v[4:5], v[4:5], 1, s[6:7]
	global_store_short_d16_hi v[4:5], v11, off
	v_add_f32_e32 v16, v16, v17
	v_fmamk_f32 v16, v16, 0x3c000000, v254
	s_nop 0
	s_nop 0
	s_nop 0
	s_nop 1
	s_nop 1
	s_nop 0
	v_rsq_f32_e32 v26, v16
	s_nop 0
	v_mul_f32_e32 v17, v24, v26
	v_mul_f32_e32 v24, v25, v26
	v_mul_f32_e32 v17, v7, v17
	v_mul_f32_e32 v24, v9, v24
	v_add_u32_e32 v16, 0xb000, v2
	v_cvt_pk_bf16_f32 v24, v17, v24
	v_mov_b32_e32 v17, v3
	v_lshl_add_u64 v[16:17], v[16:17], 1, s[6:7]
	global_store_short v[16:17], v24, off
	v_add_u32_e32 v16, 0xb020, v2
	v_mov_b32_e32 v17, v3
	v_lshl_add_u64 v[16:17], v[16:17], 1, s[6:7]
	global_store_short_d16_hi v[16:17], v24, off
	v_mul_f32_e32 v16, v27, v26
	v_mul_f32_e32 v17, v23, v26
	v_mul_f32_e32 v16, v6, v16
	v_mul_f32_e32 v17, v8, v17
	v_cvt_pk_bf16_f32 v23, v16, v17
	v_add_u32_e32 v16, 0xb040, v2
	v_mov_b32_e32 v17, v3
	v_lshl_add_u64 v[16:17], v[16:17], 1, s[6:7]
	global_store_short v[16:17], v23, off
	v_add_u32_e32 v16, 0xb060, v2
	v_mov_b32_e32 v17, v3
	v_lshl_add_u64 v[16:17], v[16:17], 1, s[6:7]
	global_store_short_d16_hi v[16:17], v23, off
	ds_read_b32 v11, v10 offset:64
	ds_read2st64_b32 v[4:5], v1 offset0:8 offset1:24
	ds_read_b32 v23, v10 offset:68
	ds_read2st64_b32 v[16:17], v1 offset0:9 offset1:25
	s_waitcnt lgkmcnt(0)
	v_fma_f32 v12, v92, v11, -v4
	v_fma_f32 v13, v108, v11, -v5
	ds_read2st64_b32 v[4:5], v1 offset0:40 offset1:56
	v_mul_f32_e32 v14, v13, v13
	v_fmac_f32_e32 v14, v12, v12
	v_fma_f32 v24, v93, v23, -v16
	v_fma_f32 v25, v109, v23, -v17
	ds_read2st64_b32 v[16:17], v1 offset0:41 offset1:57
	v_mul_f32_e32 v26, v25, v25
	v_fmac_f32_e32 v26, v24, v24
	s_waitcnt lgkmcnt(0)
	v_fma_f32 v15, v124, v11, -v4
	v_fmac_f32_e32 v14, v15, v15
	v_fma_f32 v11, v140, v11, -v5
	v_fmac_f32_e32 v14, v11, v11
	s_nop 1
	v_add_f32_dpp v4, v14, v14 quad_perm:[1,0,3,2] row_mask:0xf bank_mask:0xf
	s_nop 1
	v_add_f32_dpp v4, v4, v4 quad_perm:[2,3,0,1] row_mask:0xf bank_mask:0xf
	s_nop 1
	v_add_f32_dpp v4, v4, v4 row_half_mirror row_mask:0xf bank_mask:0xf
	s_nop 1
	v_add_f32_dpp v4, v4, v4 row_mirror row_mask:0xf bank_mask:0xf
	ds_swizzle_b32 v5, v4 offset:swizzle(SWAP,16)
	v_fma_f32 v27, v125, v23, -v16
	v_fmac_f32_e32 v26, v27, v27
	v_fma_f32 v23, v141, v23, -v17
	v_fmac_f32_e32 v26, v23, v23
	s_nop 1
	v_add_f32_dpp v16, v26, v26 quad_perm:[1,0,3,2] row_mask:0xf bank_mask:0xf
	s_nop 1
	v_add_f32_dpp v16, v16, v16 quad_perm:[2,3,0,1] row_mask:0xf bank_mask:0xf
	s_nop 1
	v_add_f32_dpp v16, v16, v16 row_half_mirror row_mask:0xf bank_mask:0xf
	s_nop 1
	v_add_f32_dpp v16, v16, v16 row_mirror row_mask:0xf bank_mask:0xf
	ds_swizzle_b32 v17, v16 offset:swizzle(SWAP,16)
	s_waitcnt lgkmcnt(0)
	v_add_f32_e32 v4, v4, v5
	v_fmamk_f32 v4, v4, 0x3c000000, v254
	s_nop 0
	s_nop 0
	s_nop 0
	s_nop 1
	s_nop 1
	s_nop 0
	v_rsq_f32_e32 v14, v4
	s_nop 0
	v_mul_f32_e32 v5, v12, v14
	v_mul_f32_e32 v12, v13, v14
	v_mul_f32_e32 v5, v7, v5
	v_mul_f32_e32 v12, v9, v12
	v_add_u32_e32 v4, 0x10000, v2
	v_cvt_pk_bf16_f32 v12, v5, v12
	v_mov_b32_e32 v5, v3
	v_lshl_add_u64 v[4:5], v[4:5], 1, s[6:7]
	global_store_short v[4:5], v12, off
	v_add_u32_e32 v4, 0x10020, v2
	v_mov_b32_e32 v5, v3
	v_lshl_add_u64 v[4:5], v[4:5], 1, s[6:7]
	global_store_short_d16_hi v[4:5], v12, off
	v_mul_f32_e32 v4, v15, v14
	v_mul_f32_e32 v5, v11, v14
	v_mul_f32_e32 v4, v6, v4
	v_mul_f32_e32 v5, v8, v5
	v_cvt_pk_bf16_f32 v11, v4, v5
	v_add_u32_e32 v4, 0x10040, v2
	v_mov_b32_e32 v5, v3
	v_lshl_add_u64 v[4:5], v[4:5], 1, s[6:7]
	global_store_short v[4:5], v11, off
	v_add_u32_e32 v4, 0x10060, v2
	v_mov_b32_e32 v5, v3
	v_lshl_add_u64 v[4:5], v[4:5], 1, s[6:7]
	global_store_short_d16_hi v[4:5], v11, off
	v_add_f32_e32 v16, v16, v17
	v_fmamk_f32 v16, v16, 0x3c000000, v254
	s_nop 0
	s_nop 0
	s_nop 0
	s_nop 1
	s_nop 1
	s_nop 0
	v_rsq_f32_e32 v26, v16
	s_nop 0
	v_mul_f32_e32 v17, v24, v26
	v_mul_f32_e32 v24, v25, v26
	v_mul_f32_e32 v17, v7, v17
	v_mul_f32_e32 v24, v9, v24
	v_add_u32_e32 v16, 0x11000, v2
	v_cvt_pk_bf16_f32 v24, v17, v24
	v_mov_b32_e32 v17, v3
	v_lshl_add_u64 v[16:17], v[16:17], 1, s[6:7]
	global_store_short v[16:17], v24, off
	v_add_u32_e32 v16, 0x11020, v2
	v_mov_b32_e32 v17, v3
	v_lshl_add_u64 v[16:17], v[16:17], 1, s[6:7]
	global_store_short_d16_hi v[16:17], v24, off
	v_mul_f32_e32 v16, v27, v26
	v_mul_f32_e32 v17, v23, v26
	v_mul_f32_e32 v16, v6, v16
	v_mul_f32_e32 v17, v8, v17
	v_cvt_pk_bf16_f32 v23, v16, v17
	v_add_u32_e32 v16, 0x11040, v2
	v_mov_b32_e32 v17, v3
	v_lshl_add_u64 v[16:17], v[16:17], 1, s[6:7]
	global_store_short v[16:17], v23, off
	v_add_u32_e32 v16, 0x11060, v2
	v_mov_b32_e32 v17, v3
	v_lshl_add_u64 v[16:17], v[16:17], 1, s[6:7]
	global_store_short_d16_hi v[16:17], v23, off
	ds_read_b32 v11, v10 offset:72
	ds_read2st64_b32 v[4:5], v1 offset0:10 offset1:26
	ds_read_b32 v23, v10 offset:76
	ds_read2st64_b32 v[16:17], v1 offset0:11 offset1:27
	s_waitcnt lgkmcnt(0)
	v_fma_f32 v12, v94, v11, -v4
	v_fma_f32 v13, v110, v11, -v5
	ds_read2st64_b32 v[4:5], v1 offset0:42 offset1:58
	v_mul_f32_e32 v14, v13, v13
	v_fmac_f32_e32 v14, v12, v12
	v_fma_f32 v24, v95, v23, -v16
	v_fma_f32 v25, v111, v23, -v17
	ds_read2st64_b32 v[16:17], v1 offset0:43 offset1:59
	v_mul_f32_e32 v26, v25, v25
	v_fmac_f32_e32 v26, v24, v24
	s_waitcnt lgkmcnt(0)
	v_fma_f32 v15, v126, v11, -v4
	v_fmac_f32_e32 v14, v15, v15
	v_fma_f32 v11, v142, v11, -v5
	v_fmac_f32_e32 v14, v11, v11
	s_nop 1
	v_add_f32_dpp v4, v14, v14 quad_perm:[1,0,3,2] row_mask:0xf bank_mask:0xf
	s_nop 1
	v_add_f32_dpp v4, v4, v4 quad_perm:[2,3,0,1] row_mask:0xf bank_mask:0xf
	s_nop 1
	v_add_f32_dpp v4, v4, v4 row_half_mirror row_mask:0xf bank_mask:0xf
	s_nop 1
	v_add_f32_dpp v4, v4, v4 row_mirror row_mask:0xf bank_mask:0xf
	ds_swizzle_b32 v5, v4 offset:swizzle(SWAP,16)
	v_fma_f32 v27, v127, v23, -v16
	v_fmac_f32_e32 v26, v27, v27
	v_fma_f32 v23, v143, v23, -v17
	v_fmac_f32_e32 v26, v23, v23
	s_nop 1
	v_add_f32_dpp v16, v26, v26 quad_perm:[1,0,3,2] row_mask:0xf bank_mask:0xf
	s_nop 1
	v_add_f32_dpp v16, v16, v16 quad_perm:[2,3,0,1] row_mask:0xf bank_mask:0xf
	s_nop 1
	v_add_f32_dpp v16, v16, v16 row_half_mirror row_mask:0xf bank_mask:0xf
	s_nop 1
	v_add_f32_dpp v16, v16, v16 row_mirror row_mask:0xf bank_mask:0xf
	ds_swizzle_b32 v17, v16 offset:swizzle(SWAP,16)
	s_waitcnt lgkmcnt(0)
	v_add_f32_e32 v4, v4, v5
	v_fmamk_f32 v4, v4, 0x3c000000, v254
	s_nop 0
	s_nop 0
	s_nop 0
	s_nop 1
	s_nop 1
	s_nop 0
	v_rsq_f32_e32 v14, v4
	s_nop 0
	v_mul_f32_e32 v5, v12, v14
	v_mul_f32_e32 v12, v13, v14
	v_mul_f32_e32 v5, v7, v5
	v_mul_f32_e32 v12, v9, v12
	v_add_u32_e32 v4, 0x12000, v2
	v_cvt_pk_bf16_f32 v12, v5, v12
	v_mov_b32_e32 v5, v3
	v_lshl_add_u64 v[4:5], v[4:5], 1, s[6:7]
	global_store_short v[4:5], v12, off
	v_add_u32_e32 v4, 0x12020, v2
	v_mov_b32_e32 v5, v3
	v_lshl_add_u64 v[4:5], v[4:5], 1, s[6:7]
	global_store_short_d16_hi v[4:5], v12, off
	v_mul_f32_e32 v4, v15, v14
	v_mul_f32_e32 v5, v11, v14
	v_mul_f32_e32 v4, v6, v4
	v_mul_f32_e32 v5, v8, v5
	v_cvt_pk_bf16_f32 v11, v4, v5
	v_add_u32_e32 v4, 0x12040, v2
	v_mov_b32_e32 v5, v3
	v_lshl_add_u64 v[4:5], v[4:5], 1, s[6:7]
	global_store_short v[4:5], v11, off
	v_add_u32_e32 v4, 0x12060, v2
	v_mov_b32_e32 v5, v3
	v_lshl_add_u64 v[4:5], v[4:5], 1, s[6:7]
	global_store_short_d16_hi v[4:5], v11, off
	v_add_f32_e32 v16, v16, v17
	v_fmamk_f32 v16, v16, 0x3c000000, v254
	s_nop 0
	s_nop 0
	s_nop 0
	s_nop 1
	s_nop 1
	s_nop 0
	v_rsq_f32_e32 v26, v16
	s_nop 0
	v_mul_f32_e32 v17, v24, v26
	v_mul_f32_e32 v24, v25, v26
	v_mul_f32_e32 v17, v7, v17
	v_mul_f32_e32 v24, v9, v24
	v_add_u32_e32 v16, 0x13000, v2
	v_cvt_pk_bf16_f32 v24, v17, v24
	v_mov_b32_e32 v17, v3
	v_lshl_add_u64 v[16:17], v[16:17], 1, s[6:7]
	global_store_short v[16:17], v24, off
	v_add_u32_e32 v16, 0x13020, v2
	v_mov_b32_e32 v17, v3
	v_lshl_add_u64 v[16:17], v[16:17], 1, s[6:7]
	global_store_short_d16_hi v[16:17], v24, off
	v_mul_f32_e32 v16, v27, v26
	v_mul_f32_e32 v17, v23, v26
	v_mul_f32_e32 v16, v6, v16
	v_mul_f32_e32 v17, v8, v17
	v_cvt_pk_bf16_f32 v23, v16, v17
	v_add_u32_e32 v16, 0x13040, v2
	v_mov_b32_e32 v17, v3
	v_lshl_add_u64 v[16:17], v[16:17], 1, s[6:7]
	global_store_short v[16:17], v23, off
	v_add_u32_e32 v16, 0x13060, v2
	v_mov_b32_e32 v17, v3
	v_lshl_add_u64 v[16:17], v[16:17], 1, s[6:7]
	global_store_short_d16_hi v[16:17], v23, off
	ds_read_b32 v11, v10 offset:96
	ds_read2st64_b32 v[4:5], v1 offset0:12 offset1:28
	ds_read_b32 v23, v10 offset:100
	ds_read2st64_b32 v[16:17], v1 offset0:13 offset1:29
	s_waitcnt lgkmcnt(0)
	v_fma_f32 v12, v96, v11, -v4
	v_fma_f32 v13, v112, v11, -v5
	ds_read2st64_b32 v[4:5], v1 offset0:44 offset1:60
	v_mul_f32_e32 v14, v13, v13
	v_fmac_f32_e32 v14, v12, v12
	v_fma_f32 v24, v97, v23, -v16
	v_fma_f32 v25, v113, v23, -v17
	ds_read2st64_b32 v[16:17], v1 offset0:45 offset1:61
	v_mul_f32_e32 v26, v25, v25
	v_fmac_f32_e32 v26, v24, v24
	s_waitcnt lgkmcnt(0)
	v_fma_f32 v15, v128, v11, -v4
	v_fmac_f32_e32 v14, v15, v15
	v_fma_f32 v11, v144, v11, -v5
	v_fmac_f32_e32 v14, v11, v11
	s_nop 1
	v_add_f32_dpp v4, v14, v14 quad_perm:[1,0,3,2] row_mask:0xf bank_mask:0xf
	s_nop 1
	v_add_f32_dpp v4, v4, v4 quad_perm:[2,3,0,1] row_mask:0xf bank_mask:0xf
	s_nop 1
	v_add_f32_dpp v4, v4, v4 row_half_mirror row_mask:0xf bank_mask:0xf
	s_nop 1
	v_add_f32_dpp v4, v4, v4 row_mirror row_mask:0xf bank_mask:0xf
	ds_swizzle_b32 v5, v4 offset:swizzle(SWAP,16)
	v_fma_f32 v27, v129, v23, -v16
	v_fmac_f32_e32 v26, v27, v27
	v_fma_f32 v23, v145, v23, -v17
	v_fmac_f32_e32 v26, v23, v23
	s_nop 1
	v_add_f32_dpp v16, v26, v26 quad_perm:[1,0,3,2] row_mask:0xf bank_mask:0xf
	s_nop 1
	v_add_f32_dpp v16, v16, v16 quad_perm:[2,3,0,1] row_mask:0xf bank_mask:0xf
	s_nop 1
	v_add_f32_dpp v16, v16, v16 row_half_mirror row_mask:0xf bank_mask:0xf
	s_nop 1
	v_add_f32_dpp v16, v16, v16 row_mirror row_mask:0xf bank_mask:0xf
	ds_swizzle_b32 v17, v16 offset:swizzle(SWAP,16)
	s_waitcnt lgkmcnt(0)
	v_add_f32_e32 v4, v4, v5
	v_fmamk_f32 v4, v4, 0x3c000000, v254
	s_nop 0
	s_nop 0
	s_nop 0
	s_nop 1
	s_nop 1
	s_nop 0
	v_rsq_f32_e32 v14, v4
	s_nop 0
	v_mul_f32_e32 v5, v12, v14
	v_mul_f32_e32 v12, v13, v14
	v_mul_f32_e32 v5, v7, v5
	v_mul_f32_e32 v12, v9, v12
	v_add_u32_e32 v4, 0x18000, v2
	v_cvt_pk_bf16_f32 v12, v5, v12
	v_mov_b32_e32 v5, v3
	v_lshl_add_u64 v[4:5], v[4:5], 1, s[6:7]
	global_store_short v[4:5], v12, off
	v_add_u32_e32 v4, 0x18020, v2
	v_mov_b32_e32 v5, v3
	v_lshl_add_u64 v[4:5], v[4:5], 1, s[6:7]
	global_store_short_d16_hi v[4:5], v12, off
	v_mul_f32_e32 v4, v15, v14
	v_mul_f32_e32 v5, v11, v14
	v_mul_f32_e32 v4, v6, v4
	v_mul_f32_e32 v5, v8, v5
	v_cvt_pk_bf16_f32 v11, v4, v5
	v_add_u32_e32 v4, 0x18040, v2
	v_mov_b32_e32 v5, v3
	v_lshl_add_u64 v[4:5], v[4:5], 1, s[6:7]
	global_store_short v[4:5], v11, off
	v_add_u32_e32 v4, 0x18060, v2
	v_mov_b32_e32 v5, v3
	v_lshl_add_u64 v[4:5], v[4:5], 1, s[6:7]
	global_store_short_d16_hi v[4:5], v11, off
	v_add_f32_e32 v16, v16, v17
	v_fmamk_f32 v16, v16, 0x3c000000, v254
	s_nop 0
	s_nop 0
	s_nop 0
	s_nop 1
	s_nop 1
	s_nop 0
	v_rsq_f32_e32 v26, v16
	s_nop 0
	v_mul_f32_e32 v17, v24, v26
	v_mul_f32_e32 v24, v25, v26
	v_mul_f32_e32 v17, v7, v17
	v_mul_f32_e32 v24, v9, v24
	v_add_u32_e32 v16, 0x19000, v2
	v_cvt_pk_bf16_f32 v24, v17, v24
	v_mov_b32_e32 v17, v3
	v_lshl_add_u64 v[16:17], v[16:17], 1, s[6:7]
	global_store_short v[16:17], v24, off
	v_add_u32_e32 v16, 0x19020, v2
	v_mov_b32_e32 v17, v3
	v_lshl_add_u64 v[16:17], v[16:17], 1, s[6:7]
	global_store_short_d16_hi v[16:17], v24, off
	v_mul_f32_e32 v16, v27, v26
	v_mul_f32_e32 v17, v23, v26
	v_mul_f32_e32 v16, v6, v16
	v_mul_f32_e32 v17, v8, v17
	v_cvt_pk_bf16_f32 v23, v16, v17
	v_add_u32_e32 v16, 0x19040, v2
	v_mov_b32_e32 v17, v3
	v_lshl_add_u64 v[16:17], v[16:17], 1, s[6:7]
	global_store_short v[16:17], v23, off
	v_add_u32_e32 v16, 0x19060, v2
	v_mov_b32_e32 v17, v3
	v_lshl_add_u64 v[16:17], v[16:17], 1, s[6:7]
	global_store_short_d16_hi v[16:17], v23, off
	ds_read_b32 v11, v10 offset:104
	ds_read2st64_b32 v[4:5], v1 offset0:14 offset1:30
	s_waitcnt lgkmcnt(0)
	v_fma_f32 v12, v98, v11, -v4
	v_fma_f32 v13, v114, v11, -v5
	ds_read2st64_b32 v[4:5], v1 offset0:46 offset1:62
	v_mul_f32_e32 v14, v13, v13
	v_fmac_f32_e32 v14, v12, v12
	s_waitcnt lgkmcnt(0)
	v_fma_f32 v15, v130, v11, -v4
	v_fmac_f32_e32 v14, v15, v15
	v_fma_f32 v11, v146, v11, -v5
	v_fmac_f32_e32 v14, v11, v11
	s_nop 1
	v_add_f32_dpp v4, v14, v14 quad_perm:[1,0,3,2] row_mask:0xf bank_mask:0xf
	s_nop 1
	v_add_f32_dpp v4, v4, v4 quad_perm:[2,3,0,1] row_mask:0xf bank_mask:0xf
	s_nop 1
	v_add_f32_dpp v4, v4, v4 row_half_mirror row_mask:0xf bank_mask:0xf
	s_nop 1
	v_add_f32_dpp v4, v4, v4 row_mirror row_mask:0xf bank_mask:0xf
	ds_swizzle_b32 v5, v4 offset:swizzle(SWAP,16)
	s_waitcnt lgkmcnt(0)
	v_add_f32_e32 v4, v4, v5
	v_fmamk_f32 v4, v4, 0x3c000000, v254
	s_nop 0
	s_nop 0
	s_nop 0
	s_nop 1
	s_nop 1
	s_nop 0
	v_rsq_f32_e32 v14, v4
	s_nop 0
	v_mul_f32_e32 v5, v12, v14
	v_mul_f32_e32 v12, v13, v14
	v_mul_f32_e32 v5, v7, v5
	v_mul_f32_e32 v12, v9, v12
	v_add_u32_e32 v4, 0x1a000, v2
	v_cvt_pk_bf16_f32 v12, v5, v12
	v_mov_b32_e32 v5, v3
	v_lshl_add_u64 v[4:5], v[4:5], 1, s[6:7]
	global_store_short v[4:5], v12, off
	v_add_u32_e32 v4, 0x1a020, v2
	v_mov_b32_e32 v5, v3
	v_lshl_add_u64 v[4:5], v[4:5], 1, s[6:7]
	global_store_short_d16_hi v[4:5], v12, off
	v_mul_f32_e32 v4, v15, v14
	v_mul_f32_e32 v5, v11, v14
	v_mul_f32_e32 v4, v6, v4
	v_mul_f32_e32 v5, v8, v5
	v_cvt_pk_bf16_f32 v11, v4, v5
	v_add_u32_e32 v4, 0x1a040, v2
	v_mov_b32_e32 v5, v3
	v_lshl_add_u64 v[4:5], v[4:5], 1, s[6:7]
	global_store_short v[4:5], v11, off
	v_add_u32_e32 v4, 0x1a060, v2
	v_mov_b32_e32 v5, v3
	v_lshl_add_u64 v[4:5], v[4:5], 1, s[6:7]
	global_store_short_d16_hi v[4:5], v11, off
	ds_read_b32 v10, v10 offset:108
	ds_read2st64_b32 v[4:5], v1 offset0:15 offset1:31
	s_waitcnt lgkmcnt(0)
	v_fma_f32 v11, v99, v10, -v4
	v_fma_f32 v12, v115, v10, -v5
	ds_read2st64_b32 v[4:5], v1 offset0:47 offset1:63
	v_mul_f32_e32 v13, v12, v12
	v_fmac_f32_e32 v13, v11, v11
	s_waitcnt lgkmcnt(0)
	v_fma_f32 v1, v131, v10, -v4
	v_fmac_f32_e32 v13, v1, v1
	v_fma_f32 v10, v147, v10, -v5
	v_fmac_f32_e32 v13, v10, v10
	s_nop 1
	v_add_f32_dpp v4, v13, v13 quad_perm:[1,0,3,2] row_mask:0xf bank_mask:0xf
	s_nop 1
	v_add_f32_dpp v4, v4, v4 quad_perm:[2,3,0,1] row_mask:0xf bank_mask:0xf
	s_nop 1
	v_add_f32_dpp v4, v4, v4 row_half_mirror row_mask:0xf bank_mask:0xf
	s_nop 1
	v_add_f32_dpp v4, v4, v4 row_mirror row_mask:0xf bank_mask:0xf
	ds_swizzle_b32 v5, v4 offset:swizzle(SWAP,16)
	s_waitcnt lgkmcnt(0)
	v_add_f32_e32 v4, v4, v5
	v_fmamk_f32 v4, v4, 0x3c000000, v254
	s_nop 0
	s_nop 0
	s_nop 0
	s_nop 1
	s_nop 1
	s_nop 0
	v_rsq_f32_e32 v13, v4
	s_nop 0
	v_mul_f32_e32 v5, v11, v13
	v_mul_f32_e32 v5, v7, v5
	v_mul_f32_e32 v7, v12, v13
	v_mul_f32_e32 v7, v9, v7
	v_add_u32_e32 v4, 0x1b000, v2
	v_cvt_pk_bf16_f32 v7, v5, v7
	v_mov_b32_e32 v5, v3
	v_lshl_add_u64 v[4:5], v[4:5], 1, s[6:7]
	global_store_short v[4:5], v7, off
	v_add_u32_e32 v4, 0x1b020, v2
	v_mov_b32_e32 v5, v3
	v_lshl_add_u64 v[4:5], v[4:5], 1, s[6:7]
	global_store_short_d16_hi v[4:5], v7, off
	v_mul_f32_e32 v1, v1, v13
	v_mul_f32_e32 v4, v10, v13
	v_mul_f32_e32 v1, v6, v1
	v_mul_f32_e32 v4, v8, v4
	v_cvt_pk_bf16_f32 v1, v1, v4
	v_add_u32_e32 v4, 0x1b040, v2
	v_mov_b32_e32 v5, v3
	v_lshl_add_u64 v[4:5], v[4:5], 1, s[6:7]
	v_add_u32_e32 v2, 0x1b060, v2
	global_store_short v[4:5], v1, off
	v_lshl_add_u64 v[4:5], v[2:3], 1, s[6:7]
	global_store_short_d16_hi v[4:5], v1, off

.LBB0_1239:
	s_or_b64 exec, exec, s[4:5]
	s_waitcnt lgkmcnt(0)
	v_lshlrev_b32_e32 v2, 2, v158
	global_load_dword v249, v2, s[0:1]
	global_load_dword v250, v2, s[0:1] offset:128
	global_load_dword v251, v2, s[0:1] offset:256
	global_load_dword v253, v2, s[0:1] offset:384
	v_add_u32_e32 v10, s43, v148
	s_lshl_b64 s[4:5], s[24:25], 13
	s_add_u32 s4, s86, s4
	s_addc_u32 s5, s87, s5
	s_lshl_b32 s6, s8, 1
	s_add_u32 s6, s4, s6
	s_addc_u32 s7, s5, 0
	s_waitcnt vmcnt(0)
	v_mul_f32_e32 v7, v164, v249
	v_mul_f32_e32 v9, v164, v250
	v_mul_f32_e32 v6, v164, v251
	v_mul_f32_e32 v8, v164, v253
	v_lshl_or_b32 v2, v159, 14, v158
	ds_read_b32 v11, v10
	ds_read2st64_b32 v[4:5], v1 offset1:16
	ds_read_b32 v23, v10 offset:4
	ds_read2st64_b32 v[16:17], v1 offset0:1 offset1:17
	s_waitcnt lgkmcnt(0)
	v_fma_f32 v12, v68, v11, -v4
	v_fma_f32 v13, v84, v11, -v5
	ds_read2st64_b32 v[4:5], v1 offset0:32 offset1:48
	v_mul_f32_e32 v14, v13, v13
	v_fmac_f32_e32 v14, v12, v12
	v_fma_f32 v24, v69, v23, -v16
	v_fma_f32 v25, v85, v23, -v17
	ds_read2st64_b32 v[16:17], v1 offset0:33 offset1:49
	v_mul_f32_e32 v26, v25, v25
	v_fmac_f32_e32 v26, v24, v24
	s_waitcnt lgkmcnt(0)
	v_fma_f32 v15, v100, v11, -v4
	v_fmac_f32_e32 v14, v15, v15
	v_fma_f32 v11, v116, v11, -v5
	v_fmac_f32_e32 v14, v11, v11
	s_nop 1
	v_add_f32_dpp v4, v14, v14 quad_perm:[1,0,3,2] row_mask:0xf bank_mask:0xf
	s_nop 1
	v_add_f32_dpp v4, v4, v4 quad_perm:[2,3,0,1] row_mask:0xf bank_mask:0xf
	s_nop 1
	v_add_f32_dpp v4, v4, v4 row_half_mirror row_mask:0xf bank_mask:0xf
	s_nop 1
	v_add_f32_dpp v4, v4, v4 row_mirror row_mask:0xf bank_mask:0xf
	ds_swizzle_b32 v5, v4 offset:swizzle(SWAP,16)
	v_fma_f32 v27, v101, v23, -v16
	v_fmac_f32_e32 v26, v27, v27
	v_fma_f32 v23, v117, v23, -v17
	v_fmac_f32_e32 v26, v23, v23
	s_nop 1
	v_add_f32_dpp v16, v26, v26 quad_perm:[1,0,3,2] row_mask:0xf bank_mask:0xf
	s_nop 1
	v_add_f32_dpp v16, v16, v16 quad_perm:[2,3,0,1] row_mask:0xf bank_mask:0xf
	s_nop 1
	v_add_f32_dpp v16, v16, v16 row_half_mirror row_mask:0xf bank_mask:0xf
	s_nop 1
	v_add_f32_dpp v16, v16, v16 row_mirror row_mask:0xf bank_mask:0xf
	ds_swizzle_b32 v17, v16 offset:swizzle(SWAP,16)
	s_waitcnt lgkmcnt(0)
	v_add_f32_e32 v4, v4, v5
	v_fmamk_f32 v4, v4, 0x3c000000, v254
	s_nop 0
	s_nop 0
	s_nop 0
	s_nop 1
	s_nop 1
	s_nop 0
	v_rsq_f32_e32 v14, v4
	s_nop 0
	v_mul_f32_e32 v4, v12, v14
	v_mul_f32_e32 v5, v13, v14
	v_mul_f32_e32 v4, v7, v4
	v_mul_f32_e32 v5, v9, v5
	v_cvt_pk_bf16_f32 v12, v4, v5
	v_lshl_add_u64 v[4:5], v[2:3], 1, s[6:7]
	global_store_short v[4:5], v12, off
	v_add_u32_e32 v4, 32, v2
	v_mov_b32_e32 v5, v3
	v_lshl_add_u64 v[4:5], v[4:5], 1, s[6:7]
	global_store_short_d16_hi v[4:5], v12, off
	v_mul_f32_e32 v4, v15, v14
	v_mul_f32_e32 v5, v11, v14
	v_mul_f32_e32 v4, v6, v4
	v_mul_f32_e32 v5, v8, v5
	v_cvt_pk_bf16_f32 v11, v4, v5
	v_add_u32_e32 v4, 64, v2
	v_mov_b32_e32 v5, v3
	v_lshl_add_u64 v[4:5], v[4:5], 1, s[6:7]
	global_store_short v[4:5], v11, off
	v_add_u32_e32 v4, 0x60, v2
	v_mov_b32_e32 v5, v3
	v_lshl_add_u64 v[4:5], v[4:5], 1, s[6:7]
	global_store_short_d16_hi v[4:5], v11, off
	v_add_f32_e32 v16, v16, v17
	v_fmamk_f32 v16, v16, 0x3c000000, v254
	s_nop 0
	s_nop 0
	s_nop 0
	s_nop 1
	s_nop 1
	s_nop 0
	v_rsq_f32_e32 v26, v16
	s_nop 0
	v_mul_f32_e32 v17, v24, v26
	v_mul_f32_e32 v24, v25, v26
	v_mul_f32_e32 v17, v7, v17
	v_mul_f32_e32 v24, v9, v24
	v_add_u32_e32 v16, 0x1000, v2
	v_cvt_pk_bf16_f32 v24, v17, v24
	v_mov_b32_e32 v17, v3
	v_lshl_add_u64 v[16:17], v[16:17], 1, s[6:7]
	global_store_short v[16:17], v24, off
	v_add_u32_e32 v16, 0x1020, v2
	v_mov_b32_e32 v17, v3
	v_lshl_add_u64 v[16:17], v[16:17], 1, s[6:7]
	global_store_short_d16_hi v[16:17], v24, off
	v_mul_f32_e32 v16, v27, v26
	v_mul_f32_e32 v17, v23, v26
	v_mul_f32_e32 v16, v6, v16
	v_mul_f32_e32 v17, v8, v17
	v_cvt_pk_bf16_f32 v23, v16, v17
	v_add_u32_e32 v16, 0x1040, v2
	v_mov_b32_e32 v17, v3
	v_lshl_add_u64 v[16:17], v[16:17], 1, s[6:7]
	global_store_short v[16:17], v23, off
	v_add_u32_e32 v16, 0x1060, v2
	v_mov_b32_e32 v17, v3
	v_lshl_add_u64 v[16:17], v[16:17], 1, s[6:7]
	global_store_short_d16_hi v[16:17], v23, off
	ds_read_b32 v11, v10 offset:8
	ds_read2st64_b32 v[4:5], v1 offset0:2 offset1:18
	ds_read_b32 v23, v10 offset:12
	ds_read2st64_b32 v[16:17], v1 offset0:3 offset1:19
	s_waitcnt lgkmcnt(0)
	v_fma_f32 v12, v70, v11, -v4
	v_fma_f32 v13, v86, v11, -v5
	ds_read2st64_b32 v[4:5], v1 offset0:34 offset1:50
	v_mul_f32_e32 v14, v13, v13
	v_fmac_f32_e32 v14, v12, v12
	v_fma_f32 v24, v71, v23, -v16
	v_fma_f32 v25, v87, v23, -v17
	ds_read2st64_b32 v[16:17], v1 offset0:35 offset1:51
	v_mul_f32_e32 v26, v25, v25
	v_fmac_f32_e32 v26, v24, v24
	s_waitcnt lgkmcnt(0)
	v_fma_f32 v15, v102, v11, -v4
	v_fmac_f32_e32 v14, v15, v15
	v_fma_f32 v11, v118, v11, -v5
	v_fmac_f32_e32 v14, v11, v11
	s_nop 1
	v_add_f32_dpp v4, v14, v14 quad_perm:[1,0,3,2] row_mask:0xf bank_mask:0xf
	s_nop 1
	v_add_f32_dpp v4, v4, v4 quad_perm:[2,3,0,1] row_mask:0xf bank_mask:0xf
	s_nop 1
	v_add_f32_dpp v4, v4, v4 row_half_mirror row_mask:0xf bank_mask:0xf
	s_nop 1
	v_add_f32_dpp v4, v4, v4 row_mirror row_mask:0xf bank_mask:0xf
	ds_swizzle_b32 v5, v4 offset:swizzle(SWAP,16)
	v_fma_f32 v27, v103, v23, -v16
	v_fmac_f32_e32 v26, v27, v27
	v_fma_f32 v23, v119, v23, -v17
	v_fmac_f32_e32 v26, v23, v23
	s_nop 1
	v_add_f32_dpp v16, v26, v26 quad_perm:[1,0,3,2] row_mask:0xf bank_mask:0xf
	s_nop 1
	v_add_f32_dpp v16, v16, v16 quad_perm:[2,3,0,1] row_mask:0xf bank_mask:0xf
	s_nop 1
	v_add_f32_dpp v16, v16, v16 row_half_mirror row_mask:0xf bank_mask:0xf
	s_nop 1
	v_add_f32_dpp v16, v16, v16 row_mirror row_mask:0xf bank_mask:0xf
	ds_swizzle_b32 v17, v16 offset:swizzle(SWAP,16)
	s_waitcnt lgkmcnt(0)
	v_add_f32_e32 v4, v4, v5
	v_fmamk_f32 v4, v4, 0x3c000000, v254
	s_nop 0
	s_nop 0
	s_nop 0
	s_nop 1
	s_nop 1
	s_nop 0
	v_rsq_f32_e32 v14, v4
	s_nop 0
	v_mul_f32_e32 v5, v12, v14
	v_mul_f32_e32 v12, v13, v14
	v_mul_f32_e32 v5, v7, v5
	v_mul_f32_e32 v12, v9, v12
	v_add_u32_e32 v4, 0x2000, v2
	v_cvt_pk_bf16_f32 v12, v5, v12
	v_mov_b32_e32 v5, v3
	v_lshl_add_u64 v[4:5], v[4:5], 1, s[6:7]
	global_store_short v[4:5], v12, off
	v_add_u32_e32 v4, 0x2020, v2
	v_mov_b32_e32 v5, v3
	v_lshl_add_u64 v[4:5], v[4:5], 1, s[6:7]
	global_store_short_d16_hi v[4:5], v12, off
	v_mul_f32_e32 v4, v15, v14
	v_mul_f32_e32 v5, v11, v14
	v_mul_f32_e32 v4, v6, v4
	v_mul_f32_e32 v5, v8, v5
	v_cvt_pk_bf16_f32 v11, v4, v5
	v_add_u32_e32 v4, 0x2040, v2
	v_mov_b32_e32 v5, v3
	v_lshl_add_u64 v[4:5], v[4:5], 1, s[6:7]
	global_store_short v[4:5], v11, off
	v_add_u32_e32 v4, 0x2060, v2
	v_mov_b32_e32 v5, v3
	v_lshl_add_u64 v[4:5], v[4:5], 1, s[6:7]
	global_store_short_d16_hi v[4:5], v11, off
	v_add_f32_e32 v16, v16, v17
	v_fmamk_f32 v16, v16, 0x3c000000, v254
	s_nop 0
	s_nop 0
	s_nop 0
	s_nop 1
	s_nop 1
	s_nop 0
	v_rsq_f32_e32 v26, v16
	s_nop 0
	v_mul_f32_e32 v17, v24, v26
	v_mul_f32_e32 v24, v25, v26
	v_mul_f32_e32 v17, v7, v17
	v_mul_f32_e32 v24, v9, v24
	v_add_u32_e32 v16, 0x3000, v2
	v_cvt_pk_bf16_f32 v24, v17, v24
	v_mov_b32_e32 v17, v3
	v_lshl_add_u64 v[16:17], v[16:17], 1, s[6:7]
	global_store_short v[16:17], v24, off
	v_add_u32_e32 v16, 0x3020, v2
	v_mov_b32_e32 v17, v3
	v_lshl_add_u64 v[16:17], v[16:17], 1, s[6:7]
	global_store_short_d16_hi v[16:17], v24, off
	v_mul_f32_e32 v16, v27, v26
	v_mul_f32_e32 v17, v23, v26
	v_mul_f32_e32 v16, v6, v16
	v_mul_f32_e32 v17, v8, v17
	v_cvt_pk_bf16_f32 v23, v16, v17
	v_add_u32_e32 v16, 0x3040, v2
	v_mov_b32_e32 v17, v3
	v_lshl_add_u64 v[16:17], v[16:17], 1, s[6:7]
	global_store_short v[16:17], v23, off
	v_add_u32_e32 v16, 0x3060, v2
	v_mov_b32_e32 v17, v3
	v_lshl_add_u64 v[16:17], v[16:17], 1, s[6:7]
	global_store_short_d16_hi v[16:17], v23, off
	ds_read_b32 v11, v10 offset:32
	ds_read2st64_b32 v[4:5], v1 offset0:4 offset1:20
	ds_read_b32 v23, v10 offset:36
	ds_read2st64_b32 v[16:17], v1 offset0:5 offset1:21
	s_waitcnt lgkmcnt(0)
	v_fma_f32 v12, v72, v11, -v4
	v_fma_f32 v13, v88, v11, -v5
	ds_read2st64_b32 v[4:5], v1 offset0:36 offset1:52
	v_mul_f32_e32 v14, v13, v13
	v_fmac_f32_e32 v14, v12, v12
	v_fma_f32 v24, v73, v23, -v16
	v_fma_f32 v25, v89, v23, -v17
	ds_read2st64_b32 v[16:17], v1 offset0:37 offset1:53
	v_mul_f32_e32 v26, v25, v25
	v_fmac_f32_e32 v26, v24, v24
	s_waitcnt lgkmcnt(0)
	v_fma_f32 v15, v104, v11, -v4
	v_fmac_f32_e32 v14, v15, v15
	v_fma_f32 v11, v120, v11, -v5
	v_fmac_f32_e32 v14, v11, v11
	s_nop 1
	v_add_f32_dpp v4, v14, v14 quad_perm:[1,0,3,2] row_mask:0xf bank_mask:0xf
	s_nop 1
	v_add_f32_dpp v4, v4, v4 quad_perm:[2,3,0,1] row_mask:0xf bank_mask:0xf
	s_nop 1
	v_add_f32_dpp v4, v4, v4 row_half_mirror row_mask:0xf bank_mask:0xf
	s_nop 1
	v_add_f32_dpp v4, v4, v4 row_mirror row_mask:0xf bank_mask:0xf
	ds_swizzle_b32 v5, v4 offset:swizzle(SWAP,16)
	v_fma_f32 v27, v105, v23, -v16
	v_fmac_f32_e32 v26, v27, v27
	v_fma_f32 v23, v121, v23, -v17
	v_fmac_f32_e32 v26, v23, v23
	s_nop 1
	v_add_f32_dpp v16, v26, v26 quad_perm:[1,0,3,2] row_mask:0xf bank_mask:0xf
	s_nop 1
	v_add_f32_dpp v16, v16, v16 quad_perm:[2,3,0,1] row_mask:0xf bank_mask:0xf
	s_nop 1
	v_add_f32_dpp v16, v16, v16 row_half_mirror row_mask:0xf bank_mask:0xf
	s_nop 1
	v_add_f32_dpp v16, v16, v16 row_mirror row_mask:0xf bank_mask:0xf
	ds_swizzle_b32 v17, v16 offset:swizzle(SWAP,16)
	s_waitcnt lgkmcnt(0)
	v_add_f32_e32 v4, v4, v5
	v_fmamk_f32 v4, v4, 0x3c000000, v254
	s_nop 0
	s_nop 0
	s_nop 0
	s_nop 1
	s_nop 1
	s_nop 0
	v_rsq_f32_e32 v14, v4
	s_nop 0
	v_mul_f32_e32 v5, v12, v14
	v_mul_f32_e32 v12, v13, v14
	v_mul_f32_e32 v5, v7, v5
	v_mul_f32_e32 v12, v9, v12
	v_add_u32_e32 v4, 0x8000, v2
	v_cvt_pk_bf16_f32 v12, v5, v12
	v_mov_b32_e32 v5, v3
	v_lshl_add_u64 v[4:5], v[4:5], 1, s[6:7]
	global_store_short v[4:5], v12, off
	v_add_u32_e32 v4, 0x8020, v2
	v_mov_b32_e32 v5, v3
	v_lshl_add_u64 v[4:5], v[4:5], 1, s[6:7]
	global_store_short_d16_hi v[4:5], v12, off
	v_mul_f32_e32 v4, v15, v14
	v_mul_f32_e32 v5, v11, v14
	v_mul_f32_e32 v4, v6, v4
	v_mul_f32_e32 v5, v8, v5
	v_cvt_pk_bf16_f32 v11, v4, v5
	v_add_u32_e32 v4, 0x8040, v2
	v_mov_b32_e32 v5, v3
	v_lshl_add_u64 v[4:5], v[4:5], 1, s[6:7]
	global_store_short v[4:5], v11, off
	v_add_u32_e32 v4, 0x8060, v2
	v_mov_b32_e32 v5, v3
	v_lshl_add_u64 v[4:5], v[4:5], 1, s[6:7]
	global_store_short_d16_hi v[4:5], v11, off
	v_add_f32_e32 v16, v16, v17
	v_fmamk_f32 v16, v16, 0x3c000000, v254
	s_nop 0
	s_nop 0
	s_nop 0
	s_nop 1
	s_nop 1
	s_nop 0
	v_rsq_f32_e32 v26, v16
	s_nop 0
	v_mul_f32_e32 v17, v24, v26
	v_mul_f32_e32 v24, v25, v26
	v_mul_f32_e32 v17, v7, v17
	v_mul_f32_e32 v24, v9, v24
	v_add_u32_e32 v16, 0x9000, v2
	v_cvt_pk_bf16_f32 v24, v17, v24
	v_mov_b32_e32 v17, v3
	v_lshl_add_u64 v[16:17], v[16:17], 1, s[6:7]
	global_store_short v[16:17], v24, off
	v_add_u32_e32 v16, 0x9020, v2
	v_mov_b32_e32 v17, v3
	v_lshl_add_u64 v[16:17], v[16:17], 1, s[6:7]
	global_store_short_d16_hi v[16:17], v24, off
	v_mul_f32_e32 v16, v27, v26
	v_mul_f32_e32 v17, v23, v26
	v_mul_f32_e32 v16, v6, v16
	v_mul_f32_e32 v17, v8, v17
	v_cvt_pk_bf16_f32 v23, v16, v17
	v_add_u32_e32 v16, 0x9040, v2
	v_mov_b32_e32 v17, v3
	v_lshl_add_u64 v[16:17], v[16:17], 1, s[6:7]
	global_store_short v[16:17], v23, off
	v_add_u32_e32 v16, 0x9060, v2
	v_mov_b32_e32 v17, v3
	v_lshl_add_u64 v[16:17], v[16:17], 1, s[6:7]
	global_store_short_d16_hi v[16:17], v23, off
	ds_read_b32 v11, v10 offset:40
	ds_read2st64_b32 v[4:5], v1 offset0:6 offset1:22
	ds_read_b32 v23, v10 offset:44
	ds_read2st64_b32 v[16:17], v1 offset0:7 offset1:23
	s_waitcnt lgkmcnt(0)
	v_fma_f32 v12, v74, v11, -v4
	v_fma_f32 v13, v90, v11, -v5
	ds_read2st64_b32 v[4:5], v1 offset0:38 offset1:54
	v_mul_f32_e32 v14, v13, v13
	v_fmac_f32_e32 v14, v12, v12
	v_fma_f32 v24, v75, v23, -v16
	v_fma_f32 v25, v91, v23, -v17
	ds_read2st64_b32 v[16:17], v1 offset0:39 offset1:55
	v_mul_f32_e32 v26, v25, v25
	v_fmac_f32_e32 v26, v24, v24
	s_waitcnt lgkmcnt(0)
	v_fma_f32 v15, v106, v11, -v4
	v_fmac_f32_e32 v14, v15, v15
	v_fma_f32 v11, v122, v11, -v5
	v_fmac_f32_e32 v14, v11, v11
	s_nop 1
	v_add_f32_dpp v4, v14, v14 quad_perm:[1,0,3,2] row_mask:0xf bank_mask:0xf
	s_nop 1
	v_add_f32_dpp v4, v4, v4 quad_perm:[2,3,0,1] row_mask:0xf bank_mask:0xf
	s_nop 1
	v_add_f32_dpp v4, v4, v4 row_half_mirror row_mask:0xf bank_mask:0xf
	s_nop 1
	v_add_f32_dpp v4, v4, v4 row_mirror row_mask:0xf bank_mask:0xf
	ds_swizzle_b32 v5, v4 offset:swizzle(SWAP,16)
	v_fma_f32 v27, v107, v23, -v16
	v_fmac_f32_e32 v26, v27, v27
	v_fma_f32 v23, v123, v23, -v17
	v_fmac_f32_e32 v26, v23, v23
	s_nop 1
	v_add_f32_dpp v16, v26, v26 quad_perm:[1,0,3,2] row_mask:0xf bank_mask:0xf
	s_nop 1
	v_add_f32_dpp v16, v16, v16 quad_perm:[2,3,0,1] row_mask:0xf bank_mask:0xf
	s_nop 1
	v_add_f32_dpp v16, v16, v16 row_half_mirror row_mask:0xf bank_mask:0xf
	s_nop 1
	v_add_f32_dpp v16, v16, v16 row_mirror row_mask:0xf bank_mask:0xf
	ds_swizzle_b32 v17, v16 offset:swizzle(SWAP,16)
	s_waitcnt lgkmcnt(0)
	v_add_f32_e32 v4, v4, v5
	v_fmamk_f32 v4, v4, 0x3c000000, v254
	s_nop 0
	s_nop 0
	s_nop 0
	s_nop 1
	s_nop 1
	s_nop 0
	v_rsq_f32_e32 v14, v4
	s_nop 0
	v_mul_f32_e32 v5, v12, v14
	v_mul_f32_e32 v12, v13, v14
	v_mul_f32_e32 v5, v7, v5
	v_mul_f32_e32 v12, v9, v12
	v_add_u32_e32 v4, 0xa000, v2
	v_cvt_pk_bf16_f32 v12, v5, v12
	v_mov_b32_e32 v5, v3
	v_lshl_add_u64 v[4:5], v[4:5], 1, s[6:7]
	global_store_short v[4:5], v12, off
	v_add_u32_e32 v4, 0xa020, v2
	v_mov_b32_e32 v5, v3
	v_lshl_add_u64 v[4:5], v[4:5], 1, s[6:7]
	global_store_short_d16_hi v[4:5], v12, off
	v_mul_f32_e32 v4, v15, v14
	v_mul_f32_e32 v5, v11, v14
	v_mul_f32_e32 v4, v6, v4
	v_mul_f32_e32 v5, v8, v5
	v_cvt_pk_bf16_f32 v11, v4, v5
	v_add_u32_e32 v4, 0xa040, v2
	v_mov_b32_e32 v5, v3
	v_lshl_add_u64 v[4:5], v[4:5], 1, s[6:7]
	global_store_short v[4:5], v11, off
	v_add_u32_e32 v4, 0xa060, v2
	v_mov_b32_e32 v5, v3
	v_lshl_add_u64 v[4:5], v[4:5], 1, s[6:7]
	global_store_short_d16_hi v[4:5], v11, off
	v_add_f32_e32 v16, v16, v17
	v_fmamk_f32 v16, v16, 0x3c000000, v254
	s_nop 0
	s_nop 0
	s_nop 0
	s_nop 1
	s_nop 1
	s_nop 0
	v_rsq_f32_e32 v26, v16
	s_nop 0
	v_mul_f32_e32 v17, v24, v26
	v_mul_f32_e32 v24, v25, v26
	v_mul_f32_e32 v17, v7, v17
	v_mul_f32_e32 v24, v9, v24
	v_add_u32_e32 v16, 0xb000, v2
	v_cvt_pk_bf16_f32 v24, v17, v24
	v_mov_b32_e32 v17, v3
	v_lshl_add_u64 v[16:17], v[16:17], 1, s[6:7]
	global_store_short v[16:17], v24, off
	v_add_u32_e32 v16, 0xb020, v2
	v_mov_b32_e32 v17, v3
	v_lshl_add_u64 v[16:17], v[16:17], 1, s[6:7]
	global_store_short_d16_hi v[16:17], v24, off
	v_mul_f32_e32 v16, v27, v26
	v_mul_f32_e32 v17, v23, v26
	v_mul_f32_e32 v16, v6, v16
	v_mul_f32_e32 v17, v8, v17
	v_cvt_pk_bf16_f32 v23, v16, v17
	v_add_u32_e32 v16, 0xb040, v2
	v_mov_b32_e32 v17, v3
	v_lshl_add_u64 v[16:17], v[16:17], 1, s[6:7]
	global_store_short v[16:17], v23, off
	v_add_u32_e32 v16, 0xb060, v2
	v_mov_b32_e32 v17, v3
	v_lshl_add_u64 v[16:17], v[16:17], 1, s[6:7]
	global_store_short_d16_hi v[16:17], v23, off
	ds_read_b32 v11, v10 offset:64
	ds_read2st64_b32 v[4:5], v1 offset0:8 offset1:24
	ds_read_b32 v23, v10 offset:68
	ds_read2st64_b32 v[16:17], v1 offset0:9 offset1:25
	s_waitcnt lgkmcnt(0)
	v_fma_f32 v12, v76, v11, -v4
	v_fma_f32 v13, v92, v11, -v5
	ds_read2st64_b32 v[4:5], v1 offset0:40 offset1:56
	v_mul_f32_e32 v14, v13, v13
	v_fmac_f32_e32 v14, v12, v12
	v_fma_f32 v24, v77, v23, -v16
	v_fma_f32 v25, v93, v23, -v17
	ds_read2st64_b32 v[16:17], v1 offset0:41 offset1:57
	v_mul_f32_e32 v26, v25, v25
	v_fmac_f32_e32 v26, v24, v24
	s_waitcnt lgkmcnt(0)
	v_fma_f32 v15, v108, v11, -v4
	v_fmac_f32_e32 v14, v15, v15
	v_fma_f32 v11, v124, v11, -v5
	v_fmac_f32_e32 v14, v11, v11
	s_nop 1
	v_add_f32_dpp v4, v14, v14 quad_perm:[1,0,3,2] row_mask:0xf bank_mask:0xf
	s_nop 1
	v_add_f32_dpp v4, v4, v4 quad_perm:[2,3,0,1] row_mask:0xf bank_mask:0xf
	s_nop 1
	v_add_f32_dpp v4, v4, v4 row_half_mirror row_mask:0xf bank_mask:0xf
	s_nop 1
	v_add_f32_dpp v4, v4, v4 row_mirror row_mask:0xf bank_mask:0xf
	ds_swizzle_b32 v5, v4 offset:swizzle(SWAP,16)
	v_fma_f32 v27, v109, v23, -v16
	v_fmac_f32_e32 v26, v27, v27
	v_fma_f32 v23, v125, v23, -v17
	v_fmac_f32_e32 v26, v23, v23
	s_nop 1
	v_add_f32_dpp v16, v26, v26 quad_perm:[1,0,3,2] row_mask:0xf bank_mask:0xf
	s_nop 1
	v_add_f32_dpp v16, v16, v16 quad_perm:[2,3,0,1] row_mask:0xf bank_mask:0xf
	s_nop 1
	v_add_f32_dpp v16, v16, v16 row_half_mirror row_mask:0xf bank_mask:0xf
	s_nop 1
	v_add_f32_dpp v16, v16, v16 row_mirror row_mask:0xf bank_mask:0xf
	ds_swizzle_b32 v17, v16 offset:swizzle(SWAP,16)
	s_waitcnt lgkmcnt(0)
	v_add_f32_e32 v4, v4, v5
	v_fmamk_f32 v4, v4, 0x3c000000, v254
	s_nop 0
	s_nop 0
	s_nop 0
	s_nop 1
	s_nop 1
	s_nop 0
	v_rsq_f32_e32 v14, v4
	s_nop 0
	v_mul_f32_e32 v5, v12, v14
	v_mul_f32_e32 v12, v13, v14
	v_mul_f32_e32 v5, v7, v5
	v_mul_f32_e32 v12, v9, v12
	v_add_u32_e32 v4, 0x10000, v2
	v_cvt_pk_bf16_f32 v12, v5, v12
	v_mov_b32_e32 v5, v3
	v_lshl_add_u64 v[4:5], v[4:5], 1, s[6:7]
	global_store_short v[4:5], v12, off
	v_add_u32_e32 v4, 0x10020, v2
	v_mov_b32_e32 v5, v3
	v_lshl_add_u64 v[4:5], v[4:5], 1, s[6:7]
	global_store_short_d16_hi v[4:5], v12, off
	v_mul_f32_e32 v4, v15, v14
	v_mul_f32_e32 v5, v11, v14
	v_mul_f32_e32 v4, v6, v4
	v_mul_f32_e32 v5, v8, v5
	v_cvt_pk_bf16_f32 v11, v4, v5
	v_add_u32_e32 v4, 0x10040, v2
	v_mov_b32_e32 v5, v3
	v_lshl_add_u64 v[4:5], v[4:5], 1, s[6:7]
	global_store_short v[4:5], v11, off
	v_add_u32_e32 v4, 0x10060, v2
	v_mov_b32_e32 v5, v3
	v_lshl_add_u64 v[4:5], v[4:5], 1, s[6:7]
	global_store_short_d16_hi v[4:5], v11, off
	v_add_f32_e32 v16, v16, v17
	v_fmamk_f32 v16, v16, 0x3c000000, v254
	s_nop 0
	s_nop 0
	s_nop 0
	s_nop 1
	s_nop 1
	s_nop 0
	v_rsq_f32_e32 v26, v16
	s_nop 0
	v_mul_f32_e32 v17, v24, v26
	v_mul_f32_e32 v24, v25, v26
	v_mul_f32_e32 v17, v7, v17
	v_mul_f32_e32 v24, v9, v24
	v_add_u32_e32 v16, 0x11000, v2
	v_cvt_pk_bf16_f32 v24, v17, v24
	v_mov_b32_e32 v17, v3
	v_lshl_add_u64 v[16:17], v[16:17], 1, s[6:7]
	global_store_short v[16:17], v24, off
	v_add_u32_e32 v16, 0x11020, v2
	v_mov_b32_e32 v17, v3
	v_lshl_add_u64 v[16:17], v[16:17], 1, s[6:7]
	global_store_short_d16_hi v[16:17], v24, off
	v_mul_f32_e32 v16, v27, v26
	v_mul_f32_e32 v17, v23, v26
	v_mul_f32_e32 v16, v6, v16
	v_mul_f32_e32 v17, v8, v17
	v_cvt_pk_bf16_f32 v23, v16, v17
	v_add_u32_e32 v16, 0x11040, v2
	v_mov_b32_e32 v17, v3
	v_lshl_add_u64 v[16:17], v[16:17], 1, s[6:7]
	global_store_short v[16:17], v23, off
	v_add_u32_e32 v16, 0x11060, v2
	v_mov_b32_e32 v17, v3
	v_lshl_add_u64 v[16:17], v[16:17], 1, s[6:7]
	global_store_short_d16_hi v[16:17], v23, off
	ds_read_b32 v11, v10 offset:72
	ds_read2st64_b32 v[4:5], v1 offset0:10 offset1:26
	ds_read_b32 v23, v10 offset:76
	ds_read2st64_b32 v[16:17], v1 offset0:11 offset1:27
	s_waitcnt lgkmcnt(0)
	v_fma_f32 v12, v78, v11, -v4
	v_fma_f32 v13, v94, v11, -v5
	ds_read2st64_b32 v[4:5], v1 offset0:42 offset1:58
	v_mul_f32_e32 v14, v13, v13
	v_fmac_f32_e32 v14, v12, v12
	v_fma_f32 v24, v79, v23, -v16
	v_fma_f32 v25, v95, v23, -v17
	ds_read2st64_b32 v[16:17], v1 offset0:43 offset1:59
	v_mul_f32_e32 v26, v25, v25
	v_fmac_f32_e32 v26, v24, v24
	s_waitcnt lgkmcnt(0)
	v_fma_f32 v15, v110, v11, -v4
	v_fmac_f32_e32 v14, v15, v15
	v_fma_f32 v11, v126, v11, -v5
	v_fmac_f32_e32 v14, v11, v11
	s_nop 1
	v_add_f32_dpp v4, v14, v14 quad_perm:[1,0,3,2] row_mask:0xf bank_mask:0xf
	s_nop 1
	v_add_f32_dpp v4, v4, v4 quad_perm:[2,3,0,1] row_mask:0xf bank_mask:0xf
	s_nop 1
	v_add_f32_dpp v4, v4, v4 row_half_mirror row_mask:0xf bank_mask:0xf
	s_nop 1
	v_add_f32_dpp v4, v4, v4 row_mirror row_mask:0xf bank_mask:0xf
	ds_swizzle_b32 v5, v4 offset:swizzle(SWAP,16)
	v_fma_f32 v27, v111, v23, -v16
	v_fmac_f32_e32 v26, v27, v27
	v_fma_f32 v23, v127, v23, -v17
	v_fmac_f32_e32 v26, v23, v23
	s_nop 1
	v_add_f32_dpp v16, v26, v26 quad_perm:[1,0,3,2] row_mask:0xf bank_mask:0xf
	s_nop 1
	v_add_f32_dpp v16, v16, v16 quad_perm:[2,3,0,1] row_mask:0xf bank_mask:0xf
	s_nop 1
	v_add_f32_dpp v16, v16, v16 row_half_mirror row_mask:0xf bank_mask:0xf
	s_nop 1
	v_add_f32_dpp v16, v16, v16 row_mirror row_mask:0xf bank_mask:0xf
	ds_swizzle_b32 v17, v16 offset:swizzle(SWAP,16)
	s_waitcnt lgkmcnt(0)
	v_add_f32_e32 v4, v4, v5
	v_fmamk_f32 v4, v4, 0x3c000000, v254
	s_nop 0
	s_nop 0
	s_nop 0
	s_nop 1
	s_nop 1
	s_nop 0
	v_rsq_f32_e32 v14, v4
	s_nop 0
	v_mul_f32_e32 v5, v12, v14
	v_mul_f32_e32 v12, v13, v14
	v_mul_f32_e32 v5, v7, v5
	v_mul_f32_e32 v12, v9, v12
	v_add_u32_e32 v4, 0x12000, v2
	v_cvt_pk_bf16_f32 v12, v5, v12
	v_mov_b32_e32 v5, v3
	v_lshl_add_u64 v[4:5], v[4:5], 1, s[6:7]
	global_store_short v[4:5], v12, off
	v_add_u32_e32 v4, 0x12020, v2
	v_mov_b32_e32 v5, v3
	v_lshl_add_u64 v[4:5], v[4:5], 1, s[6:7]
	global_store_short_d16_hi v[4:5], v12, off
	v_mul_f32_e32 v4, v15, v14
	v_mul_f32_e32 v5, v11, v14
	v_mul_f32_e32 v4, v6, v4
	v_mul_f32_e32 v5, v8, v5
	v_cvt_pk_bf16_f32 v11, v4, v5
	v_add_u32_e32 v4, 0x12040, v2
	v_mov_b32_e32 v5, v3
	v_lshl_add_u64 v[4:5], v[4:5], 1, s[6:7]
	global_store_short v[4:5], v11, off
	v_add_u32_e32 v4, 0x12060, v2
	v_mov_b32_e32 v5, v3
	v_lshl_add_u64 v[4:5], v[4:5], 1, s[6:7]
	global_store_short_d16_hi v[4:5], v11, off
	v_add_f32_e32 v16, v16, v17
	v_fmamk_f32 v16, v16, 0x3c000000, v254
	s_nop 0
	s_nop 0
	s_nop 0
	s_nop 1
	s_nop 1
	s_nop 0
	v_rsq_f32_e32 v26, v16
	s_nop 0
	v_mul_f32_e32 v17, v24, v26
	v_mul_f32_e32 v24, v25, v26
	v_mul_f32_e32 v17, v7, v17
	v_mul_f32_e32 v24, v9, v24
	v_add_u32_e32 v16, 0x13000, v2
	v_cvt_pk_bf16_f32 v24, v17, v24
	v_mov_b32_e32 v17, v3
	v_lshl_add_u64 v[16:17], v[16:17], 1, s[6:7]
	global_store_short v[16:17], v24, off
	v_add_u32_e32 v16, 0x13020, v2
	v_mov_b32_e32 v17, v3
	v_lshl_add_u64 v[16:17], v[16:17], 1, s[6:7]
	global_store_short_d16_hi v[16:17], v24, off
	v_mul_f32_e32 v16, v27, v26
	v_mul_f32_e32 v17, v23, v26
	v_mul_f32_e32 v16, v6, v16
	v_mul_f32_e32 v17, v8, v17
	v_cvt_pk_bf16_f32 v23, v16, v17
	v_add_u32_e32 v16, 0x13040, v2
	v_mov_b32_e32 v17, v3
	v_lshl_add_u64 v[16:17], v[16:17], 1, s[6:7]
	global_store_short v[16:17], v23, off
	v_add_u32_e32 v16, 0x13060, v2
	v_mov_b32_e32 v17, v3
	v_lshl_add_u64 v[16:17], v[16:17], 1, s[6:7]
	global_store_short_d16_hi v[16:17], v23, off
	ds_read_b32 v11, v10 offset:96
	ds_read2st64_b32 v[4:5], v1 offset0:12 offset1:28
	ds_read_b32 v23, v10 offset:100
	ds_read2st64_b32 v[16:17], v1 offset0:13 offset1:29
	s_waitcnt lgkmcnt(0)
	v_fma_f32 v12, v80, v11, -v4
	v_fma_f32 v13, v96, v11, -v5
	ds_read2st64_b32 v[4:5], v1 offset0:44 offset1:60
	v_mul_f32_e32 v14, v13, v13
	v_fmac_f32_e32 v14, v12, v12
	v_fma_f32 v24, v81, v23, -v16
	v_fma_f32 v25, v97, v23, -v17
	ds_read2st64_b32 v[16:17], v1 offset0:45 offset1:61
	v_mul_f32_e32 v26, v25, v25
	v_fmac_f32_e32 v26, v24, v24
	s_waitcnt lgkmcnt(0)
	v_fma_f32 v15, v112, v11, -v4
	v_fmac_f32_e32 v14, v15, v15
	v_fma_f32 v11, v128, v11, -v5
	v_fmac_f32_e32 v14, v11, v11
	s_nop 1
	v_add_f32_dpp v4, v14, v14 quad_perm:[1,0,3,2] row_mask:0xf bank_mask:0xf
	s_nop 1
	v_add_f32_dpp v4, v4, v4 quad_perm:[2,3,0,1] row_mask:0xf bank_mask:0xf
	s_nop 1
	v_add_f32_dpp v4, v4, v4 row_half_mirror row_mask:0xf bank_mask:0xf
	s_nop 1
	v_add_f32_dpp v4, v4, v4 row_mirror row_mask:0xf bank_mask:0xf
	ds_swizzle_b32 v5, v4 offset:swizzle(SWAP,16)
	v_fma_f32 v27, v113, v23, -v16
	v_fmac_f32_e32 v26, v27, v27
	v_fma_f32 v23, v129, v23, -v17
	v_fmac_f32_e32 v26, v23, v23
	s_nop 1
	v_add_f32_dpp v16, v26, v26 quad_perm:[1,0,3,2] row_mask:0xf bank_mask:0xf
	s_nop 1
	v_add_f32_dpp v16, v16, v16 quad_perm:[2,3,0,1] row_mask:0xf bank_mask:0xf
	s_nop 1
	v_add_f32_dpp v16, v16, v16 row_half_mirror row_mask:0xf bank_mask:0xf
	s_nop 1
	v_add_f32_dpp v16, v16, v16 row_mirror row_mask:0xf bank_mask:0xf
	ds_swizzle_b32 v17, v16 offset:swizzle(SWAP,16)
	s_waitcnt lgkmcnt(0)
	v_add_f32_e32 v4, v4, v5
	v_fmamk_f32 v4, v4, 0x3c000000, v254
	s_nop 0
	s_nop 0
	s_nop 0
	s_nop 1
	s_nop 1
	s_nop 0
	v_rsq_f32_e32 v14, v4
	s_nop 0
	v_mul_f32_e32 v5, v12, v14
	v_mul_f32_e32 v12, v13, v14
	v_mul_f32_e32 v5, v7, v5
	v_mul_f32_e32 v12, v9, v12
	v_add_u32_e32 v4, 0x18000, v2
	v_cvt_pk_bf16_f32 v12, v5, v12
	v_mov_b32_e32 v5, v3
	v_lshl_add_u64 v[4:5], v[4:5], 1, s[6:7]
	global_store_short v[4:5], v12, off
	v_add_u32_e32 v4, 0x18020, v2
	v_mov_b32_e32 v5, v3
	v_lshl_add_u64 v[4:5], v[4:5], 1, s[6:7]
	global_store_short_d16_hi v[4:5], v12, off
	v_mul_f32_e32 v4, v15, v14
	v_mul_f32_e32 v5, v11, v14
	v_mul_f32_e32 v4, v6, v4
	v_mul_f32_e32 v5, v8, v5
	v_cvt_pk_bf16_f32 v11, v4, v5
	v_add_u32_e32 v4, 0x18040, v2
	v_mov_b32_e32 v5, v3
	v_lshl_add_u64 v[4:5], v[4:5], 1, s[6:7]
	global_store_short v[4:5], v11, off
	v_add_u32_e32 v4, 0x18060, v2
	v_mov_b32_e32 v5, v3
	v_lshl_add_u64 v[4:5], v[4:5], 1, s[6:7]
	global_store_short_d16_hi v[4:5], v11, off
	v_add_f32_e32 v16, v16, v17
	v_fmamk_f32 v16, v16, 0x3c000000, v254
	s_nop 0
	s_nop 0
	s_nop 0
	s_nop 1
	s_nop 1
	s_nop 0
	v_rsq_f32_e32 v26, v16
	s_nop 0
	v_mul_f32_e32 v17, v24, v26
	v_mul_f32_e32 v24, v25, v26
	v_mul_f32_e32 v17, v7, v17
	v_mul_f32_e32 v24, v9, v24
	v_add_u32_e32 v16, 0x19000, v2
	v_cvt_pk_bf16_f32 v24, v17, v24
	v_mov_b32_e32 v17, v3
	v_lshl_add_u64 v[16:17], v[16:17], 1, s[6:7]
	global_store_short v[16:17], v24, off
	v_add_u32_e32 v16, 0x19020, v2
	v_mov_b32_e32 v17, v3
	v_lshl_add_u64 v[16:17], v[16:17], 1, s[6:7]
	global_store_short_d16_hi v[16:17], v24, off
	v_mul_f32_e32 v16, v27, v26
	v_mul_f32_e32 v17, v23, v26
	v_mul_f32_e32 v16, v6, v16
	v_mul_f32_e32 v17, v8, v17
	v_cvt_pk_bf16_f32 v23, v16, v17
	v_add_u32_e32 v16, 0x19040, v2
	v_mov_b32_e32 v17, v3
	v_lshl_add_u64 v[16:17], v[16:17], 1, s[6:7]
	global_store_short v[16:17], v23, off
	v_add_u32_e32 v16, 0x19060, v2
	v_mov_b32_e32 v17, v3
	v_lshl_add_u64 v[16:17], v[16:17], 1, s[6:7]
	global_store_short_d16_hi v[16:17], v23, off
	ds_read_b32 v11, v10 offset:104
	ds_read2st64_b32 v[4:5], v1 offset0:14 offset1:30
	s_waitcnt lgkmcnt(0)
	v_fma_f32 v12, v82, v11, -v4
	v_fma_f32 v13, v98, v11, -v5
	ds_read2st64_b32 v[4:5], v1 offset0:46 offset1:62
	v_mul_f32_e32 v14, v13, v13
	v_fmac_f32_e32 v14, v12, v12
	s_waitcnt lgkmcnt(0)
	v_fma_f32 v15, v114, v11, -v4
	v_fmac_f32_e32 v14, v15, v15
	v_fma_f32 v11, v130, v11, -v5
	v_fmac_f32_e32 v14, v11, v11
	s_nop 1
	v_add_f32_dpp v4, v14, v14 quad_perm:[1,0,3,2] row_mask:0xf bank_mask:0xf
	s_nop 1
	v_add_f32_dpp v4, v4, v4 quad_perm:[2,3,0,1] row_mask:0xf bank_mask:0xf
	s_nop 1
	v_add_f32_dpp v4, v4, v4 row_half_mirror row_mask:0xf bank_mask:0xf
	s_nop 1
	v_add_f32_dpp v4, v4, v4 row_mirror row_mask:0xf bank_mask:0xf
	ds_swizzle_b32 v5, v4 offset:swizzle(SWAP,16)
	s_waitcnt lgkmcnt(0)
	v_add_f32_e32 v4, v4, v5
	v_fmamk_f32 v4, v4, 0x3c000000, v254
	s_nop 0
	s_nop 0
	s_nop 0
	s_nop 1
	s_nop 1
	s_nop 0
	v_rsq_f32_e32 v14, v4
	s_nop 0
	v_mul_f32_e32 v5, v12, v14
	v_mul_f32_e32 v12, v13, v14
	v_mul_f32_e32 v5, v7, v5
	v_mul_f32_e32 v12, v9, v12
	v_add_u32_e32 v4, 0x1a000, v2
	v_cvt_pk_bf16_f32 v12, v5, v12
	v_mov_b32_e32 v5, v3
	v_lshl_add_u64 v[4:5], v[4:5], 1, s[6:7]
	global_store_short v[4:5], v12, off
	v_add_u32_e32 v4, 0x1a020, v2
	v_mov_b32_e32 v5, v3
	v_lshl_add_u64 v[4:5], v[4:5], 1, s[6:7]
	global_store_short_d16_hi v[4:5], v12, off
	v_mul_f32_e32 v4, v15, v14
	v_mul_f32_e32 v5, v11, v14
	v_mul_f32_e32 v4, v6, v4
	v_mul_f32_e32 v5, v8, v5
	v_cvt_pk_bf16_f32 v11, v4, v5
	v_add_u32_e32 v4, 0x1a040, v2
	v_mov_b32_e32 v5, v3
	v_lshl_add_u64 v[4:5], v[4:5], 1, s[6:7]
	global_store_short v[4:5], v11, off
	v_add_u32_e32 v4, 0x1a060, v2
	v_mov_b32_e32 v5, v3
	v_lshl_add_u64 v[4:5], v[4:5], 1, s[6:7]
	global_store_short_d16_hi v[4:5], v11, off
	ds_read_b32 v10, v10 offset:108
	ds_read2st64_b32 v[4:5], v1 offset0:15 offset1:31
	s_waitcnt lgkmcnt(0)
	v_fma_f32 v11, v83, v10, -v4
	v_fma_f32 v12, v99, v10, -v5
	ds_read2st64_b32 v[4:5], v1 offset0:47 offset1:63
	v_mul_f32_e32 v13, v12, v12
	v_fmac_f32_e32 v13, v11, v11
	s_waitcnt lgkmcnt(0)
	v_fma_f32 v1, v115, v10, -v4
	v_fmac_f32_e32 v13, v1, v1
	v_fma_f32 v10, v131, v10, -v5
	v_fmac_f32_e32 v13, v10, v10
	s_nop 1
	v_add_f32_dpp v4, v13, v13 quad_perm:[1,0,3,2] row_mask:0xf bank_mask:0xf
	s_nop 1
	v_add_f32_dpp v4, v4, v4 quad_perm:[2,3,0,1] row_mask:0xf bank_mask:0xf
	s_nop 1
	v_add_f32_dpp v4, v4, v4 row_half_mirror row_mask:0xf bank_mask:0xf
	s_nop 1
	v_add_f32_dpp v4, v4, v4 row_mirror row_mask:0xf bank_mask:0xf
	ds_swizzle_b32 v5, v4 offset:swizzle(SWAP,16)
	s_waitcnt lgkmcnt(0)
	v_add_f32_e32 v4, v4, v5
	v_fmamk_f32 v4, v4, 0x3c000000, v254
	s_nop 0
	s_nop 0
	s_nop 0
	s_nop 1
	s_nop 1
	s_nop 0
	v_rsq_f32_e32 v13, v4
	s_nop 0
	v_mul_f32_e32 v5, v11, v13
	v_mul_f32_e32 v5, v7, v5
	v_mul_f32_e32 v7, v12, v13
	v_mul_f32_e32 v7, v9, v7
	v_add_u32_e32 v4, 0x1b000, v2
	v_cvt_pk_bf16_f32 v7, v5, v7
	v_mov_b32_e32 v5, v3
	v_lshl_add_u64 v[4:5], v[4:5], 1, s[6:7]
	global_store_short v[4:5], v7, off
	v_add_u32_e32 v4, 0x1b020, v2
	v_mov_b32_e32 v5, v3
	v_lshl_add_u64 v[4:5], v[4:5], 1, s[6:7]
	global_store_short_d16_hi v[4:5], v7, off
	v_mul_f32_e32 v1, v1, v13
	v_mul_f32_e32 v4, v10, v13
	v_mul_f32_e32 v1, v6, v1
	v_mul_f32_e32 v4, v8, v4
	v_cvt_pk_bf16_f32 v1, v1, v4
	v_add_u32_e32 v4, 0x1b040, v2
	v_mov_b32_e32 v5, v3
	v_lshl_add_u64 v[4:5], v[4:5], 1, s[6:7]
	v_add_u32_e32 v2, 0x1b060, v2
	global_store_short v[4:5], v1, off
	v_lshl_add_u64 v[4:5], v[2:3], 1, s[6:7]
	global_store_short_d16_hi v[4:5], v1, off

.LBB0_1374:
	s_or_b64 exec, exec, s[4:5]
	s_waitcnt lgkmcnt(0)
	v_lshlrev_b32_e32 v4, 2, v158
	global_load_dword v248, v4, s[0:1]
	global_load_dword v249, v4, s[0:1] offset:128
	global_load_dword v250, v4, s[0:1] offset:256
	global_load_dword v251, v4, s[0:1] offset:384
	v_add_u32_e32 v9, s29, v148
	s_lshl_b64 s[4:5], s[24:25], 13
	s_add_u32 s6, s86, s4
	s_addc_u32 s7, s87, s5
	s_waitcnt vmcnt(0)
	v_mul_f32_e32 v6, v164, v248
	v_mul_f32_e32 v8, v164, v249
	v_mul_f32_e32 v2, v164, v250
	v_mul_f32_e32 v7, v164, v251
	v_lshl_or_b32 v4, v159, 14, v158
	ds_read_b32 v5, v9
	ds_read2st64_b32 v[10:11], v1 offset1:16
	s_waitcnt lgkmcnt(0)
	v_fma_f32 v12, v68, v5, -v10
	v_fma_f32 v13, v84, v5, -v11
	ds_read2st64_b32 v[10:11], v1 offset0:32 offset1:48
	v_mul_f32_e32 v14, v13, v13
	v_fmac_f32_e32 v14, v12, v12
	s_waitcnt lgkmcnt(0)
	v_fma_f32 v15, v100, v5, -v10
	v_fmac_f32_e32 v14, v15, v15
	v_fma_f32 v16, v116, v5, -v11
	v_fmac_f32_e32 v14, v16, v16
	s_nop 1
	v_add_f32_dpp v5, v14, v14 quad_perm:[1,0,3,2] row_mask:0xf bank_mask:0xf
	s_nop 1
	v_add_f32_dpp v5, v5, v5 quad_perm:[2,3,0,1] row_mask:0xf bank_mask:0xf
	s_nop 1
	v_add_f32_dpp v5, v5, v5 row_half_mirror row_mask:0xf bank_mask:0xf
	s_nop 1
	v_add_f32_dpp v5, v5, v5 row_mirror row_mask:0xf bank_mask:0xf
	ds_swizzle_b32 v10, v5 offset:swizzle(SWAP,16)
	s_waitcnt lgkmcnt(0)
	v_add_f32_e32 v5, v5, v10
	v_fmamk_f32 v5, v5, 0x3c000000, v254
	s_nop 0
	s_nop 0
	s_nop 0
	s_nop 1
	s_nop 1
	s_nop 0
	v_rsq_f32_e32 v14, v5
	s_nop 0
	v_mul_f32_e32 v5, v12, v14
	v_mul_f32_e32 v5, v6, v5
	v_mul_f32_e32 v10, v13, v14
	v_mul_f32_e32 v10, v8, v10
	v_cvt_pk_bf16_f32 v12, v5, v10
	v_mov_b32_e32 v5, v3
	v_lshl_add_u64 v[10:11], v[4:5], 1, s[6:7]
	global_store_short v[10:11], v12, off offset:768
	v_add_u32_e32 v10, 32, v4
	v_mov_b32_e32 v11, v3
	v_lshl_add_u64 v[10:11], v[10:11], 1, s[6:7]
	global_store_short_d16_hi v[10:11], v12, off offset:768
	v_mul_f32_e32 v5, v15, v14
	v_mul_f32_e32 v10, v16, v14
	v_mul_f32_e32 v5, v2, v5
	v_mul_f32_e32 v10, v7, v10
	v_cvt_pk_bf16_f32 v5, v5, v10
	v_add_u32_e32 v10, 64, v4
	v_mov_b32_e32 v11, v3
	v_lshl_add_u64 v[10:11], v[10:11], 1, s[6:7]
	global_store_short v[10:11], v5, off offset:768
	v_add_u32_e32 v10, 0x60, v4
	v_mov_b32_e32 v11, v3
	v_lshl_add_u64 v[10:11], v[10:11], 1, s[6:7]
	global_store_short_d16_hi v[10:11], v5, off offset:768
	ds_read_b32 v5, v9 offset:4
	ds_read2st64_b32 v[10:11], v1 offset0:1 offset1:17
	s_waitcnt lgkmcnt(0)
	v_fma_f32 v12, v69, v5, -v10
	v_fma_f32 v13, v85, v5, -v11
	ds_read2st64_b32 v[10:11], v1 offset0:33 offset1:49
	v_mul_f32_e32 v14, v13, v13
	v_fmac_f32_e32 v14, v12, v12
	s_waitcnt lgkmcnt(0)
	v_fma_f32 v15, v101, v5, -v10
	v_fmac_f32_e32 v14, v15, v15
	v_fma_f32 v5, v117, v5, -v11
	v_fmac_f32_e32 v14, v5, v5
	s_nop 1
	v_add_f32_dpp v10, v14, v14 quad_perm:[1,0,3,2] row_mask:0xf bank_mask:0xf
	s_nop 1
	v_add_f32_dpp v10, v10, v10 quad_perm:[2,3,0,1] row_mask:0xf bank_mask:0xf
	s_nop 1
	v_add_f32_dpp v10, v10, v10 row_half_mirror row_mask:0xf bank_mask:0xf
	s_nop 1
	v_add_f32_dpp v10, v10, v10 row_mirror row_mask:0xf bank_mask:0xf
	ds_swizzle_b32 v11, v10 offset:swizzle(SWAP,16)
	s_waitcnt lgkmcnt(0)
	v_add_f32_e32 v10, v10, v11
	v_fmamk_f32 v10, v10, 0x3c000000, v254
	s_nop 0
	s_nop 0
	s_nop 0
	s_nop 1
	s_nop 1
	s_nop 0
	v_rsq_f32_e32 v14, v10
	s_nop 0
	v_mul_f32_e32 v11, v12, v14
	v_mul_f32_e32 v12, v13, v14
	v_mul_f32_e32 v11, v6, v11
	v_mul_f32_e32 v12, v8, v12
	v_add_u32_e32 v10, 0x1000, v4
	v_cvt_pk_bf16_f32 v12, v11, v12
	v_mov_b32_e32 v11, v3
	v_lshl_add_u64 v[10:11], v[10:11], 1, s[6:7]
	global_store_short v[10:11], v12, off offset:768
	v_add_u32_e32 v10, 0x1020, v4
	v_mov_b32_e32 v11, v3
	v_lshl_add_u64 v[10:11], v[10:11], 1, s[6:7]
	global_store_short_d16_hi v[10:11], v12, off offset:768
	v_mul_f32_e32 v10, v15, v14
	v_mul_f32_e32 v5, v5, v14
	v_mul_f32_e32 v10, v2, v10
	v_mul_f32_e32 v5, v7, v5
	v_cvt_pk_bf16_f32 v5, v10, v5
	v_add_u32_e32 v10, 0x1040, v4
	v_mov_b32_e32 v11, v3
	v_lshl_add_u64 v[10:11], v[10:11], 1, s[6:7]
	global_store_short v[10:11], v5, off offset:768
	v_add_u32_e32 v10, 0x1060, v4
	v_mov_b32_e32 v11, v3
	v_lshl_add_u64 v[10:11], v[10:11], 1, s[6:7]
	global_store_short_d16_hi v[10:11], v5, off offset:768
	ds_read_b32 v5, v9 offset:8
	ds_read2st64_b32 v[10:11], v1 offset0:2 offset1:18
	ds_read_b32 v35, v9 offset:12
	ds_read2st64_b32 v[40:41], v1 offset0:3 offset1:19
	s_waitcnt lgkmcnt(0)
	v_fma_f32 v12, v70, v5, -v10
	v_fma_f32 v13, v86, v5, -v11
	ds_read2st64_b32 v[10:11], v1 offset0:34 offset1:50
	v_mul_f32_e32 v14, v13, v13
	v_fmac_f32_e32 v14, v12, v12
	v_fma_f32 v42, v71, v35, -v40
	v_fma_f32 v43, v87, v35, -v41
	ds_read2st64_b32 v[40:41], v1 offset0:35 offset1:51
	v_mul_f32_e32 v44, v43, v43
	v_fmac_f32_e32 v44, v42, v42
	s_waitcnt lgkmcnt(0)
	v_fma_f32 v15, v102, v5, -v10
	v_fmac_f32_e32 v14, v15, v15
	v_fma_f32 v5, v118, v5, -v11
	v_fmac_f32_e32 v14, v5, v5
	s_nop 1
	v_add_f32_dpp v10, v14, v14 quad_perm:[1,0,3,2] row_mask:0xf bank_mask:0xf
	s_nop 1
	v_add_f32_dpp v10, v10, v10 quad_perm:[2,3,0,1] row_mask:0xf bank_mask:0xf
	s_nop 1
	v_add_f32_dpp v10, v10, v10 row_half_mirror row_mask:0xf bank_mask:0xf
	s_nop 1
	v_add_f32_dpp v10, v10, v10 row_mirror row_mask:0xf bank_mask:0xf
	ds_swizzle_b32 v11, v10 offset:swizzle(SWAP,16)
	v_fma_f32 v45, v103, v35, -v40
	v_fmac_f32_e32 v44, v45, v45
	v_fma_f32 v35, v119, v35, -v41
	v_fmac_f32_e32 v44, v35, v35
	s_nop 1
	v_add_f32_dpp v40, v44, v44 quad_perm:[1,0,3,2] row_mask:0xf bank_mask:0xf
	s_nop 1
	v_add_f32_dpp v40, v40, v40 quad_perm:[2,3,0,1] row_mask:0xf bank_mask:0xf
	s_nop 1
	v_add_f32_dpp v40, v40, v40 row_half_mirror row_mask:0xf bank_mask:0xf
	s_nop 1
	v_add_f32_dpp v40, v40, v40 row_mirror row_mask:0xf bank_mask:0xf
	ds_swizzle_b32 v41, v40 offset:swizzle(SWAP,16)
	s_waitcnt lgkmcnt(0)
	v_add_f32_e32 v10, v10, v11
	v_fmamk_f32 v10, v10, 0x3c000000, v254
	s_nop 0
	s_nop 0
	s_nop 0
	s_nop 1
	s_nop 1
	s_nop 0
	v_rsq_f32_e32 v14, v10
	s_nop 0
	v_mul_f32_e32 v11, v12, v14
	v_mul_f32_e32 v12, v13, v14
	v_mul_f32_e32 v11, v6, v11
	v_mul_f32_e32 v12, v8, v12
	v_add_u32_e32 v10, 0x2000, v4
	v_cvt_pk_bf16_f32 v12, v11, v12
	v_mov_b32_e32 v11, v3
	v_lshl_add_u64 v[10:11], v[10:11], 1, s[6:7]
	global_store_short v[10:11], v12, off offset:768
	v_add_u32_e32 v10, 0x2020, v4
	v_mov_b32_e32 v11, v3
	v_lshl_add_u64 v[10:11], v[10:11], 1, s[6:7]
	global_store_short_d16_hi v[10:11], v12, off offset:768
	v_mul_f32_e32 v10, v15, v14
	v_mul_f32_e32 v5, v5, v14
	v_mul_f32_e32 v10, v2, v10
	v_mul_f32_e32 v5, v7, v5
	v_cvt_pk_bf16_f32 v5, v10, v5
	v_add_u32_e32 v10, 0x2040, v4
	v_mov_b32_e32 v11, v3
	v_lshl_add_u64 v[10:11], v[10:11], 1, s[6:7]
	global_store_short v[10:11], v5, off offset:768
	v_add_u32_e32 v10, 0x2060, v4
	v_mov_b32_e32 v11, v3
	v_lshl_add_u64 v[10:11], v[10:11], 1, s[6:7]
	global_store_short_d16_hi v[10:11], v5, off offset:768
	v_add_f32_e32 v40, v40, v41
	v_fmamk_f32 v40, v40, 0x3c000000, v254
	s_nop 0
	s_nop 0
	s_nop 0
	s_nop 1
	s_nop 1
	s_nop 0
	v_rsq_f32_e32 v44, v40
	s_nop 0
	v_mul_f32_e32 v41, v42, v44
	v_mul_f32_e32 v42, v43, v44
	v_mul_f32_e32 v41, v6, v41
	v_mul_f32_e32 v42, v8, v42
	v_add_u32_e32 v40, 0x3000, v4
	v_cvt_pk_bf16_f32 v42, v41, v42
	v_mov_b32_e32 v41, v3
	v_lshl_add_u64 v[40:41], v[40:41], 1, s[6:7]
	global_store_short v[40:41], v42, off offset:768
	v_add_u32_e32 v40, 0x3020, v4
	v_mov_b32_e32 v41, v3
	v_lshl_add_u64 v[40:41], v[40:41], 1, s[6:7]
	global_store_short_d16_hi v[40:41], v42, off offset:768
	v_mul_f32_e32 v40, v45, v44
	v_mul_f32_e32 v35, v35, v44
	v_mul_f32_e32 v40, v2, v40
	v_mul_f32_e32 v35, v7, v35
	v_cvt_pk_bf16_f32 v35, v40, v35
	v_add_u32_e32 v40, 0x3040, v4
	v_mov_b32_e32 v41, v3
	v_lshl_add_u64 v[40:41], v[40:41], 1, s[6:7]
	global_store_short v[40:41], v35, off offset:768
	v_add_u32_e32 v40, 0x3060, v4
	v_mov_b32_e32 v41, v3
	v_lshl_add_u64 v[40:41], v[40:41], 1, s[6:7]
	global_store_short_d16_hi v[40:41], v35, off offset:768
	ds_read_b32 v5, v9 offset:32
	ds_read2st64_b32 v[10:11], v1 offset0:4 offset1:20
	ds_read_b32 v35, v9 offset:36
	ds_read2st64_b32 v[40:41], v1 offset0:5 offset1:21
	s_waitcnt lgkmcnt(0)
	v_fma_f32 v12, v72, v5, -v10
	v_fma_f32 v13, v88, v5, -v11
	ds_read2st64_b32 v[10:11], v1 offset0:36 offset1:52
	v_mul_f32_e32 v14, v13, v13
	v_fmac_f32_e32 v14, v12, v12
	v_fma_f32 v42, v73, v35, -v40
	v_fma_f32 v43, v89, v35, -v41
	ds_read2st64_b32 v[40:41], v1 offset0:37 offset1:53
	v_mul_f32_e32 v44, v43, v43
	v_fmac_f32_e32 v44, v42, v42
	s_waitcnt lgkmcnt(0)
	v_fma_f32 v15, v104, v5, -v10
	v_fmac_f32_e32 v14, v15, v15
	v_fma_f32 v5, v120, v5, -v11
	v_fmac_f32_e32 v14, v5, v5
	s_nop 1
	v_add_f32_dpp v10, v14, v14 quad_perm:[1,0,3,2] row_mask:0xf bank_mask:0xf
	s_nop 1
	v_add_f32_dpp v10, v10, v10 quad_perm:[2,3,0,1] row_mask:0xf bank_mask:0xf
	s_nop 1
	v_add_f32_dpp v10, v10, v10 row_half_mirror row_mask:0xf bank_mask:0xf
	s_nop 1
	v_add_f32_dpp v10, v10, v10 row_mirror row_mask:0xf bank_mask:0xf
	ds_swizzle_b32 v11, v10 offset:swizzle(SWAP,16)
	v_fma_f32 v45, v105, v35, -v40
	v_fmac_f32_e32 v44, v45, v45
	v_fma_f32 v35, v121, v35, -v41
	v_fmac_f32_e32 v44, v35, v35
	s_nop 1
	v_add_f32_dpp v40, v44, v44 quad_perm:[1,0,3,2] row_mask:0xf bank_mask:0xf
	s_nop 1
	v_add_f32_dpp v40, v40, v40 quad_perm:[2,3,0,1] row_mask:0xf bank_mask:0xf
	s_nop 1
	v_add_f32_dpp v40, v40, v40 row_half_mirror row_mask:0xf bank_mask:0xf
	s_nop 1
	v_add_f32_dpp v40, v40, v40 row_mirror row_mask:0xf bank_mask:0xf
	ds_swizzle_b32 v41, v40 offset:swizzle(SWAP,16)
	s_waitcnt lgkmcnt(0)
	v_add_f32_e32 v10, v10, v11
	v_fmamk_f32 v10, v10, 0x3c000000, v254
	s_nop 0
	s_nop 0
	s_nop 0
	s_nop 1
	s_nop 1
	s_nop 0
	v_rsq_f32_e32 v14, v10
	s_nop 0
	v_mul_f32_e32 v11, v12, v14
	v_mul_f32_e32 v12, v13, v14
	v_mul_f32_e32 v11, v6, v11
	v_mul_f32_e32 v12, v8, v12
	v_add_u32_e32 v10, 0x8000, v4
	v_cvt_pk_bf16_f32 v12, v11, v12
	v_mov_b32_e32 v11, v3
	v_lshl_add_u64 v[10:11], v[10:11], 1, s[6:7]
	global_store_short v[10:11], v12, off offset:768
	v_add_u32_e32 v10, 0x8020, v4
	v_mov_b32_e32 v11, v3
	v_lshl_add_u64 v[10:11], v[10:11], 1, s[6:7]
	global_store_short_d16_hi v[10:11], v12, off offset:768
	v_mul_f32_e32 v10, v15, v14
	v_mul_f32_e32 v5, v5, v14
	v_mul_f32_e32 v10, v2, v10
	v_mul_f32_e32 v5, v7, v5
	v_cvt_pk_bf16_f32 v5, v10, v5
	v_add_u32_e32 v10, 0x8040, v4
	v_mov_b32_e32 v11, v3
	v_lshl_add_u64 v[10:11], v[10:11], 1, s[6:7]
	global_store_short v[10:11], v5, off offset:768
	v_add_u32_e32 v10, 0x8060, v4
	v_mov_b32_e32 v11, v3
	v_lshl_add_u64 v[10:11], v[10:11], 1, s[6:7]
	global_store_short_d16_hi v[10:11], v5, off offset:768
	v_add_f32_e32 v40, v40, v41
	v_fmamk_f32 v40, v40, 0x3c000000, v254
	s_nop 0
	s_nop 0
	s_nop 0
	s_nop 1
	s_nop 1
	s_nop 0
	v_rsq_f32_e32 v44, v40
	s_nop 0
	v_mul_f32_e32 v41, v42, v44
	v_mul_f32_e32 v42, v43, v44
	v_mul_f32_e32 v41, v6, v41
	v_mul_f32_e32 v42, v8, v42
	v_add_u32_e32 v40, 0x9000, v4
	v_cvt_pk_bf16_f32 v42, v41, v42
	v_mov_b32_e32 v41, v3
	v_lshl_add_u64 v[40:41], v[40:41], 1, s[6:7]
	global_store_short v[40:41], v42, off offset:768
	v_add_u32_e32 v40, 0x9020, v4
	v_mov_b32_e32 v41, v3
	v_lshl_add_u64 v[40:41], v[40:41], 1, s[6:7]
	global_store_short_d16_hi v[40:41], v42, off offset:768
	v_mul_f32_e32 v40, v45, v44
	v_mul_f32_e32 v35, v35, v44
	v_mul_f32_e32 v40, v2, v40
	v_mul_f32_e32 v35, v7, v35
	v_cvt_pk_bf16_f32 v35, v40, v35
	v_add_u32_e32 v40, 0x9040, v4
	v_mov_b32_e32 v41, v3
	v_lshl_add_u64 v[40:41], v[40:41], 1, s[6:7]
	global_store_short v[40:41], v35, off offset:768
	v_add_u32_e32 v40, 0x9060, v4
	v_mov_b32_e32 v41, v3
	v_lshl_add_u64 v[40:41], v[40:41], 1, s[6:7]
	global_store_short_d16_hi v[40:41], v35, off offset:768
	ds_read_b32 v5, v9 offset:40
	ds_read2st64_b32 v[10:11], v1 offset0:6 offset1:22
	ds_read_b32 v35, v9 offset:44
	ds_read2st64_b32 v[40:41], v1 offset0:7 offset1:23
	s_waitcnt lgkmcnt(0)
	v_fma_f32 v12, v74, v5, -v10
	v_fma_f32 v13, v90, v5, -v11
	ds_read2st64_b32 v[10:11], v1 offset0:38 offset1:54
	v_mul_f32_e32 v14, v13, v13
	v_fmac_f32_e32 v14, v12, v12
	v_fma_f32 v42, v75, v35, -v40
	v_fma_f32 v43, v91, v35, -v41
	ds_read2st64_b32 v[40:41], v1 offset0:39 offset1:55
	v_mul_f32_e32 v44, v43, v43
	v_fmac_f32_e32 v44, v42, v42
	s_waitcnt lgkmcnt(0)
	v_fma_f32 v15, v106, v5, -v10
	v_fmac_f32_e32 v14, v15, v15
	v_fma_f32 v5, v122, v5, -v11
	v_fmac_f32_e32 v14, v5, v5
	s_nop 1
	v_add_f32_dpp v10, v14, v14 quad_perm:[1,0,3,2] row_mask:0xf bank_mask:0xf
	s_nop 1
	v_add_f32_dpp v10, v10, v10 quad_perm:[2,3,0,1] row_mask:0xf bank_mask:0xf
	s_nop 1
	v_add_f32_dpp v10, v10, v10 row_half_mirror row_mask:0xf bank_mask:0xf
	s_nop 1
	v_add_f32_dpp v10, v10, v10 row_mirror row_mask:0xf bank_mask:0xf
	ds_swizzle_b32 v11, v10 offset:swizzle(SWAP,16)
	v_fma_f32 v45, v107, v35, -v40
	v_fmac_f32_e32 v44, v45, v45
	v_fma_f32 v35, v123, v35, -v41
	v_fmac_f32_e32 v44, v35, v35
	s_nop 1
	v_add_f32_dpp v40, v44, v44 quad_perm:[1,0,3,2] row_mask:0xf bank_mask:0xf
	s_nop 1
	v_add_f32_dpp v40, v40, v40 quad_perm:[2,3,0,1] row_mask:0xf bank_mask:0xf
	s_nop 1
	v_add_f32_dpp v40, v40, v40 row_half_mirror row_mask:0xf bank_mask:0xf
	s_nop 1
	v_add_f32_dpp v40, v40, v40 row_mirror row_mask:0xf bank_mask:0xf
	ds_swizzle_b32 v41, v40 offset:swizzle(SWAP,16)
	s_waitcnt lgkmcnt(0)
	v_add_f32_e32 v10, v10, v11
	v_fmamk_f32 v10, v10, 0x3c000000, v254
	s_nop 0
	s_nop 0
	s_nop 0
	s_nop 1
	s_nop 1
	s_nop 0
	v_rsq_f32_e32 v14, v10
	s_nop 0
	v_mul_f32_e32 v11, v12, v14
	v_mul_f32_e32 v12, v13, v14
	v_mul_f32_e32 v11, v6, v11
	v_mul_f32_e32 v12, v8, v12
	v_add_u32_e32 v10, 0xa000, v4
	v_cvt_pk_bf16_f32 v12, v11, v12
	v_mov_b32_e32 v11, v3
	v_lshl_add_u64 v[10:11], v[10:11], 1, s[6:7]
	global_store_short v[10:11], v12, off offset:768
	v_add_u32_e32 v10, 0xa020, v4
	v_mov_b32_e32 v11, v3
	v_lshl_add_u64 v[10:11], v[10:11], 1, s[6:7]
	global_store_short_d16_hi v[10:11], v12, off offset:768
	v_mul_f32_e32 v10, v15, v14
	v_mul_f32_e32 v5, v5, v14
	v_mul_f32_e32 v10, v2, v10
	v_mul_f32_e32 v5, v7, v5
	v_cvt_pk_bf16_f32 v5, v10, v5
	v_add_u32_e32 v10, 0xa040, v4
	v_mov_b32_e32 v11, v3
	v_lshl_add_u64 v[10:11], v[10:11], 1, s[6:7]
	global_store_short v[10:11], v5, off offset:768
	v_add_u32_e32 v10, 0xa060, v4
	v_mov_b32_e32 v11, v3
	v_lshl_add_u64 v[10:11], v[10:11], 1, s[6:7]
	global_store_short_d16_hi v[10:11], v5, off offset:768
	v_add_f32_e32 v40, v40, v41
	v_fmamk_f32 v40, v40, 0x3c000000, v254
	s_nop 0
	s_nop 0
	s_nop 0
	s_nop 1
	s_nop 1
	s_nop 0
	v_rsq_f32_e32 v44, v40
	s_nop 0
	v_mul_f32_e32 v41, v42, v44
	v_mul_f32_e32 v42, v43, v44
	v_mul_f32_e32 v41, v6, v41
	v_mul_f32_e32 v42, v8, v42
	v_add_u32_e32 v40, 0xb000, v4
	v_cvt_pk_bf16_f32 v42, v41, v42
	v_mov_b32_e32 v41, v3
	v_lshl_add_u64 v[40:41], v[40:41], 1, s[6:7]
	global_store_short v[40:41], v42, off offset:768
	v_add_u32_e32 v40, 0xb020, v4
	v_mov_b32_e32 v41, v3
	v_lshl_add_u64 v[40:41], v[40:41], 1, s[6:7]
	global_store_short_d16_hi v[40:41], v42, off offset:768
	v_mul_f32_e32 v40, v45, v44
	v_mul_f32_e32 v35, v35, v44
	v_mul_f32_e32 v40, v2, v40
	v_mul_f32_e32 v35, v7, v35
	v_cvt_pk_bf16_f32 v35, v40, v35
	v_add_u32_e32 v40, 0xb040, v4
	v_mov_b32_e32 v41, v3
	v_lshl_add_u64 v[40:41], v[40:41], 1, s[6:7]
	global_store_short v[40:41], v35, off offset:768
	v_add_u32_e32 v40, 0xb060, v4
	v_mov_b32_e32 v41, v3
	v_lshl_add_u64 v[40:41], v[40:41], 1, s[6:7]
	global_store_short_d16_hi v[40:41], v35, off offset:768
	ds_read_b32 v5, v9 offset:64
	ds_read2st64_b32 v[10:11], v1 offset0:8 offset1:24
	ds_read_b32 v35, v9 offset:68
	ds_read2st64_b32 v[40:41], v1 offset0:9 offset1:25
	s_waitcnt lgkmcnt(0)
	v_fma_f32 v12, v76, v5, -v10
	v_fma_f32 v13, v92, v5, -v11
	ds_read2st64_b32 v[10:11], v1 offset0:40 offset1:56
	v_mul_f32_e32 v14, v13, v13
	v_fmac_f32_e32 v14, v12, v12
	v_fma_f32 v42, v77, v35, -v40
	v_fma_f32 v43, v93, v35, -v41
	ds_read2st64_b32 v[40:41], v1 offset0:41 offset1:57
	v_mul_f32_e32 v44, v43, v43
	v_fmac_f32_e32 v44, v42, v42
	s_waitcnt lgkmcnt(0)
	v_fma_f32 v15, v108, v5, -v10
	v_fmac_f32_e32 v14, v15, v15
	v_fma_f32 v5, v124, v5, -v11
	v_fmac_f32_e32 v14, v5, v5
	s_nop 1
	v_add_f32_dpp v10, v14, v14 quad_perm:[1,0,3,2] row_mask:0xf bank_mask:0xf
	s_nop 1
	v_add_f32_dpp v10, v10, v10 quad_perm:[2,3,0,1] row_mask:0xf bank_mask:0xf
	s_nop 1
	v_add_f32_dpp v10, v10, v10 row_half_mirror row_mask:0xf bank_mask:0xf
	s_nop 1
	v_add_f32_dpp v10, v10, v10 row_mirror row_mask:0xf bank_mask:0xf
	ds_swizzle_b32 v11, v10 offset:swizzle(SWAP,16)
	v_fma_f32 v45, v109, v35, -v40
	v_fmac_f32_e32 v44, v45, v45
	v_fma_f32 v35, v125, v35, -v41
	v_fmac_f32_e32 v44, v35, v35
	s_nop 1
	v_add_f32_dpp v40, v44, v44 quad_perm:[1,0,3,2] row_mask:0xf bank_mask:0xf
	s_nop 1
	v_add_f32_dpp v40, v40, v40 quad_perm:[2,3,0,1] row_mask:0xf bank_mask:0xf
	s_nop 1
	v_add_f32_dpp v40, v40, v40 row_half_mirror row_mask:0xf bank_mask:0xf
	s_nop 1
	v_add_f32_dpp v40, v40, v40 row_mirror row_mask:0xf bank_mask:0xf
	ds_swizzle_b32 v41, v40 offset:swizzle(SWAP,16)
	s_waitcnt lgkmcnt(0)
	v_add_f32_e32 v10, v10, v11
	v_fmamk_f32 v10, v10, 0x3c000000, v254
	s_nop 0
	s_nop 0
	s_nop 0
	s_nop 1
	s_nop 1
	s_nop 0
	v_rsq_f32_e32 v14, v10
	s_nop 0
	v_mul_f32_e32 v11, v12, v14
	v_mul_f32_e32 v12, v13, v14
	v_mul_f32_e32 v11, v6, v11
	v_mul_f32_e32 v12, v8, v12
	v_add_u32_e32 v10, 0x10000, v4
	v_cvt_pk_bf16_f32 v12, v11, v12
	v_mov_b32_e32 v11, v3
	v_lshl_add_u64 v[10:11], v[10:11], 1, s[6:7]
	global_store_short v[10:11], v12, off offset:768
	v_add_u32_e32 v10, 0x10020, v4
	v_mov_b32_e32 v11, v3
	v_lshl_add_u64 v[10:11], v[10:11], 1, s[6:7]
	global_store_short_d16_hi v[10:11], v12, off offset:768
	v_mul_f32_e32 v10, v15, v14
	v_mul_f32_e32 v5, v5, v14
	v_mul_f32_e32 v10, v2, v10
	v_mul_f32_e32 v5, v7, v5
	v_cvt_pk_bf16_f32 v5, v10, v5
	v_add_u32_e32 v10, 0x10040, v4
	v_mov_b32_e32 v11, v3
	v_lshl_add_u64 v[10:11], v[10:11], 1, s[6:7]
	global_store_short v[10:11], v5, off offset:768
	v_add_u32_e32 v10, 0x10060, v4
	v_mov_b32_e32 v11, v3
	v_lshl_add_u64 v[10:11], v[10:11], 1, s[6:7]
	global_store_short_d16_hi v[10:11], v5, off offset:768
	v_add_f32_e32 v40, v40, v41
	v_fmamk_f32 v40, v40, 0x3c000000, v254
	s_nop 0
	s_nop 0
	s_nop 0
	s_nop 1
	s_nop 1
	s_nop 0
	v_rsq_f32_e32 v44, v40
	s_nop 0
	v_mul_f32_e32 v41, v42, v44
	v_mul_f32_e32 v42, v43, v44
	v_mul_f32_e32 v41, v6, v41
	v_mul_f32_e32 v42, v8, v42
	v_add_u32_e32 v40, 0x11000, v4
	v_cvt_pk_bf16_f32 v42, v41, v42
	v_mov_b32_e32 v41, v3
	v_lshl_add_u64 v[40:41], v[40:41], 1, s[6:7]
	global_store_short v[40:41], v42, off offset:768
	v_add_u32_e32 v40, 0x11020, v4
	v_mov_b32_e32 v41, v3
	v_lshl_add_u64 v[40:41], v[40:41], 1, s[6:7]
	global_store_short_d16_hi v[40:41], v42, off offset:768
	v_mul_f32_e32 v40, v45, v44
	v_mul_f32_e32 v35, v35, v44
	v_mul_f32_e32 v40, v2, v40
	v_mul_f32_e32 v35, v7, v35
	v_cvt_pk_bf16_f32 v35, v40, v35
	v_add_u32_e32 v40, 0x11040, v4
	v_mov_b32_e32 v41, v3
	v_lshl_add_u64 v[40:41], v[40:41], 1, s[6:7]
	global_store_short v[40:41], v35, off offset:768
	v_add_u32_e32 v40, 0x11060, v4
	v_mov_b32_e32 v41, v3
	v_lshl_add_u64 v[40:41], v[40:41], 1, s[6:7]
	global_store_short_d16_hi v[40:41], v35, off offset:768
	ds_read_b32 v5, v9 offset:72
	ds_read2st64_b32 v[10:11], v1 offset0:10 offset1:26
	ds_read_b32 v35, v9 offset:76
	ds_read2st64_b32 v[40:41], v1 offset0:11 offset1:27
	s_waitcnt lgkmcnt(0)
	v_fma_f32 v12, v78, v5, -v10
	v_fma_f32 v13, v94, v5, -v11
	ds_read2st64_b32 v[10:11], v1 offset0:42 offset1:58
	v_mul_f32_e32 v14, v13, v13
	v_fmac_f32_e32 v14, v12, v12
	v_fma_f32 v42, v79, v35, -v40
	v_fma_f32 v43, v95, v35, -v41
	ds_read2st64_b32 v[40:41], v1 offset0:43 offset1:59
	v_mul_f32_e32 v44, v43, v43
	v_fmac_f32_e32 v44, v42, v42
	s_waitcnt lgkmcnt(0)
	v_fma_f32 v15, v110, v5, -v10
	v_fmac_f32_e32 v14, v15, v15
	v_fma_f32 v5, v126, v5, -v11
	v_fmac_f32_e32 v14, v5, v5
	s_nop 1
	v_add_f32_dpp v10, v14, v14 quad_perm:[1,0,3,2] row_mask:0xf bank_mask:0xf
	s_nop 1
	v_add_f32_dpp v10, v10, v10 quad_perm:[2,3,0,1] row_mask:0xf bank_mask:0xf
	s_nop 1
	v_add_f32_dpp v10, v10, v10 row_half_mirror row_mask:0xf bank_mask:0xf
	s_nop 1
	v_add_f32_dpp v10, v10, v10 row_mirror row_mask:0xf bank_mask:0xf
	ds_swizzle_b32 v11, v10 offset:swizzle(SWAP,16)
	v_fma_f32 v45, v111, v35, -v40
	v_fmac_f32_e32 v44, v45, v45
	v_fma_f32 v35, v127, v35, -v41
	v_fmac_f32_e32 v44, v35, v35
	s_nop 1
	v_add_f32_dpp v40, v44, v44 quad_perm:[1,0,3,2] row_mask:0xf bank_mask:0xf
	s_nop 1
	v_add_f32_dpp v40, v40, v40 quad_perm:[2,3,0,1] row_mask:0xf bank_mask:0xf
	s_nop 1
	v_add_f32_dpp v40, v40, v40 row_half_mirror row_mask:0xf bank_mask:0xf
	s_nop 1
	v_add_f32_dpp v40, v40, v40 row_mirror row_mask:0xf bank_mask:0xf
	ds_swizzle_b32 v41, v40 offset:swizzle(SWAP,16)
	s_waitcnt lgkmcnt(0)
	v_add_f32_e32 v10, v10, v11
	v_fmamk_f32 v10, v10, 0x3c000000, v254
	s_nop 0
	s_nop 0
	s_nop 0
	s_nop 1
	s_nop 1
	s_nop 0
	v_rsq_f32_e32 v14, v10
	s_nop 0
	v_mul_f32_e32 v11, v12, v14
	v_mul_f32_e32 v12, v13, v14
	v_mul_f32_e32 v11, v6, v11
	v_mul_f32_e32 v12, v8, v12
	v_add_u32_e32 v10, 0x12000, v4
	v_cvt_pk_bf16_f32 v12, v11, v12
	v_mov_b32_e32 v11, v3
	v_lshl_add_u64 v[10:11], v[10:11], 1, s[6:7]
	global_store_short v[10:11], v12, off offset:768
	v_add_u32_e32 v10, 0x12020, v4
	v_mov_b32_e32 v11, v3
	v_lshl_add_u64 v[10:11], v[10:11], 1, s[6:7]
	global_store_short_d16_hi v[10:11], v12, off offset:768
	v_mul_f32_e32 v10, v15, v14
	v_mul_f32_e32 v5, v5, v14
	v_mul_f32_e32 v10, v2, v10
	v_mul_f32_e32 v5, v7, v5
	v_cvt_pk_bf16_f32 v5, v10, v5
	v_add_u32_e32 v10, 0x12040, v4
	v_mov_b32_e32 v11, v3
	v_lshl_add_u64 v[10:11], v[10:11], 1, s[6:7]
	global_store_short v[10:11], v5, off offset:768
	v_add_u32_e32 v10, 0x12060, v4
	v_mov_b32_e32 v11, v3
	v_lshl_add_u64 v[10:11], v[10:11], 1, s[6:7]
	global_store_short_d16_hi v[10:11], v5, off offset:768
	v_add_f32_e32 v40, v40, v41
	v_fmamk_f32 v40, v40, 0x3c000000, v254
	s_nop 0
	s_nop 0
	s_nop 0
	s_nop 1
	s_nop 1
	s_nop 0
	v_rsq_f32_e32 v44, v40
	s_nop 0
	v_mul_f32_e32 v41, v42, v44
	v_mul_f32_e32 v42, v43, v44
	v_mul_f32_e32 v41, v6, v41
	v_mul_f32_e32 v42, v8, v42
	v_add_u32_e32 v40, 0x13000, v4
	v_cvt_pk_bf16_f32 v42, v41, v42
	v_mov_b32_e32 v41, v3
	v_lshl_add_u64 v[40:41], v[40:41], 1, s[6:7]
	global_store_short v[40:41], v42, off offset:768
	v_add_u32_e32 v40, 0x13020, v4
	v_mov_b32_e32 v41, v3
	v_lshl_add_u64 v[40:41], v[40:41], 1, s[6:7]
	global_store_short_d16_hi v[40:41], v42, off offset:768
	v_mul_f32_e32 v40, v45, v44
	v_mul_f32_e32 v35, v35, v44
	v_mul_f32_e32 v40, v2, v40
	v_mul_f32_e32 v35, v7, v35
	v_cvt_pk_bf16_f32 v35, v40, v35
	v_add_u32_e32 v40, 0x13040, v4
	v_mov_b32_e32 v41, v3
	v_lshl_add_u64 v[40:41], v[40:41], 1, s[6:7]
	global_store_short v[40:41], v35, off offset:768
	v_add_u32_e32 v40, 0x13060, v4
	v_mov_b32_e32 v41, v3
	v_lshl_add_u64 v[40:41], v[40:41], 1, s[6:7]
	global_store_short_d16_hi v[40:41], v35, off offset:768
	ds_read_b32 v5, v9 offset:96
	ds_read2st64_b32 v[10:11], v1 offset0:12 offset1:28
	ds_read_b32 v35, v9 offset:100
	ds_read2st64_b32 v[40:41], v1 offset0:13 offset1:29
	s_waitcnt lgkmcnt(0)
	v_fma_f32 v12, v80, v5, -v10
	v_fma_f32 v13, v96, v5, -v11
	ds_read2st64_b32 v[10:11], v1 offset0:44 offset1:60
	v_mul_f32_e32 v14, v13, v13
	v_fmac_f32_e32 v14, v12, v12
	v_fma_f32 v42, v81, v35, -v40
	v_fma_f32 v43, v97, v35, -v41
	ds_read2st64_b32 v[40:41], v1 offset0:45 offset1:61
	v_mul_f32_e32 v44, v43, v43
	v_fmac_f32_e32 v44, v42, v42
	s_waitcnt lgkmcnt(0)
	v_fma_f32 v15, v112, v5, -v10
	v_fmac_f32_e32 v14, v15, v15
	v_fma_f32 v5, v128, v5, -v11
	v_fmac_f32_e32 v14, v5, v5
	s_nop 1
	v_add_f32_dpp v10, v14, v14 quad_perm:[1,0,3,2] row_mask:0xf bank_mask:0xf
	s_nop 1
	v_add_f32_dpp v10, v10, v10 quad_perm:[2,3,0,1] row_mask:0xf bank_mask:0xf
	s_nop 1
	v_add_f32_dpp v10, v10, v10 row_half_mirror row_mask:0xf bank_mask:0xf
	s_nop 1
	v_add_f32_dpp v10, v10, v10 row_mirror row_mask:0xf bank_mask:0xf
	ds_swizzle_b32 v11, v10 offset:swizzle(SWAP,16)
	v_fma_f32 v45, v113, v35, -v40
	v_fmac_f32_e32 v44, v45, v45
	v_fma_f32 v35, v129, v35, -v41
	v_fmac_f32_e32 v44, v35, v35
	s_nop 1
	v_add_f32_dpp v40, v44, v44 quad_perm:[1,0,3,2] row_mask:0xf bank_mask:0xf
	s_nop 1
	v_add_f32_dpp v40, v40, v40 quad_perm:[2,3,0,1] row_mask:0xf bank_mask:0xf
	s_nop 1
	v_add_f32_dpp v40, v40, v40 row_half_mirror row_mask:0xf bank_mask:0xf
	s_nop 1
	v_add_f32_dpp v40, v40, v40 row_mirror row_mask:0xf bank_mask:0xf
	ds_swizzle_b32 v41, v40 offset:swizzle(SWAP,16)
	s_waitcnt lgkmcnt(0)
	v_add_f32_e32 v10, v10, v11
	v_fmamk_f32 v10, v10, 0x3c000000, v254
	s_nop 0
	s_nop 0
	s_nop 0
	s_nop 1
	s_nop 1
	s_nop 0
	v_rsq_f32_e32 v14, v10
	s_nop 0
	v_mul_f32_e32 v11, v12, v14
	v_mul_f32_e32 v12, v13, v14
	v_mul_f32_e32 v11, v6, v11
	v_mul_f32_e32 v12, v8, v12
	v_add_u32_e32 v10, 0x18000, v4
	v_cvt_pk_bf16_f32 v12, v11, v12
	v_mov_b32_e32 v11, v3
	v_lshl_add_u64 v[10:11], v[10:11], 1, s[6:7]
	global_store_short v[10:11], v12, off offset:768
	v_add_u32_e32 v10, 0x18020, v4
	v_mov_b32_e32 v11, v3
	v_lshl_add_u64 v[10:11], v[10:11], 1, s[6:7]
	global_store_short_d16_hi v[10:11], v12, off offset:768
	v_mul_f32_e32 v10, v15, v14
	v_mul_f32_e32 v5, v5, v14
	v_mul_f32_e32 v10, v2, v10
	v_mul_f32_e32 v5, v7, v5
	v_cvt_pk_bf16_f32 v5, v10, v5
	v_add_u32_e32 v10, 0x18040, v4
	v_mov_b32_e32 v11, v3
	v_lshl_add_u64 v[10:11], v[10:11], 1, s[6:7]
	global_store_short v[10:11], v5, off offset:768
	v_add_u32_e32 v10, 0x18060, v4
	v_mov_b32_e32 v11, v3
	v_lshl_add_u64 v[10:11], v[10:11], 1, s[6:7]
	global_store_short_d16_hi v[10:11], v5, off offset:768
	v_add_f32_e32 v40, v40, v41
	v_fmamk_f32 v40, v40, 0x3c000000, v254
	s_nop 0
	s_nop 0
	s_nop 0
	s_nop 1
	s_nop 1
	s_nop 0
	v_rsq_f32_e32 v44, v40
	s_nop 0
	v_mul_f32_e32 v41, v42, v44
	v_mul_f32_e32 v42, v43, v44
	v_mul_f32_e32 v41, v6, v41
	v_mul_f32_e32 v42, v8, v42
	v_add_u32_e32 v40, 0x19000, v4
	v_cvt_pk_bf16_f32 v42, v41, v42
	v_mov_b32_e32 v41, v3
	v_lshl_add_u64 v[40:41], v[40:41], 1, s[6:7]
	global_store_short v[40:41], v42, off offset:768
	v_add_u32_e32 v40, 0x19020, v4
	v_mov_b32_e32 v41, v3
	v_lshl_add_u64 v[40:41], v[40:41], 1, s[6:7]
	global_store_short_d16_hi v[40:41], v42, off offset:768
	v_mul_f32_e32 v40, v45, v44
	v_mul_f32_e32 v35, v35, v44
	v_mul_f32_e32 v40, v2, v40
	v_mul_f32_e32 v35, v7, v35
	v_cvt_pk_bf16_f32 v35, v40, v35
	v_add_u32_e32 v40, 0x19040, v4
	v_mov_b32_e32 v41, v3
	v_lshl_add_u64 v[40:41], v[40:41], 1, s[6:7]
	global_store_short v[40:41], v35, off offset:768
	v_add_u32_e32 v40, 0x19060, v4
	v_mov_b32_e32 v41, v3
	v_lshl_add_u64 v[40:41], v[40:41], 1, s[6:7]
	global_store_short_d16_hi v[40:41], v35, off offset:768
	ds_read_b32 v5, v9 offset:104
	ds_read2st64_b32 v[10:11], v1 offset0:14 offset1:30
	s_waitcnt lgkmcnt(0)
	v_fma_f32 v12, v82, v5, -v10
	v_fma_f32 v13, v98, v5, -v11
	ds_read2st64_b32 v[10:11], v1 offset0:46 offset1:62
	v_mul_f32_e32 v14, v13, v13
	v_fmac_f32_e32 v14, v12, v12
	s_waitcnt lgkmcnt(0)
	v_fma_f32 v15, v114, v5, -v10
	v_fmac_f32_e32 v14, v15, v15
	v_fma_f32 v5, v130, v5, -v11
	v_fmac_f32_e32 v14, v5, v5
	s_nop 1
	v_add_f32_dpp v10, v14, v14 quad_perm:[1,0,3,2] row_mask:0xf bank_mask:0xf
	s_nop 1
	v_add_f32_dpp v10, v10, v10 quad_perm:[2,3,0,1] row_mask:0xf bank_mask:0xf
	s_nop 1
	v_add_f32_dpp v10, v10, v10 row_half_mirror row_mask:0xf bank_mask:0xf
	s_nop 1
	v_add_f32_dpp v10, v10, v10 row_mirror row_mask:0xf bank_mask:0xf
	ds_swizzle_b32 v11, v10 offset:swizzle(SWAP,16)
	s_waitcnt lgkmcnt(0)
	v_add_f32_e32 v10, v10, v11
	v_fmamk_f32 v10, v10, 0x3c000000, v254
	v_cmp_gt_f32_e32 vcc, s90, v10
	v_mul_f32_e32 v11, 0x4f800000, v10
	s_nop 0
	v_cndmask_b32_e32 v10, v10, v11, vcc
	v_sqrt_f32_e32 v11, v10
	s_nop 0
	v_add_u32_e32 v14, -1, v11
	v_fma_f32 v16, -v14, v11, v10
	v_cmp_ge_f32_e64 s[4:5], 0, v16
	v_add_u32_e32 v16, 1, v11
	s_nop 0
	v_cndmask_b32_e64 v14, v11, v14, s[4:5]
	v_fma_f32 v11, -v16, v11, v10
	v_cmp_lt_f32_e64 s[4:5], 0, v11
	s_nop 1
	v_cndmask_b32_e64 v11, v14, v16, s[4:5]
	v_mul_f32_e32 v14, 0x37800000, v11
	v_cndmask_b32_e32 v11, v11, v14, vcc
	v_cmp_class_f32_e32 vcc, v10, v209
	s_nop 1
	v_cndmask_b32_e32 v10, v11, v10, vcc
	v_div_scale_f32 v11, s[4:5], v10, v10, 1.0
	v_rcp_f32_e32 v14, v11
	s_nop 0
	v_fma_f32 v16, -v11, v14, 1.0
	v_fmac_f32_e32 v14, v16, v14
	v_div_scale_f32 v16, vcc, 1.0, v10, 1.0
	v_mul_f32_e32 v17, v16, v14
	v_fma_f32 v18, -v11, v17, v16
	v_fmac_f32_e32 v17, v18, v14
	v_fma_f32 v11, -v11, v17, v16
	v_div_fmas_f32 v11, v11, v14, v17
	v_div_fixup_f32 v14, v11, v10, 1.0
	v_mul_f32_e32 v11, v12, v14
	v_mul_f32_e32 v12, v13, v14
	v_mul_f32_e32 v11, v6, v11
	v_mul_f32_e32 v12, v8, v12
	v_add_u32_e32 v10, 0x1a000, v4
	v_cvt_pk_bf16_f32 v12, v11, v12
	v_mov_b32_e32 v11, v3
	v_lshl_add_u64 v[10:11], v[10:11], 1, s[6:7]
	global_store_short v[10:11], v12, off offset:768
	v_add_u32_e32 v10, 0x1a020, v4
	v_mov_b32_e32 v11, v3
	v_lshl_add_u64 v[10:11], v[10:11], 1, s[6:7]
	global_store_short_d16_hi v[10:11], v12, off offset:768
	v_mul_f32_e32 v10, v15, v14
	v_mul_f32_e32 v5, v5, v14
	v_mul_f32_e32 v10, v2, v10
	v_mul_f32_e32 v5, v7, v5
	v_cvt_pk_bf16_f32 v5, v10, v5
	v_add_u32_e32 v10, 0x1a040, v4
	v_mov_b32_e32 v11, v3
	v_lshl_add_u64 v[10:11], v[10:11], 1, s[6:7]
	global_store_short v[10:11], v5, off offset:768
	v_add_u32_e32 v10, 0x1a060, v4
	v_mov_b32_e32 v11, v3
	v_lshl_add_u64 v[10:11], v[10:11], 1, s[6:7]
	global_store_short_d16_hi v[10:11], v5, off offset:768
	ds_read_b32 v5, v9 offset:108
	ds_read2st64_b32 v[10:11], v1 offset0:15 offset1:31
	s_waitcnt lgkmcnt(0)
	v_fma_f32 v9, v83, v5, -v10
	v_fma_f32 v12, v99, v5, -v11
	ds_read2st64_b32 v[10:11], v1 offset0:47 offset1:63
	v_mul_f32_e32 v13, v12, v12
	v_fmac_f32_e32 v13, v9, v9
	s_waitcnt lgkmcnt(0)
	v_fma_f32 v1, v115, v5, -v10
	v_fmac_f32_e32 v13, v1, v1
	v_fma_f32 v5, v131, v5, -v11
	v_fmac_f32_e32 v13, v5, v5
	s_nop 1
	v_add_f32_dpp v10, v13, v13 quad_perm:[1,0,3,2] row_mask:0xf bank_mask:0xf
	s_nop 1
	v_add_f32_dpp v10, v10, v10 quad_perm:[2,3,0,1] row_mask:0xf bank_mask:0xf
	s_nop 1
	v_add_f32_dpp v10, v10, v10 row_half_mirror row_mask:0xf bank_mask:0xf
	s_nop 1
	v_add_f32_dpp v10, v10, v10 row_mirror row_mask:0xf bank_mask:0xf
	ds_swizzle_b32 v11, v10 offset:swizzle(SWAP,16)
	s_waitcnt lgkmcnt(0)
	v_add_f32_e32 v10, v10, v11
	v_fmamk_f32 v10, v10, 0x3c000000, v254
	v_cmp_gt_f32_e32 vcc, s90, v10
	v_mul_f32_e32 v11, 0x4f800000, v10
	s_nop 0
	v_cndmask_b32_e32 v10, v10, v11, vcc
	v_sqrt_f32_e32 v11, v10
	s_nop 0
	v_add_u32_e32 v13, -1, v11
	v_fma_f32 v14, -v13, v11, v10
	v_cmp_ge_f32_e64 s[4:5], 0, v14
	v_add_u32_e32 v14, 1, v11
	s_nop 0
	v_cndmask_b32_e64 v13, v11, v13, s[4:5]
	v_fma_f32 v11, -v14, v11, v10
	v_cmp_lt_f32_e64 s[4:5], 0, v11
	s_nop 1
	v_cndmask_b32_e64 v11, v13, v14, s[4:5]
	v_mul_f32_e32 v13, 0x37800000, v11
	v_cndmask_b32_e32 v11, v11, v13, vcc
	v_cmp_class_f32_e32 vcc, v10, v209
	s_nop 1
	v_cndmask_b32_e32 v10, v11, v10, vcc
	v_div_scale_f32 v11, s[4:5], v10, v10, 1.0
	v_rcp_f32_e32 v13, v11
	s_nop 0
	v_fma_f32 v14, -v11, v13, 1.0
	v_fmac_f32_e32 v13, v14, v13
	v_div_scale_f32 v14, vcc, 1.0, v10, 1.0
	v_mul_f32_e32 v15, v14, v13
	v_fma_f32 v16, -v11, v15, v14
	v_fmac_f32_e32 v15, v16, v13
	v_fma_f32 v11, -v11, v15, v14
	v_div_fmas_f32 v11, v11, v13, v15
	v_div_fixup_f32 v13, v11, v10, 1.0
	v_mul_f32_e32 v9, v9, v13
	v_mul_f32_e32 v6, v6, v9
	v_mul_f32_e32 v9, v12, v13
	v_add_u32_e32 v10, 0x1b000, v4
	v_mul_f32_e32 v8, v8, v9
	v_mov_b32_e32 v11, v3
	v_cvt_pk_bf16_f32 v6, v6, v8
	v_lshl_add_u64 v[8:9], v[10:11], 1, s[6:7]
	global_store_short v[8:9], v6, off offset:768
	v_add_u32_e32 v8, 0x1b020, v4
	v_mov_b32_e32 v9, v3
	v_mul_f32_e32 v1, v1, v13
	v_lshl_add_u64 v[8:9], v[8:9], 1, s[6:7]
	v_mul_f32_e32 v1, v2, v1
	v_mul_f32_e32 v2, v5, v13
	global_store_short_d16_hi v[8:9], v6, off offset:768
	v_mul_f32_e32 v2, v7, v2
	v_add_u32_e32 v6, 0x1b040, v4
	v_mov_b32_e32 v7, v3
	v_add_u32_e32 v4, 0x1b060, v4
	v_mov_b32_e32 v5, v3
	v_lshl_add_u64 v[6:7], v[6:7], 1, s[6:7]
	v_lshl_add_u64 v[4:5], v[4:5], 1, s[6:7]
	v_cvt_pk_bf16_f32 v1, v1, v2
	global_store_short v[6:7], v1, off offset:768
	global_store_short_d16_hi v[4:5], v1, off offset:768

.LBB0_1426:
	s_or_b64 exec, exec, s[4:5]
	s_waitcnt lgkmcnt(0)
	v_lshlrev_b32_e32 v68, 2, v1
	global_load_dword v248, v68, s[0:1]
	global_load_dword v249, v68, s[0:1] offset:128
	global_load_dword v250, v68, s[0:1] offset:256
	global_load_dword v251, v68, s[0:1] offset:384
	s_or_b32 s24, s24, s35
	s_lshl_b64 s[4:5], s[24:25], 13
	s_add_u32 s6, s86, s4
	s_addc_u32 s7, s87, s5
	s_lshl_b64 s[4:5], s[46:47], 1
	s_add_u32 s6, s6, s4
	s_addc_u32 s7, s7, s5
	s_waitcnt vmcnt(0)
	v_mul_f32_e32 v72, v164, v248
	v_mul_f32_e32 v74, v164, v249
	v_mul_f32_e32 v71, v164, v250
	v_mul_f32_e32 v73, v164, v251
	v_lshl_or_b32 v68, v2, 14, v1
	v_lshl_add_u32 v1, v2, 4, s34
	ds_read_b32 v2, v1
	ds_read2st64_b32 v[76:77], v70 offset1:16
	s_waitcnt lgkmcnt(0)
	v_fma_f32 v52, v52, v2, -v76
	v_fma_f32 v36, v36, v2, -v77
	ds_read2st64_b32 v[76:77], v70 offset0:32 offset1:48
	v_mul_f32_e32 v69, v36, v36
	v_fmac_f32_e32 v69, v52, v52
	s_waitcnt lgkmcnt(0)
	v_fma_f32 v20, v20, v2, -v76
	v_fmac_f32_e32 v69, v20, v20
	v_fma_f32 v2, v4, v2, -v77
	v_fmac_f32_e32 v69, v2, v2
	s_nop 1
	v_add_f32_dpp v4, v69, v69 quad_perm:[1,0,3,2] row_mask:0xf bank_mask:0xf
	s_nop 1
	v_add_f32_dpp v4, v4, v4 quad_perm:[2,3,0,1] row_mask:0xf bank_mask:0xf
	s_nop 1
	v_add_f32_dpp v4, v4, v4 row_half_mirror row_mask:0xf bank_mask:0xf
	s_nop 1
	v_add_f32_dpp v4, v4, v4 row_mirror row_mask:0xf bank_mask:0xf
	ds_swizzle_b32 v69, v4 offset:swizzle(SWAP,16)
	s_waitcnt lgkmcnt(0)
	v_add_f32_e32 v4, v4, v69
	v_fmamk_f32 v4, v4, 0x3c000000, v254
	v_cmp_gt_f32_e32 vcc, s90, v4
	v_mul_f32_e32 v69, 0x4f800000, v4
	s_nop 0
	v_cndmask_b32_e32 v4, v4, v69, vcc
	v_sqrt_f32_e32 v69, v4
	s_nop 0
	v_add_u32_e32 v75, -1, v69
	v_fma_f32 v76, -v75, v69, v4
	v_cmp_ge_f32_e64 s[4:5], 0, v76
	v_add_u32_e32 v76, 1, v69
	s_nop 0
	v_cndmask_b32_e64 v75, v69, v75, s[4:5]
	v_fma_f32 v69, -v76, v69, v4
	v_cmp_lt_f32_e64 s[4:5], 0, v69
	s_nop 1
	v_cndmask_b32_e64 v69, v75, v76, s[4:5]
	v_mul_f32_e32 v75, 0x37800000, v69
	v_cndmask_b32_e32 v69, v69, v75, vcc
	v_cmp_class_f32_e32 vcc, v4, v209
	s_nop 1
	v_cndmask_b32_e32 v4, v69, v4, vcc
	v_div_scale_f32 v69, s[4:5], v4, v4, 1.0
	v_rcp_f32_e32 v75, v69
	s_nop 0
	v_fma_f32 v76, -v69, v75, 1.0
	v_fmac_f32_e32 v75, v76, v75
	v_div_scale_f32 v76, vcc, 1.0, v4, 1.0
	v_mul_f32_e32 v77, v76, v75
	v_fma_f32 v78, -v69, v77, v76
	v_fmac_f32_e32 v77, v78, v75
	v_fma_f32 v69, -v69, v77, v76
	v_div_fmas_f32 v69, v69, v75, v77
	v_div_fixup_f32 v4, v69, v4, 1.0
	v_mul_f32_e32 v36, v36, v4
	v_mov_b32_e32 v69, v3
	v_mul_f32_e32 v52, v52, v4
	v_mul_f32_e32 v36, v74, v36
	v_lshl_add_u64 v[76:77], v[68:69], 1, s[6:7]
	v_mul_f32_e32 v52, v72, v52
	v_cvt_pk_bf16_f32 v36, v52, v36
	global_store_short v[76:77], v36, off
	v_add_u32_e32 v76, 32, v68
	v_mov_b32_e32 v77, v3
	v_lshl_add_u64 v[76:77], v[76:77], 1, s[6:7]
	global_store_short_d16_hi v[76:77], v36, off
	v_mul_f32_e32 v2, v2, v4
	v_add_u32_e32 v76, 64, v68
	v_mov_b32_e32 v77, v3
	v_mul_f32_e32 v20, v20, v4
	v_mul_f32_e32 v2, v73, v2
	v_lshl_add_u64 v[76:77], v[76:77], 1, s[6:7]
	v_mul_f32_e32 v20, v71, v20
	v_cvt_pk_bf16_f32 v2, v20, v2
	global_store_short v[76:77], v2, off
	v_add_u32_e32 v76, 0x60, v68
	v_mov_b32_e32 v77, v3
	v_lshl_add_u64 v[76:77], v[76:77], 1, s[6:7]
	global_store_short_d16_hi v[76:77], v2, off
	ds_read_b32 v2, v1 offset:4
	ds_read2st64_b32 v[76:77], v70 offset0:1 offset1:17
	s_waitcnt lgkmcnt(0)
	v_fma_f32 v52, v37, v2, -v77
	ds_read2st64_b32 v[36:37], v70 offset0:33 offset1:49
	v_fma_f32 v20, v53, v2, -v76
	v_mul_f32_e32 v4, v52, v52
	v_fmac_f32_e32 v4, v20, v20
	s_waitcnt lgkmcnt(0)
	v_fma_f32 v21, v21, v2, -v36
	v_fmac_f32_e32 v4, v21, v21
	v_fma_f32 v2, v5, v2, -v37
	v_fmac_f32_e32 v4, v2, v2
	ds_swizzle_b32 v5, v4 offset:swizzle(SWAP,1)
	s_waitcnt lgkmcnt(0)
	v_add_f32_e32 v4, v4, v5
	ds_swizzle_b32 v5, v4 offset:swizzle(SWAP,2)
	s_waitcnt lgkmcnt(0)
	v_add_f32_e32 v4, v4, v5
	ds_swizzle_b32 v5, v4 offset:swizzle(SWAP,4)
	s_waitcnt lgkmcnt(0)
	v_add_f32_e32 v4, v4, v5
	ds_swizzle_b32 v5, v4 offset:swizzle(SWAP,8)
	s_waitcnt lgkmcnt(0)
	v_add_f32_e32 v4, v4, v5
	ds_swizzle_b32 v5, v4 offset:swizzle(SWAP,16)
	s_waitcnt lgkmcnt(0)
	v_add_f32_e32 v4, v4, v5
	v_fmamk_f32 v4, v4, 0x3c000000, v254
	v_cmp_gt_f32_e32 vcc, s90, v4
	v_mul_f32_e32 v5, 0x4f800000, v4
	s_nop 0
	v_cndmask_b32_e32 v4, v4, v5, vcc
	v_sqrt_f32_e32 v5, v4
	s_nop 0
	v_add_u32_e32 v36, -1, v5
	v_fma_f32 v37, -v36, v5, v4
	v_cmp_ge_f32_e64 s[4:5], 0, v37
	v_add_u32_e32 v37, 1, v5
	s_nop 0
	v_cndmask_b32_e64 v36, v5, v36, s[4:5]
	v_fma_f32 v5, -v37, v5, v4
	v_cmp_lt_f32_e64 s[4:5], 0, v5
	s_nop 1
	v_cndmask_b32_e64 v5, v36, v37, s[4:5]
	v_mul_f32_e32 v36, 0x37800000, v5
	v_cndmask_b32_e32 v5, v5, v36, vcc
	v_cmp_class_f32_e32 vcc, v4, v209
	s_nop 1
	v_cndmask_b32_e32 v4, v5, v4, vcc
	v_div_scale_f32 v5, s[4:5], v4, v4, 1.0
	v_rcp_f32_e32 v36, v5
	s_nop 0
	v_fma_f32 v37, -v5, v36, 1.0
	v_fmac_f32_e32 v36, v37, v36
	v_div_scale_f32 v37, vcc, 1.0, v4, 1.0
	v_mul_f32_e32 v53, v37, v36
	v_fma_f32 v69, -v5, v53, v37
	v_fmac_f32_e32 v53, v69, v36
	v_fma_f32 v5, -v5, v53, v37
	v_div_fmas_f32 v5, v5, v36, v53
	v_div_fixup_f32 v36, v5, v4, 1.0
	v_mul_f32_e32 v5, v20, v36
	v_mul_f32_e32 v20, v52, v36
	v_mul_f32_e32 v5, v72, v5
	v_mul_f32_e32 v20, v74, v20
	v_add_u32_e32 v4, 0x1000, v68
	v_cvt_pk_bf16_f32 v20, v5, v20
	v_mov_b32_e32 v5, v3
	v_lshl_add_u64 v[4:5], v[4:5], 1, s[6:7]
	global_store_short v[4:5], v20, off
	v_add_u32_e32 v4, 0x1020, v68
	v_mov_b32_e32 v5, v3
	v_lshl_add_u64 v[4:5], v[4:5], 1, s[6:7]
	global_store_short_d16_hi v[4:5], v20, off
	v_mul_f32_e32 v4, v21, v36
	v_mul_f32_e32 v2, v2, v36
	v_mul_f32_e32 v4, v71, v4
	v_mul_f32_e32 v2, v73, v2
	v_cvt_pk_bf16_f32 v2, v4, v2
	v_add_u32_e32 v4, 0x1040, v68
	v_mov_b32_e32 v5, v3
	v_lshl_add_u64 v[4:5], v[4:5], 1, s[6:7]
	global_store_short v[4:5], v2, off
	v_add_u32_e32 v4, 0x1060, v68
	v_mov_b32_e32 v5, v3
	v_lshl_add_u64 v[4:5], v[4:5], 1, s[6:7]
	global_store_short_d16_hi v[4:5], v2, off
	ds_read_b32 v2, v1 offset:8
	ds_read2st64_b32 v[4:5], v70 offset0:2 offset1:18
	s_waitcnt lgkmcnt(0)
	v_fma_f32 v20, v54, v2, -v4
	v_fma_f32 v21, v38, v2, -v5
	ds_read2st64_b32 v[4:5], v70 offset0:34 offset1:50
	v_mul_f32_e32 v36, v21, v21
	v_fmac_f32_e32 v36, v20, v20
	s_waitcnt lgkmcnt(0)
	v_fma_f32 v22, v22, v2, -v4
	v_fmac_f32_e32 v36, v22, v22
	v_fma_f32 v2, v6, v2, -v5
	v_fmac_f32_e32 v36, v2, v2
	s_nop 1
	v_add_f32_dpp v4, v36, v36 quad_perm:[1,0,3,2] row_mask:0xf bank_mask:0xf
	s_nop 1
	v_add_f32_dpp v4, v4, v4 quad_perm:[2,3,0,1] row_mask:0xf bank_mask:0xf
	s_nop 1
	v_add_f32_dpp v4, v4, v4 row_half_mirror row_mask:0xf bank_mask:0xf
	s_nop 1
	v_add_f32_dpp v4, v4, v4 row_mirror row_mask:0xf bank_mask:0xf
	ds_swizzle_b32 v5, v4 offset:swizzle(SWAP,16)
	s_waitcnt lgkmcnt(0)
	v_add_f32_e32 v4, v4, v5
	v_fmamk_f32 v4, v4, 0x3c000000, v254
	s_nop 0
	s_nop 0
	s_nop 0
	s_nop 1
	s_nop 1
	s_nop 0
	v_rsq_f32_e32 v6, v4
	s_nop 0
	v_mul_f32_e32 v5, v20, v6
	v_mul_f32_e32 v20, v21, v6
	v_mul_f32_e32 v5, v72, v5
	v_mul_f32_e32 v20, v74, v20
	v_add_u32_e32 v4, 0x2000, v68
	v_cvt_pk_bf16_f32 v20, v5, v20
	v_mov_b32_e32 v5, v3
	v_lshl_add_u64 v[4:5], v[4:5], 1, s[6:7]
	global_store_short v[4:5], v20, off
	v_add_u32_e32 v4, 0x2020, v68
	v_mov_b32_e32 v5, v3
	v_lshl_add_u64 v[4:5], v[4:5], 1, s[6:7]
	global_store_short_d16_hi v[4:5], v20, off
	v_mul_f32_e32 v4, v22, v6
	v_mul_f32_e32 v2, v2, v6
	v_mul_f32_e32 v4, v71, v4
	v_mul_f32_e32 v2, v73, v2
	v_cvt_pk_bf16_f32 v2, v4, v2
	v_add_u32_e32 v4, 0x2040, v68
	v_mov_b32_e32 v5, v3
	v_lshl_add_u64 v[4:5], v[4:5], 1, s[6:7]
	global_store_short v[4:5], v2, off
	v_add_u32_e32 v4, 0x2060, v68
	v_mov_b32_e32 v5, v3
	v_lshl_add_u64 v[4:5], v[4:5], 1, s[6:7]
	global_store_short_d16_hi v[4:5], v2, off
	ds_read_b32 v2, v1 offset:12
	ds_read2st64_b32 v[4:5], v70 offset0:3 offset1:19
	s_waitcnt lgkmcnt(0)
	v_fma_f32 v6, v55, v2, -v4
	v_fma_f32 v20, v39, v2, -v5
	ds_read2st64_b32 v[4:5], v70 offset0:35 offset1:51
	v_mul_f32_e32 v21, v20, v20
	v_fmac_f32_e32 v21, v6, v6
	s_waitcnt lgkmcnt(0)
	v_fma_f32 v22, v23, v2, -v4
	v_fmac_f32_e32 v21, v22, v22
	v_fma_f32 v2, v7, v2, -v5
	v_fmac_f32_e32 v21, v2, v2
	s_nop 1
	v_add_f32_dpp v4, v21, v21 quad_perm:[1,0,3,2] row_mask:0xf bank_mask:0xf
	s_nop 1
	v_add_f32_dpp v4, v4, v4 quad_perm:[2,3,0,1] row_mask:0xf bank_mask:0xf
	s_nop 1
	v_add_f32_dpp v4, v4, v4 row_half_mirror row_mask:0xf bank_mask:0xf
	s_nop 1
	v_add_f32_dpp v4, v4, v4 row_mirror row_mask:0xf bank_mask:0xf
	ds_swizzle_b32 v5, v4 offset:swizzle(SWAP,16)
	s_waitcnt lgkmcnt(0)
	v_add_f32_e32 v4, v4, v5
	v_fmamk_f32 v4, v4, 0x3c000000, v254
	s_nop 0
	s_nop 0
	s_nop 0
	s_nop 1
	s_nop 1
	s_nop 0
	v_rsq_f32_e32 v7, v4
	s_nop 0
	v_mul_f32_e32 v5, v6, v7
	v_mul_f32_e32 v6, v20, v7
	v_mul_f32_e32 v5, v72, v5
	v_mul_f32_e32 v6, v74, v6
	v_add_u32_e32 v4, 0x3000, v68
	v_cvt_pk_bf16_f32 v6, v5, v6
	v_mov_b32_e32 v5, v3
	v_lshl_add_u64 v[4:5], v[4:5], 1, s[6:7]
	global_store_short v[4:5], v6, off
	v_add_u32_e32 v4, 0x3020, v68
	v_mov_b32_e32 v5, v3
	v_lshl_add_u64 v[4:5], v[4:5], 1, s[6:7]
	global_store_short_d16_hi v[4:5], v6, off
	v_mul_f32_e32 v4, v22, v7
	v_mul_f32_e32 v2, v2, v7
	v_mul_f32_e32 v4, v71, v4
	v_mul_f32_e32 v2, v73, v2
	v_cvt_pk_bf16_f32 v2, v4, v2
	v_add_u32_e32 v4, 0x3040, v68
	v_mov_b32_e32 v5, v3
	v_lshl_add_u64 v[4:5], v[4:5], 1, s[6:7]
	global_store_short v[4:5], v2, off
	v_add_u32_e32 v4, 0x3060, v68
	v_mov_b32_e32 v5, v3
	v_lshl_add_u64 v[4:5], v[4:5], 1, s[6:7]
	global_store_short_d16_hi v[4:5], v2, off
	ds_read_b32 v2, v1 offset:32
	ds_read2st64_b32 v[4:5], v70 offset0:4 offset1:20
	s_waitcnt lgkmcnt(0)
	v_fma_f32 v6, v56, v2, -v4
	v_fma_f32 v7, v40, v2, -v5
	ds_read2st64_b32 v[4:5], v70 offset0:36 offset1:52
	v_mul_f32_e32 v20, v7, v7
	v_fmac_f32_e32 v20, v6, v6
	s_waitcnt lgkmcnt(0)
	v_fma_f32 v21, v24, v2, -v4
	v_fmac_f32_e32 v20, v21, v21
	v_fma_f32 v2, v8, v2, -v5
	v_fmac_f32_e32 v20, v2, v2
	s_nop 1
	v_add_f32_dpp v4, v20, v20 quad_perm:[1,0,3,2] row_mask:0xf bank_mask:0xf
	s_nop 1
	v_add_f32_dpp v4, v4, v4 quad_perm:[2,3,0,1] row_mask:0xf bank_mask:0xf
	s_nop 1
	v_add_f32_dpp v4, v4, v4 row_half_mirror row_mask:0xf bank_mask:0xf
	s_nop 1
	v_add_f32_dpp v4, v4, v4 row_mirror row_mask:0xf bank_mask:0xf
	ds_swizzle_b32 v5, v4 offset:swizzle(SWAP,16)
	s_waitcnt lgkmcnt(0)
	v_add_f32_e32 v4, v4, v5
	v_fmamk_f32 v4, v4, 0x3c000000, v254
	s_nop 0
	s_nop 0
	s_nop 0
	s_nop 1
	s_nop 1
	s_nop 0
	v_rsq_f32_e32 v8, v4
	s_nop 0
	v_mul_f32_e32 v5, v6, v8
	v_mul_f32_e32 v6, v7, v8
	v_mul_f32_e32 v5, v72, v5
	v_mul_f32_e32 v6, v74, v6
	v_add_u32_e32 v4, 0x8000, v68
	v_cvt_pk_bf16_f32 v6, v5, v6
	v_mov_b32_e32 v5, v3
	v_lshl_add_u64 v[4:5], v[4:5], 1, s[6:7]
	global_store_short v[4:5], v6, off
	v_add_u32_e32 v4, 0x8020, v68
	v_mov_b32_e32 v5, v3
	v_lshl_add_u64 v[4:5], v[4:5], 1, s[6:7]
	global_store_short_d16_hi v[4:5], v6, off
	v_mul_f32_e32 v4, v21, v8
	v_mul_f32_e32 v2, v2, v8
	v_mul_f32_e32 v4, v71, v4
	v_mul_f32_e32 v2, v73, v2
	v_cvt_pk_bf16_f32 v2, v4, v2
	v_add_u32_e32 v4, 0x8040, v68
	v_mov_b32_e32 v5, v3
	v_lshl_add_u64 v[4:5], v[4:5], 1, s[6:7]
	global_store_short v[4:5], v2, off
	v_add_u32_e32 v4, 0x8060, v68
	v_mov_b32_e32 v5, v3
	v_lshl_add_u64 v[4:5], v[4:5], 1, s[6:7]
	global_store_short_d16_hi v[4:5], v2, off
	ds_read_b32 v2, v1 offset:36
	ds_read2st64_b32 v[4:5], v70 offset0:5 offset1:21
	s_waitcnt lgkmcnt(0)
	v_fma_f32 v6, v57, v2, -v4
	v_fma_f32 v7, v41, v2, -v5
	ds_read2st64_b32 v[4:5], v70 offset0:37 offset1:53
	v_mul_f32_e32 v8, v7, v7
	v_fmac_f32_e32 v8, v6, v6
	s_waitcnt lgkmcnt(0)
	v_fma_f32 v20, v25, v2, -v4
	v_fmac_f32_e32 v8, v20, v20
	v_fma_f32 v2, v9, v2, -v5
	v_fmac_f32_e32 v8, v2, v2
	s_nop 1
	v_add_f32_dpp v4, v8, v8 quad_perm:[1,0,3,2] row_mask:0xf bank_mask:0xf
	s_nop 1
	v_add_f32_dpp v4, v4, v4 quad_perm:[2,3,0,1] row_mask:0xf bank_mask:0xf
	s_nop 1
	v_add_f32_dpp v4, v4, v4 row_half_mirror row_mask:0xf bank_mask:0xf
	s_nop 1
	v_add_f32_dpp v4, v4, v4 row_mirror row_mask:0xf bank_mask:0xf
	ds_swizzle_b32 v5, v4 offset:swizzle(SWAP,16)
	s_waitcnt lgkmcnt(0)
	v_add_f32_e32 v4, v4, v5
	v_fmamk_f32 v4, v4, 0x3c000000, v254
	s_nop 0
	s_nop 0
	s_nop 0
	s_nop 1
	s_nop 1
	s_nop 0
	v_rsq_f32_e32 v8, v4
	s_nop 0
	v_mul_f32_e32 v5, v6, v8
	v_mul_f32_e32 v6, v7, v8
	v_mul_f32_e32 v5, v72, v5
	v_mul_f32_e32 v6, v74, v6
	v_add_u32_e32 v4, 0x9000, v68
	v_cvt_pk_bf16_f32 v6, v5, v6
	v_mov_b32_e32 v5, v3
	v_lshl_add_u64 v[4:5], v[4:5], 1, s[6:7]
	global_store_short v[4:5], v6, off
	v_add_u32_e32 v4, 0x9020, v68
	v_mov_b32_e32 v5, v3
	v_lshl_add_u64 v[4:5], v[4:5], 1, s[6:7]
	global_store_short_d16_hi v[4:5], v6, off
	v_mul_f32_e32 v4, v20, v8
	v_mul_f32_e32 v2, v2, v8
	v_mul_f32_e32 v4, v71, v4
	v_mul_f32_e32 v2, v73, v2
	v_cvt_pk_bf16_f32 v2, v4, v2
	v_add_u32_e32 v4, 0x9040, v68
	v_mov_b32_e32 v5, v3
	v_lshl_add_u64 v[4:5], v[4:5], 1, s[6:7]
	global_store_short v[4:5], v2, off
	v_add_u32_e32 v4, 0x9060, v68
	v_mov_b32_e32 v5, v3
	v_lshl_add_u64 v[4:5], v[4:5], 1, s[6:7]
	global_store_short_d16_hi v[4:5], v2, off
	ds_read_b32 v2, v1 offset:40
	ds_read2st64_b32 v[4:5], v70 offset0:6 offset1:22
	ds_read_b32 v84, v1 offset:44
	ds_read2st64_b32 v[86:87], v70 offset0:7 offset1:23
	s_waitcnt lgkmcnt(0)
	v_fma_f32 v6, v58, v2, -v4
	v_fma_f32 v7, v42, v2, -v5
	ds_read2st64_b32 v[4:5], v70 offset0:38 offset1:54
	v_mul_f32_e32 v8, v7, v7
	v_fmac_f32_e32 v8, v6, v6
	v_fma_f32 v88, v59, v84, -v86
	v_fma_f32 v89, v43, v84, -v87
	ds_read2st64_b32 v[86:87], v70 offset0:39 offset1:55
	v_mul_f32_e32 v90, v89, v89
	v_fmac_f32_e32 v90, v88, v88
	s_waitcnt lgkmcnt(0)
	v_fma_f32 v9, v26, v2, -v4
	v_fmac_f32_e32 v8, v9, v9
	v_fma_f32 v2, v10, v2, -v5
	v_fmac_f32_e32 v8, v2, v2
	s_nop 1
	v_add_f32_dpp v4, v8, v8 quad_perm:[1,0,3,2] row_mask:0xf bank_mask:0xf
	s_nop 1
	v_add_f32_dpp v4, v4, v4 quad_perm:[2,3,0,1] row_mask:0xf bank_mask:0xf
	s_nop 1
	v_add_f32_dpp v4, v4, v4 row_half_mirror row_mask:0xf bank_mask:0xf
	s_nop 1
	v_add_f32_dpp v4, v4, v4 row_mirror row_mask:0xf bank_mask:0xf
	ds_swizzle_b32 v5, v4 offset:swizzle(SWAP,16)
	v_fma_f32 v91, v27, v84, -v86
	v_fmac_f32_e32 v90, v91, v91
	v_fma_f32 v84, v11, v84, -v87
	v_fmac_f32_e32 v90, v84, v84
	s_nop 1
	v_add_f32_dpp v86, v90, v90 quad_perm:[1,0,3,2] row_mask:0xf bank_mask:0xf
	s_nop 1
	v_add_f32_dpp v86, v86, v86 quad_perm:[2,3,0,1] row_mask:0xf bank_mask:0xf
	s_nop 1
	v_add_f32_dpp v86, v86, v86 row_half_mirror row_mask:0xf bank_mask:0xf
	s_nop 1
	v_add_f32_dpp v86, v86, v86 row_mirror row_mask:0xf bank_mask:0xf
	ds_swizzle_b32 v87, v86 offset:swizzle(SWAP,16)
	s_waitcnt lgkmcnt(0)
	v_add_f32_e32 v4, v4, v5
	v_fmamk_f32 v4, v4, 0x3c000000, v254
	s_nop 0
	s_nop 0
	s_nop 0
	s_nop 1
	s_nop 1
	s_nop 0
	v_rsq_f32_e32 v8, v4
	s_nop 0
	v_mul_f32_e32 v5, v6, v8
	v_mul_f32_e32 v6, v7, v8
	v_mul_f32_e32 v5, v72, v5
	v_mul_f32_e32 v6, v74, v6
	v_add_u32_e32 v4, 0xa000, v68
	v_cvt_pk_bf16_f32 v6, v5, v6
	v_mov_b32_e32 v5, v3
	v_lshl_add_u64 v[4:5], v[4:5], 1, s[6:7]
	global_store_short v[4:5], v6, off
	v_add_u32_e32 v4, 0xa020, v68
	v_mov_b32_e32 v5, v3
	v_lshl_add_u64 v[4:5], v[4:5], 1, s[6:7]
	global_store_short_d16_hi v[4:5], v6, off
	v_mul_f32_e32 v4, v9, v8
	v_mul_f32_e32 v2, v2, v8
	v_mul_f32_e32 v4, v71, v4
	v_mul_f32_e32 v2, v73, v2
	v_cvt_pk_bf16_f32 v2, v4, v2
	v_add_u32_e32 v4, 0xa040, v68
	v_mov_b32_e32 v5, v3
	v_lshl_add_u64 v[4:5], v[4:5], 1, s[6:7]
	global_store_short v[4:5], v2, off
	v_add_u32_e32 v4, 0xa060, v68
	v_mov_b32_e32 v5, v3
	v_lshl_add_u64 v[4:5], v[4:5], 1, s[6:7]
	global_store_short_d16_hi v[4:5], v2, off
	v_add_f32_e32 v86, v86, v87
	v_fmamk_f32 v86, v86, 0x3c000000, v254
	s_nop 0
	s_nop 0
	s_nop 0
	s_nop 1
	s_nop 1
	s_nop 0
	v_rsq_f32_e32 v90, v86
	s_nop 0
	v_mul_f32_e32 v87, v88, v90
	v_mul_f32_e32 v88, v89, v90
	v_mul_f32_e32 v87, v72, v87
	v_mul_f32_e32 v88, v74, v88
	v_add_u32_e32 v86, 0xb000, v68
	v_cvt_pk_bf16_f32 v88, v87, v88
	v_mov_b32_e32 v87, v3
	v_lshl_add_u64 v[86:87], v[86:87], 1, s[6:7]
	global_store_short v[86:87], v88, off
	v_add_u32_e32 v86, 0xb020, v68
	v_mov_b32_e32 v87, v3
	v_lshl_add_u64 v[86:87], v[86:87], 1, s[6:7]
	global_store_short_d16_hi v[86:87], v88, off
	v_mul_f32_e32 v86, v91, v90
	v_mul_f32_e32 v84, v84, v90
	v_mul_f32_e32 v86, v71, v86
	v_mul_f32_e32 v84, v73, v84
	v_cvt_pk_bf16_f32 v84, v86, v84
	v_add_u32_e32 v86, 0xb040, v68
	v_mov_b32_e32 v87, v3
	v_lshl_add_u64 v[86:87], v[86:87], 1, s[6:7]
	global_store_short v[86:87], v84, off
	v_add_u32_e32 v86, 0xb060, v68
	v_mov_b32_e32 v87, v3
	v_lshl_add_u64 v[86:87], v[86:87], 1, s[6:7]
	global_store_short_d16_hi v[86:87], v84, off
	ds_read_b32 v2, v1 offset:64
	ds_read2st64_b32 v[4:5], v70 offset0:8 offset1:24
	ds_read_b32 v84, v1 offset:68
	ds_read2st64_b32 v[86:87], v70 offset0:9 offset1:25
	s_waitcnt lgkmcnt(0)
	v_fma_f32 v6, v60, v2, -v4
	v_fma_f32 v7, v44, v2, -v5
	ds_read2st64_b32 v[4:5], v70 offset0:40 offset1:56
	v_mul_f32_e32 v8, v7, v7
	v_fmac_f32_e32 v8, v6, v6
	v_fma_f32 v88, v61, v84, -v86
	v_fma_f32 v89, v45, v84, -v87
	ds_read2st64_b32 v[86:87], v70 offset0:41 offset1:57
	v_mul_f32_e32 v90, v89, v89
	v_fmac_f32_e32 v90, v88, v88
	s_waitcnt lgkmcnt(0)
	v_fma_f32 v9, v28, v2, -v4
	v_fmac_f32_e32 v8, v9, v9
	v_fma_f32 v2, v12, v2, -v5
	v_fmac_f32_e32 v8, v2, v2
	s_nop 1
	v_add_f32_dpp v4, v8, v8 quad_perm:[1,0,3,2] row_mask:0xf bank_mask:0xf
	s_nop 1
	v_add_f32_dpp v4, v4, v4 quad_perm:[2,3,0,1] row_mask:0xf bank_mask:0xf
	s_nop 1
	v_add_f32_dpp v4, v4, v4 row_half_mirror row_mask:0xf bank_mask:0xf
	s_nop 1
	v_add_f32_dpp v4, v4, v4 row_mirror row_mask:0xf bank_mask:0xf
	ds_swizzle_b32 v5, v4 offset:swizzle(SWAP,16)
	v_fma_f32 v91, v29, v84, -v86
	v_fmac_f32_e32 v90, v91, v91
	v_fma_f32 v84, v13, v84, -v87
	v_fmac_f32_e32 v90, v84, v84
	s_nop 1
	v_add_f32_dpp v86, v90, v90 quad_perm:[1,0,3,2] row_mask:0xf bank_mask:0xf
	s_nop 1
	v_add_f32_dpp v86, v86, v86 quad_perm:[2,3,0,1] row_mask:0xf bank_mask:0xf
	s_nop 1
	v_add_f32_dpp v86, v86, v86 row_half_mirror row_mask:0xf bank_mask:0xf
	s_nop 1
	v_add_f32_dpp v86, v86, v86 row_mirror row_mask:0xf bank_mask:0xf
	ds_swizzle_b32 v87, v86 offset:swizzle(SWAP,16)
	s_waitcnt lgkmcnt(0)
	v_add_f32_e32 v4, v4, v5
	v_fmamk_f32 v4, v4, 0x3c000000, v254
	s_nop 0
	s_nop 0
	s_nop 0
	s_nop 1
	s_nop 1
	s_nop 0
	v_rsq_f32_e32 v8, v4
	s_nop 0
	v_mul_f32_e32 v5, v6, v8
	v_mul_f32_e32 v6, v7, v8
	v_mul_f32_e32 v5, v72, v5
	v_mul_f32_e32 v6, v74, v6
	v_add_u32_e32 v4, 0x10000, v68
	v_cvt_pk_bf16_f32 v6, v5, v6
	v_mov_b32_e32 v5, v3
	v_lshl_add_u64 v[4:5], v[4:5], 1, s[6:7]
	global_store_short v[4:5], v6, off
	v_add_u32_e32 v4, 0x10020, v68
	v_mov_b32_e32 v5, v3
	v_lshl_add_u64 v[4:5], v[4:5], 1, s[6:7]
	global_store_short_d16_hi v[4:5], v6, off
	v_mul_f32_e32 v4, v9, v8
	v_mul_f32_e32 v2, v2, v8
	v_mul_f32_e32 v4, v71, v4
	v_mul_f32_e32 v2, v73, v2
	v_cvt_pk_bf16_f32 v2, v4, v2
	v_add_u32_e32 v4, 0x10040, v68
	v_mov_b32_e32 v5, v3
	v_lshl_add_u64 v[4:5], v[4:5], 1, s[6:7]
	global_store_short v[4:5], v2, off
	v_add_u32_e32 v4, 0x10060, v68
	v_mov_b32_e32 v5, v3
	v_lshl_add_u64 v[4:5], v[4:5], 1, s[6:7]
	global_store_short_d16_hi v[4:5], v2, off
	v_add_f32_e32 v86, v86, v87
	v_fmamk_f32 v86, v86, 0x3c000000, v254
	s_nop 0
	s_nop 0
	s_nop 0
	s_nop 1
	s_nop 1
	s_nop 0
	v_rsq_f32_e32 v90, v86
	s_nop 0
	v_mul_f32_e32 v87, v88, v90
	v_mul_f32_e32 v88, v89, v90
	v_mul_f32_e32 v87, v72, v87
	v_mul_f32_e32 v88, v74, v88
	v_add_u32_e32 v86, 0x11000, v68
	v_cvt_pk_bf16_f32 v88, v87, v88
	v_mov_b32_e32 v87, v3
	v_lshl_add_u64 v[86:87], v[86:87], 1, s[6:7]
	global_store_short v[86:87], v88, off
	v_add_u32_e32 v86, 0x11020, v68
	v_mov_b32_e32 v87, v3
	v_lshl_add_u64 v[86:87], v[86:87], 1, s[6:7]
	global_store_short_d16_hi v[86:87], v88, off
	v_mul_f32_e32 v86, v91, v90
	v_mul_f32_e32 v84, v84, v90
	v_mul_f32_e32 v86, v71, v86
	v_mul_f32_e32 v84, v73, v84
	v_cvt_pk_bf16_f32 v84, v86, v84
	v_add_u32_e32 v86, 0x11040, v68
	v_mov_b32_e32 v87, v3
	v_lshl_add_u64 v[86:87], v[86:87], 1, s[6:7]
	global_store_short v[86:87], v84, off
	v_add_u32_e32 v86, 0x11060, v68
	v_mov_b32_e32 v87, v3
	v_lshl_add_u64 v[86:87], v[86:87], 1, s[6:7]
	global_store_short_d16_hi v[86:87], v84, off
	ds_read_b32 v2, v1 offset:72
	ds_read2st64_b32 v[4:5], v70 offset0:10 offset1:26
	ds_read_b32 v84, v1 offset:76
	ds_read2st64_b32 v[86:87], v70 offset0:11 offset1:27
	s_waitcnt lgkmcnt(0)
	v_fma_f32 v6, v62, v2, -v4
	v_fma_f32 v7, v46, v2, -v5
	ds_read2st64_b32 v[4:5], v70 offset0:42 offset1:58
	v_mul_f32_e32 v8, v7, v7
	v_fmac_f32_e32 v8, v6, v6
	v_fma_f32 v88, v63, v84, -v86
	v_fma_f32 v89, v47, v84, -v87
	ds_read2st64_b32 v[86:87], v70 offset0:43 offset1:59
	v_mul_f32_e32 v90, v89, v89
	v_fmac_f32_e32 v90, v88, v88
	s_waitcnt lgkmcnt(0)
	v_fma_f32 v9, v30, v2, -v4
	v_fmac_f32_e32 v8, v9, v9
	v_fma_f32 v2, v14, v2, -v5
	v_fmac_f32_e32 v8, v2, v2
	s_nop 1
	v_add_f32_dpp v4, v8, v8 quad_perm:[1,0,3,2] row_mask:0xf bank_mask:0xf
	s_nop 1
	v_add_f32_dpp v4, v4, v4 quad_perm:[2,3,0,1] row_mask:0xf bank_mask:0xf
	s_nop 1
	v_add_f32_dpp v4, v4, v4 row_half_mirror row_mask:0xf bank_mask:0xf
	s_nop 1
	v_add_f32_dpp v4, v4, v4 row_mirror row_mask:0xf bank_mask:0xf
	ds_swizzle_b32 v5, v4 offset:swizzle(SWAP,16)
	v_fma_f32 v91, v31, v84, -v86
	v_fmac_f32_e32 v90, v91, v91
	v_fma_f32 v84, v15, v84, -v87
	v_fmac_f32_e32 v90, v84, v84
	s_nop 1
	v_add_f32_dpp v86, v90, v90 quad_perm:[1,0,3,2] row_mask:0xf bank_mask:0xf
	s_nop 1
	v_add_f32_dpp v86, v86, v86 quad_perm:[2,3,0,1] row_mask:0xf bank_mask:0xf
	s_nop 1
	v_add_f32_dpp v86, v86, v86 row_half_mirror row_mask:0xf bank_mask:0xf
	s_nop 1
	v_add_f32_dpp v86, v86, v86 row_mirror row_mask:0xf bank_mask:0xf
	ds_swizzle_b32 v87, v86 offset:swizzle(SWAP,16)
	s_waitcnt lgkmcnt(0)
	v_add_f32_e32 v4, v4, v5
	v_fmamk_f32 v4, v4, 0x3c000000, v254
	s_nop 0
	s_nop 0
	s_nop 0
	s_nop 1
	s_nop 1
	s_nop 0
	v_rsq_f32_e32 v8, v4
	s_nop 0
	v_mul_f32_e32 v5, v6, v8
	v_mul_f32_e32 v6, v7, v8
	v_mul_f32_e32 v5, v72, v5
	v_mul_f32_e32 v6, v74, v6
	v_add_u32_e32 v4, 0x12000, v68
	v_cvt_pk_bf16_f32 v6, v5, v6
	v_mov_b32_e32 v5, v3
	v_lshl_add_u64 v[4:5], v[4:5], 1, s[6:7]
	global_store_short v[4:5], v6, off
	v_add_u32_e32 v4, 0x12020, v68
	v_mov_b32_e32 v5, v3
	v_lshl_add_u64 v[4:5], v[4:5], 1, s[6:7]
	global_store_short_d16_hi v[4:5], v6, off
	v_mul_f32_e32 v4, v9, v8
	v_mul_f32_e32 v2, v2, v8
	v_mul_f32_e32 v4, v71, v4
	v_mul_f32_e32 v2, v73, v2
	v_cvt_pk_bf16_f32 v2, v4, v2
	v_add_u32_e32 v4, 0x12040, v68
	v_mov_b32_e32 v5, v3
	v_lshl_add_u64 v[4:5], v[4:5], 1, s[6:7]
	global_store_short v[4:5], v2, off
	v_add_u32_e32 v4, 0x12060, v68
	v_mov_b32_e32 v5, v3
	v_lshl_add_u64 v[4:5], v[4:5], 1, s[6:7]
	global_store_short_d16_hi v[4:5], v2, off
	v_add_f32_e32 v86, v86, v87
	v_fmamk_f32 v86, v86, 0x3c000000, v254
	s_nop 0
	s_nop 0
	s_nop 0
	s_nop 1
	s_nop 1
	s_nop 0
	v_rsq_f32_e32 v90, v86
	s_nop 0
	v_mul_f32_e32 v87, v88, v90
	v_mul_f32_e32 v88, v89, v90
	v_mul_f32_e32 v87, v72, v87
	v_mul_f32_e32 v88, v74, v88
	v_add_u32_e32 v86, 0x13000, v68
	v_cvt_pk_bf16_f32 v88, v87, v88
	v_mov_b32_e32 v87, v3
	v_lshl_add_u64 v[86:87], v[86:87], 1, s[6:7]
	global_store_short v[86:87], v88, off
	v_add_u32_e32 v86, 0x13020, v68
	v_mov_b32_e32 v87, v3
	v_lshl_add_u64 v[86:87], v[86:87], 1, s[6:7]
	global_store_short_d16_hi v[86:87], v88, off
	v_mul_f32_e32 v86, v91, v90
	v_mul_f32_e32 v84, v84, v90
	v_mul_f32_e32 v86, v71, v86
	v_mul_f32_e32 v84, v73, v84
	v_cvt_pk_bf16_f32 v84, v86, v84
	v_add_u32_e32 v86, 0x13040, v68
	v_mov_b32_e32 v87, v3
	v_lshl_add_u64 v[86:87], v[86:87], 1, s[6:7]
	global_store_short v[86:87], v84, off
	v_add_u32_e32 v86, 0x13060, v68
	v_mov_b32_e32 v87, v3
	v_lshl_add_u64 v[86:87], v[86:87], 1, s[6:7]
	global_store_short_d16_hi v[86:87], v84, off
	ds_read_b32 v2, v1 offset:96
	ds_read2st64_b32 v[4:5], v70 offset0:12 offset1:28
	ds_read_b32 v84, v1 offset:100
	ds_read2st64_b32 v[86:87], v70 offset0:13 offset1:29
	s_waitcnt lgkmcnt(0)
	v_fma_f32 v6, v64, v2, -v4
	v_fma_f32 v7, v48, v2, -v5
	ds_read2st64_b32 v[4:5], v70 offset0:44 offset1:60
	v_mul_f32_e32 v8, v7, v7
	v_fmac_f32_e32 v8, v6, v6
	v_fma_f32 v88, v65, v84, -v86
	v_fma_f32 v89, v49, v84, -v87
	ds_read2st64_b32 v[86:87], v70 offset0:45 offset1:61
	v_mul_f32_e32 v90, v89, v89
	v_fmac_f32_e32 v90, v88, v88
	s_waitcnt lgkmcnt(0)
	v_fma_f32 v9, v32, v2, -v4
	v_fmac_f32_e32 v8, v9, v9
	v_fma_f32 v2, v16, v2, -v5
	v_fmac_f32_e32 v8, v2, v2
	s_nop 1
	v_add_f32_dpp v4, v8, v8 quad_perm:[1,0,3,2] row_mask:0xf bank_mask:0xf
	s_nop 1
	v_add_f32_dpp v4, v4, v4 quad_perm:[2,3,0,1] row_mask:0xf bank_mask:0xf
	s_nop 1
	v_add_f32_dpp v4, v4, v4 row_half_mirror row_mask:0xf bank_mask:0xf
	s_nop 1
	v_add_f32_dpp v4, v4, v4 row_mirror row_mask:0xf bank_mask:0xf
	ds_swizzle_b32 v5, v4 offset:swizzle(SWAP,16)
	v_fma_f32 v91, v33, v84, -v86
	v_fmac_f32_e32 v90, v91, v91
	v_fma_f32 v84, v17, v84, -v87
	v_fmac_f32_e32 v90, v84, v84
	s_nop 1
	v_add_f32_dpp v86, v90, v90 quad_perm:[1,0,3,2] row_mask:0xf bank_mask:0xf
	s_nop 1
	v_add_f32_dpp v86, v86, v86 quad_perm:[2,3,0,1] row_mask:0xf bank_mask:0xf
	s_nop 1
	v_add_f32_dpp v86, v86, v86 row_half_mirror row_mask:0xf bank_mask:0xf
	s_nop 1
	v_add_f32_dpp v86, v86, v86 row_mirror row_mask:0xf bank_mask:0xf
	ds_swizzle_b32 v87, v86 offset:swizzle(SWAP,16)
	s_waitcnt lgkmcnt(0)
	v_add_f32_e32 v4, v4, v5
	v_fmamk_f32 v4, v4, 0x3c000000, v254
	s_nop 0
	s_nop 0
	s_nop 0
	s_nop 1
	s_nop 1
	s_nop 0
	v_rsq_f32_e32 v8, v4
	s_nop 0
	v_mul_f32_e32 v5, v6, v8
	v_mul_f32_e32 v6, v7, v8
	v_mul_f32_e32 v5, v72, v5
	v_mul_f32_e32 v6, v74, v6
	v_add_u32_e32 v4, 0x18000, v68
	v_cvt_pk_bf16_f32 v6, v5, v6
	v_mov_b32_e32 v5, v3
	v_lshl_add_u64 v[4:5], v[4:5], 1, s[6:7]
	global_store_short v[4:5], v6, off
	v_add_u32_e32 v4, 0x18020, v68
	v_mov_b32_e32 v5, v3
	v_lshl_add_u64 v[4:5], v[4:5], 1, s[6:7]
	global_store_short_d16_hi v[4:5], v6, off
	v_mul_f32_e32 v4, v9, v8
	v_mul_f32_e32 v2, v2, v8
	v_mul_f32_e32 v4, v71, v4
	v_mul_f32_e32 v2, v73, v2
	v_cvt_pk_bf16_f32 v2, v4, v2
	v_add_u32_e32 v4, 0x18040, v68
	v_mov_b32_e32 v5, v3
	v_lshl_add_u64 v[4:5], v[4:5], 1, s[6:7]
	global_store_short v[4:5], v2, off
	v_add_u32_e32 v4, 0x18060, v68
	v_mov_b32_e32 v5, v3
	v_lshl_add_u64 v[4:5], v[4:5], 1, s[6:7]
	global_store_short_d16_hi v[4:5], v2, off
	v_add_f32_e32 v86, v86, v87
	v_fmamk_f32 v86, v86, 0x3c000000, v254
	s_nop 0
	s_nop 0
	s_nop 0
	s_nop 1
	s_nop 1
	s_nop 0
	v_rsq_f32_e32 v90, v86
	s_nop 0
	v_mul_f32_e32 v87, v88, v90
	v_mul_f32_e32 v88, v89, v90
	v_mul_f32_e32 v87, v72, v87
	v_mul_f32_e32 v88, v74, v88
	v_add_u32_e32 v86, 0x19000, v68
	v_cvt_pk_bf16_f32 v88, v87, v88
	v_mov_b32_e32 v87, v3
	v_lshl_add_u64 v[86:87], v[86:87], 1, s[6:7]
	global_store_short v[86:87], v88, off
	v_add_u32_e32 v86, 0x19020, v68
	v_mov_b32_e32 v87, v3
	v_lshl_add_u64 v[86:87], v[86:87], 1, s[6:7]
	global_store_short_d16_hi v[86:87], v88, off
	v_mul_f32_e32 v86, v91, v90
	v_mul_f32_e32 v84, v84, v90
	v_mul_f32_e32 v86, v71, v86
	v_mul_f32_e32 v84, v73, v84
	v_cvt_pk_bf16_f32 v84, v86, v84
	v_add_u32_e32 v86, 0x19040, v68
	v_mov_b32_e32 v87, v3
	v_lshl_add_u64 v[86:87], v[86:87], 1, s[6:7]
	global_store_short v[86:87], v84, off
	v_add_u32_e32 v86, 0x19060, v68
	v_mov_b32_e32 v87, v3
	v_lshl_add_u64 v[86:87], v[86:87], 1, s[6:7]
	global_store_short_d16_hi v[86:87], v84, off
	ds_read_b32 v2, v1 offset:104
	ds_read2st64_b32 v[4:5], v70 offset0:14 offset1:30
	s_waitcnt lgkmcnt(0)
	v_fma_f32 v6, v66, v2, -v4
	v_fma_f32 v7, v50, v2, -v5
	ds_read2st64_b32 v[4:5], v70 offset0:46 offset1:62
	v_mul_f32_e32 v8, v7, v7
	v_fmac_f32_e32 v8, v6, v6
	s_waitcnt lgkmcnt(0)
	v_fma_f32 v9, v34, v2, -v4
	v_fmac_f32_e32 v8, v9, v9
	v_fma_f32 v2, v18, v2, -v5
	v_fmac_f32_e32 v8, v2, v2
	s_nop 1
	v_add_f32_dpp v4, v8, v8 quad_perm:[1,0,3,2] row_mask:0xf bank_mask:0xf
	s_nop 1
	v_add_f32_dpp v4, v4, v4 quad_perm:[2,3,0,1] row_mask:0xf bank_mask:0xf
	s_nop 1
	v_add_f32_dpp v4, v4, v4 row_half_mirror row_mask:0xf bank_mask:0xf
	s_nop 1
	v_add_f32_dpp v4, v4, v4 row_mirror row_mask:0xf bank_mask:0xf
	ds_swizzle_b32 v5, v4 offset:swizzle(SWAP,16)
	s_waitcnt lgkmcnt(0)
	v_add_f32_e32 v4, v4, v5
	v_fmamk_f32 v4, v4, 0x3c000000, v254
	v_cmp_gt_f32_e32 vcc, s90, v4
	v_mul_f32_e32 v5, 0x4f800000, v4
	s_nop 0
	v_cndmask_b32_e32 v4, v4, v5, vcc
	v_sqrt_f32_e32 v5, v4
	s_nop 0
	v_add_u32_e32 v8, -1, v5
	v_fma_f32 v10, -v8, v5, v4
	v_cmp_ge_f32_e64 s[4:5], 0, v10
	v_add_u32_e32 v10, 1, v5
	s_nop 0
	v_cndmask_b32_e64 v8, v5, v8, s[4:5]
	v_fma_f32 v5, -v10, v5, v4
	v_cmp_lt_f32_e64 s[4:5], 0, v5
	s_nop 1
	v_cndmask_b32_e64 v5, v8, v10, s[4:5]
	v_mul_f32_e32 v8, 0x37800000, v5
	v_cndmask_b32_e32 v5, v5, v8, vcc
	v_cmp_class_f32_e32 vcc, v4, v209
	s_nop 1
	v_cndmask_b32_e32 v4, v5, v4, vcc
	v_div_scale_f32 v5, s[4:5], v4, v4, 1.0
	v_rcp_f32_e32 v8, v5
	s_nop 0
	v_fma_f32 v10, -v5, v8, 1.0
	v_fmac_f32_e32 v8, v10, v8
	v_div_scale_f32 v10, vcc, 1.0, v4, 1.0
	v_mul_f32_e32 v11, v10, v8
	v_fma_f32 v12, -v5, v11, v10
	v_fmac_f32_e32 v11, v12, v8
	v_fma_f32 v5, -v5, v11, v10
	v_div_fmas_f32 v5, v5, v8, v11
	v_div_fixup_f32 v8, v5, v4, 1.0
	v_mul_f32_e32 v5, v6, v8
	v_mul_f32_e32 v6, v7, v8
	v_mul_f32_e32 v5, v72, v5
	v_mul_f32_e32 v6, v74, v6
	v_add_u32_e32 v4, 0x1a000, v68
	v_cvt_pk_bf16_f32 v6, v5, v6
	v_mov_b32_e32 v5, v3
	v_lshl_add_u64 v[4:5], v[4:5], 1, s[6:7]
	global_store_short v[4:5], v6, off
	v_add_u32_e32 v4, 0x1a020, v68
	v_mov_b32_e32 v5, v3
	v_lshl_add_u64 v[4:5], v[4:5], 1, s[6:7]
	global_store_short_d16_hi v[4:5], v6, off
	v_mul_f32_e32 v4, v9, v8
	v_mul_f32_e32 v2, v2, v8
	v_mul_f32_e32 v4, v71, v4
	v_mul_f32_e32 v2, v73, v2
	v_cvt_pk_bf16_f32 v2, v4, v2
	v_add_u32_e32 v4, 0x1a040, v68
	v_mov_b32_e32 v5, v3
	v_lshl_add_u64 v[4:5], v[4:5], 1, s[6:7]
	global_store_short v[4:5], v2, off
	v_add_u32_e32 v4, 0x1a060, v68
	v_mov_b32_e32 v5, v3
	v_lshl_add_u64 v[4:5], v[4:5], 1, s[6:7]
	global_store_short_d16_hi v[4:5], v2, off
	ds_read_b32 v1, v1 offset:108
	ds_read2st64_b32 v[4:5], v70 offset0:15 offset1:31
	s_waitcnt lgkmcnt(0)
	v_fma_f32 v2, v67, v1, -v4
	v_fma_f32 v6, v51, v1, -v5
	ds_read2st64_b32 v[4:5], v70 offset0:47 offset1:63
	v_mul_f32_e32 v7, v6, v6
	v_fmac_f32_e32 v7, v2, v2
	s_waitcnt lgkmcnt(0)
	v_fma_f32 v8, v35, v1, -v4
	v_fmac_f32_e32 v7, v8, v8
	v_fma_f32 v1, v19, v1, -v5
	v_fmac_f32_e32 v7, v1, v1
	s_nop 1
	v_add_f32_dpp v4, v7, v7 quad_perm:[1,0,3,2] row_mask:0xf bank_mask:0xf
	s_nop 1
	v_add_f32_dpp v4, v4, v4 quad_perm:[2,3,0,1] row_mask:0xf bank_mask:0xf
	s_nop 1
	v_add_f32_dpp v4, v4, v4 row_half_mirror row_mask:0xf bank_mask:0xf
	s_nop 1
	v_add_f32_dpp v4, v4, v4 row_mirror row_mask:0xf bank_mask:0xf
	ds_swizzle_b32 v5, v4 offset:swizzle(SWAP,16)
	s_waitcnt lgkmcnt(0)
	v_add_f32_e32 v4, v4, v5
	v_fmamk_f32 v4, v4, 0x3c000000, v254
	v_cmp_gt_f32_e32 vcc, s90, v4
	v_mul_f32_e32 v5, 0x4f800000, v4
	s_nop 0
	v_cndmask_b32_e32 v4, v4, v5, vcc
	v_sqrt_f32_e32 v5, v4
	s_nop 0
	v_add_u32_e32 v7, -1, v5
	v_fma_f32 v9, -v7, v5, v4
	v_cmp_ge_f32_e64 s[4:5], 0, v9
	v_add_u32_e32 v9, 1, v5
	s_nop 0
	v_cndmask_b32_e64 v7, v5, v7, s[4:5]
	v_fma_f32 v5, -v9, v5, v4
	v_cmp_lt_f32_e64 s[4:5], 0, v5
	s_nop 1
	v_cndmask_b32_e64 v5, v7, v9, s[4:5]
	v_mul_f32_e32 v7, 0x37800000, v5
	v_cndmask_b32_e32 v5, v5, v7, vcc
	v_cmp_class_f32_e32 vcc, v4, v209
	s_nop 1
	v_cndmask_b32_e32 v4, v5, v4, vcc
	v_div_scale_f32 v5, s[4:5], v4, v4, 1.0
	v_rcp_f32_e32 v7, v5
	s_nop 0
	v_fma_f32 v9, -v5, v7, 1.0
	v_fmac_f32_e32 v7, v9, v7
	v_div_scale_f32 v9, vcc, 1.0, v4, 1.0
	v_mul_f32_e32 v10, v9, v7
	v_fma_f32 v11, -v5, v10, v9
	v_fmac_f32_e32 v10, v11, v7
	v_fma_f32 v5, -v5, v10, v9
	v_div_fmas_f32 v5, v5, v7, v10
	v_div_fixup_f32 v7, v5, v4, 1.0
	v_mul_f32_e32 v2, v2, v7
	v_mul_f32_e32 v5, v6, v7
	v_mul_f32_e32 v2, v72, v2
	v_mul_f32_e32 v5, v74, v5
	v_add_u32_e32 v4, 0x1b000, v68
	v_cvt_pk_bf16_f32 v2, v2, v5
	v_mov_b32_e32 v5, v3
	v_lshl_add_u64 v[4:5], v[4:5], 1, s[6:7]
	global_store_short v[4:5], v2, off
	v_add_u32_e32 v4, 0x1b020, v68
	v_mov_b32_e32 v5, v3
	v_lshl_add_u64 v[4:5], v[4:5], 1, s[6:7]
	global_store_short_d16_hi v[4:5], v2, off
	v_mul_f32_e32 v1, v1, v7
	v_add_u32_e32 v4, 0x1b040, v68
	v_mov_b32_e32 v5, v3
	v_mul_f32_e32 v2, v8, v7
	v_mul_f32_e32 v1, v73, v1
	v_lshl_add_u64 v[4:5], v[4:5], 1, s[6:7]
	v_mul_f32_e32 v2, v71, v2
	v_cvt_pk_bf16_f32 v1, v2, v1
	global_store_short v[4:5], v1, off
	v_add_u32_e32 v4, 0x1b060, v68
	v_mov_b32_e32 v5, v3
	v_lshl_add_u64 v[4:5], v[4:5], 1, s[6:7]
	global_store_short_d16_hi v[4:5], v1, off

.LBB0_1657:
	s_or_b64 exec, exec, s[4:5]
	s_waitcnt lgkmcnt(0)
	v_lshlrev_b32_e32 v2, 2, v158
	global_load_dword v248, v2, s[0:1]
	global_load_dword v249, v2, s[0:1] offset:128
	global_load_dword v250, v2, s[0:1] offset:256
	global_load_dword v251, v2, s[0:1] offset:384
	v_add_u32_e32 v8, s46, v148
	s_lshl_b64 s[4:5], s[26:27], 13
	s_add_u32 s6, s86, s4
	s_addc_u32 s7, s87, s5
	s_waitcnt vmcnt(0)
	v_mul_f32_e32 v5, v164, v248
	v_mul_f32_e32 v7, v164, v249
	v_mul_f32_e32 v4, v164, v250
	v_mul_f32_e32 v6, v164, v251
	v_lshl_or_b32 v2, v159, 14, v158
	ds_read_b32 v9, v8
	ds_read2st64_b32 v[10:11], v1 offset1:16
	ds_read_b32 v21, v8 offset:4
	ds_read2st64_b32 v[22:23], v1 offset0:1 offset1:17
	s_waitcnt lgkmcnt(0)
	v_fma_f32 v12, v68, v9, -v10
	v_fma_f32 v13, v100, v9, -v11
	ds_read2st64_b32 v[10:11], v1 offset0:32 offset1:48
	v_mul_f32_e32 v14, v13, v13
	v_fmac_f32_e32 v14, v12, v12
	v_fma_f32 v24, v69, v21, -v22
	v_fma_f32 v25, v101, v21, -v23
	ds_read2st64_b32 v[22:23], v1 offset0:33 offset1:49
	v_mul_f32_e32 v26, v25, v25
	v_fmac_f32_e32 v26, v24, v24
	s_waitcnt lgkmcnt(0)
	v_fma_f32 v15, v116, v9, -v10
	v_fmac_f32_e32 v14, v15, v15
	v_fma_f32 v9, v132, v9, -v11
	v_fmac_f32_e32 v14, v9, v9
	s_nop 1
	v_add_f32_dpp v10, v14, v14 quad_perm:[1,0,3,2] row_mask:0xf bank_mask:0xf
	s_nop 1
	v_add_f32_dpp v10, v10, v10 quad_perm:[2,3,0,1] row_mask:0xf bank_mask:0xf
	s_nop 1
	v_add_f32_dpp v10, v10, v10 row_half_mirror row_mask:0xf bank_mask:0xf
	s_nop 1
	v_add_f32_dpp v10, v10, v10 row_mirror row_mask:0xf bank_mask:0xf
	ds_swizzle_b32 v11, v10 offset:swizzle(SWAP,16)
	v_fma_f32 v27, v117, v21, -v22
	v_fmac_f32_e32 v26, v27, v27
	v_fma_f32 v21, v133, v21, -v23
	v_fmac_f32_e32 v26, v21, v21
	s_nop 1
	v_add_f32_dpp v22, v26, v26 quad_perm:[1,0,3,2] row_mask:0xf bank_mask:0xf
	s_nop 1
	v_add_f32_dpp v22, v22, v22 quad_perm:[2,3,0,1] row_mask:0xf bank_mask:0xf
	s_nop 1
	v_add_f32_dpp v22, v22, v22 row_half_mirror row_mask:0xf bank_mask:0xf
	s_nop 1
	v_add_f32_dpp v22, v22, v22 row_mirror row_mask:0xf bank_mask:0xf
	ds_swizzle_b32 v23, v22 offset:swizzle(SWAP,16)
	s_waitcnt lgkmcnt(0)
	v_add_f32_e32 v10, v10, v11
	v_fmamk_f32 v10, v10, 0x3c000000, v254
	s_nop 0
	s_nop 0
	s_nop 0
	s_nop 1
	s_nop 1
	s_nop 0
	v_rsq_f32_e32 v14, v10
	s_nop 0
	v_mul_f32_e32 v10, v12, v14
	v_mul_f32_e32 v11, v13, v14
	v_mul_f32_e32 v10, v5, v10
	v_mul_f32_e32 v11, v7, v11
	v_cvt_pk_bf16_f32 v12, v10, v11
	v_lshl_add_u64 v[10:11], v[2:3], 1, s[6:7]
	global_store_short v[10:11], v12, off offset:768
	v_add_u32_e32 v10, 32, v2
	v_mov_b32_e32 v11, v3
	v_lshl_add_u64 v[10:11], v[10:11], 1, s[6:7]
	global_store_short_d16_hi v[10:11], v12, off offset:768
	v_mul_f32_e32 v10, v15, v14
	v_mul_f32_e32 v9, v9, v14
	v_mul_f32_e32 v10, v4, v10
	v_mul_f32_e32 v9, v6, v9
	v_cvt_pk_bf16_f32 v9, v10, v9
	v_add_u32_e32 v10, 64, v2
	v_mov_b32_e32 v11, v3
	v_lshl_add_u64 v[10:11], v[10:11], 1, s[6:7]
	global_store_short v[10:11], v9, off offset:768
	v_add_u32_e32 v10, 0x60, v2
	v_mov_b32_e32 v11, v3
	v_lshl_add_u64 v[10:11], v[10:11], 1, s[6:7]
	global_store_short_d16_hi v[10:11], v9, off offset:768
	v_add_f32_e32 v22, v22, v23
	v_fmamk_f32 v22, v22, 0x3c000000, v254
	s_nop 0
	s_nop 0
	s_nop 0
	s_nop 1
	s_nop 1
	s_nop 0
	v_rsq_f32_e32 v26, v22
	s_nop 0
	v_mul_f32_e32 v23, v24, v26
	v_mul_f32_e32 v24, v25, v26
	v_mul_f32_e32 v23, v5, v23
	v_mul_f32_e32 v24, v7, v24
	v_add_u32_e32 v22, 0x1000, v2
	v_cvt_pk_bf16_f32 v24, v23, v24
	v_mov_b32_e32 v23, v3
	v_lshl_add_u64 v[22:23], v[22:23], 1, s[6:7]
	global_store_short v[22:23], v24, off offset:768
	v_add_u32_e32 v22, 0x1020, v2
	v_mov_b32_e32 v23, v3
	v_lshl_add_u64 v[22:23], v[22:23], 1, s[6:7]
	global_store_short_d16_hi v[22:23], v24, off offset:768
	v_mul_f32_e32 v22, v27, v26
	v_mul_f32_e32 v21, v21, v26
	v_mul_f32_e32 v22, v4, v22
	v_mul_f32_e32 v21, v6, v21
	v_cvt_pk_bf16_f32 v21, v22, v21
	v_add_u32_e32 v22, 0x1040, v2
	v_mov_b32_e32 v23, v3
	v_lshl_add_u64 v[22:23], v[22:23], 1, s[6:7]
	global_store_short v[22:23], v21, off offset:768
	v_add_u32_e32 v22, 0x1060, v2
	v_mov_b32_e32 v23, v3
	v_lshl_add_u64 v[22:23], v[22:23], 1, s[6:7]
	global_store_short_d16_hi v[22:23], v21, off offset:768
	ds_read_b32 v9, v8 offset:8
	ds_read2st64_b32 v[10:11], v1 offset0:2 offset1:18
	ds_read_b32 v21, v8 offset:12
	ds_read2st64_b32 v[22:23], v1 offset0:3 offset1:19
	s_waitcnt lgkmcnt(0)
	v_fma_f32 v12, v70, v9, -v10
	v_fma_f32 v13, v102, v9, -v11
	ds_read2st64_b32 v[10:11], v1 offset0:34 offset1:50
	v_mul_f32_e32 v14, v13, v13
	v_fmac_f32_e32 v14, v12, v12
	v_fma_f32 v24, v71, v21, -v22
	v_fma_f32 v25, v103, v21, -v23
	ds_read2st64_b32 v[22:23], v1 offset0:35 offset1:51
	v_mul_f32_e32 v26, v25, v25
	v_fmac_f32_e32 v26, v24, v24
	s_waitcnt lgkmcnt(0)
	v_fma_f32 v15, v118, v9, -v10
	v_fmac_f32_e32 v14, v15, v15
	v_fma_f32 v9, v134, v9, -v11
	v_fmac_f32_e32 v14, v9, v9
	s_nop 1
	v_add_f32_dpp v10, v14, v14 quad_perm:[1,0,3,2] row_mask:0xf bank_mask:0xf
	s_nop 1
	v_add_f32_dpp v10, v10, v10 quad_perm:[2,3,0,1] row_mask:0xf bank_mask:0xf
	s_nop 1
	v_add_f32_dpp v10, v10, v10 row_half_mirror row_mask:0xf bank_mask:0xf
	s_nop 1
	v_add_f32_dpp v10, v10, v10 row_mirror row_mask:0xf bank_mask:0xf
	ds_swizzle_b32 v11, v10 offset:swizzle(SWAP,16)
	v_fma_f32 v27, v119, v21, -v22
	v_fmac_f32_e32 v26, v27, v27
	v_fma_f32 v21, v135, v21, -v23
	v_fmac_f32_e32 v26, v21, v21
	s_nop 1
	v_add_f32_dpp v22, v26, v26 quad_perm:[1,0,3,2] row_mask:0xf bank_mask:0xf
	s_nop 1
	v_add_f32_dpp v22, v22, v22 quad_perm:[2,3,0,1] row_mask:0xf bank_mask:0xf
	s_nop 1
	v_add_f32_dpp v22, v22, v22 row_half_mirror row_mask:0xf bank_mask:0xf
	s_nop 1
	v_add_f32_dpp v22, v22, v22 row_mirror row_mask:0xf bank_mask:0xf
	ds_swizzle_b32 v23, v22 offset:swizzle(SWAP,16)
	s_waitcnt lgkmcnt(0)
	v_add_f32_e32 v10, v10, v11
	v_fmamk_f32 v10, v10, 0x3c000000, v254
	s_nop 0
	s_nop 0
	s_nop 0
	s_nop 1
	s_nop 1
	s_nop 0
	v_rsq_f32_e32 v14, v10
	s_nop 0
	v_mul_f32_e32 v11, v12, v14
	v_mul_f32_e32 v12, v13, v14
	v_mul_f32_e32 v11, v5, v11
	v_mul_f32_e32 v12, v7, v12
	v_add_u32_e32 v10, 0x2000, v2
	v_cvt_pk_bf16_f32 v12, v11, v12
	v_mov_b32_e32 v11, v3
	v_lshl_add_u64 v[10:11], v[10:11], 1, s[6:7]
	global_store_short v[10:11], v12, off offset:768
	v_add_u32_e32 v10, 0x2020, v2
	v_mov_b32_e32 v11, v3
	v_lshl_add_u64 v[10:11], v[10:11], 1, s[6:7]
	global_store_short_d16_hi v[10:11], v12, off offset:768
	v_mul_f32_e32 v10, v15, v14
	v_mul_f32_e32 v9, v9, v14
	v_mul_f32_e32 v10, v4, v10
	v_mul_f32_e32 v9, v6, v9
	v_cvt_pk_bf16_f32 v9, v10, v9
	v_add_u32_e32 v10, 0x2040, v2
	v_mov_b32_e32 v11, v3
	v_lshl_add_u64 v[10:11], v[10:11], 1, s[6:7]
	global_store_short v[10:11], v9, off offset:768
	v_add_u32_e32 v10, 0x2060, v2
	v_mov_b32_e32 v11, v3
	v_lshl_add_u64 v[10:11], v[10:11], 1, s[6:7]
	global_store_short_d16_hi v[10:11], v9, off offset:768
	v_add_f32_e32 v22, v22, v23
	v_fmamk_f32 v22, v22, 0x3c000000, v254
	s_nop 0
	s_nop 0
	s_nop 0
	s_nop 1
	s_nop 1
	s_nop 0
	v_rsq_f32_e32 v26, v22
	s_nop 0
	v_mul_f32_e32 v23, v24, v26
	v_mul_f32_e32 v24, v25, v26
	v_mul_f32_e32 v23, v5, v23
	v_mul_f32_e32 v24, v7, v24
	v_add_u32_e32 v22, 0x3000, v2
	v_cvt_pk_bf16_f32 v24, v23, v24
	v_mov_b32_e32 v23, v3
	v_lshl_add_u64 v[22:23], v[22:23], 1, s[6:7]
	global_store_short v[22:23], v24, off offset:768
	v_add_u32_e32 v22, 0x3020, v2
	v_mov_b32_e32 v23, v3
	v_lshl_add_u64 v[22:23], v[22:23], 1, s[6:7]
	global_store_short_d16_hi v[22:23], v24, off offset:768
	v_mul_f32_e32 v22, v27, v26
	v_mul_f32_e32 v21, v21, v26
	v_mul_f32_e32 v22, v4, v22
	v_mul_f32_e32 v21, v6, v21
	v_cvt_pk_bf16_f32 v21, v22, v21
	v_add_u32_e32 v22, 0x3040, v2
	v_mov_b32_e32 v23, v3
	v_lshl_add_u64 v[22:23], v[22:23], 1, s[6:7]
	global_store_short v[22:23], v21, off offset:768
	v_add_u32_e32 v22, 0x3060, v2
	v_mov_b32_e32 v23, v3
	v_lshl_add_u64 v[22:23], v[22:23], 1, s[6:7]
	global_store_short_d16_hi v[22:23], v21, off offset:768
	ds_read_b32 v9, v8 offset:32
	ds_read2st64_b32 v[10:11], v1 offset0:4 offset1:20
	ds_read_b32 v21, v8 offset:36
	ds_read2st64_b32 v[22:23], v1 offset0:5 offset1:21
	s_waitcnt lgkmcnt(0)
	v_fma_f32 v12, v72, v9, -v10
	v_fma_f32 v13, v104, v9, -v11
	ds_read2st64_b32 v[10:11], v1 offset0:36 offset1:52
	v_mul_f32_e32 v14, v13, v13
	v_fmac_f32_e32 v14, v12, v12
	v_fma_f32 v24, v73, v21, -v22
	v_fma_f32 v25, v105, v21, -v23
	ds_read2st64_b32 v[22:23], v1 offset0:37 offset1:53
	v_mul_f32_e32 v26, v25, v25
	v_fmac_f32_e32 v26, v24, v24
	s_waitcnt lgkmcnt(0)
	v_fma_f32 v15, v120, v9, -v10
	v_fmac_f32_e32 v14, v15, v15
	v_fma_f32 v9, v136, v9, -v11
	v_fmac_f32_e32 v14, v9, v9
	s_nop 1
	v_add_f32_dpp v10, v14, v14 quad_perm:[1,0,3,2] row_mask:0xf bank_mask:0xf
	s_nop 1
	v_add_f32_dpp v10, v10, v10 quad_perm:[2,3,0,1] row_mask:0xf bank_mask:0xf
	s_nop 1
	v_add_f32_dpp v10, v10, v10 row_half_mirror row_mask:0xf bank_mask:0xf
	s_nop 1
	v_add_f32_dpp v10, v10, v10 row_mirror row_mask:0xf bank_mask:0xf
	ds_swizzle_b32 v11, v10 offset:swizzle(SWAP,16)
	v_fma_f32 v27, v121, v21, -v22
	v_fmac_f32_e32 v26, v27, v27
	v_fma_f32 v21, v137, v21, -v23
	v_fmac_f32_e32 v26, v21, v21
	s_nop 1
	v_add_f32_dpp v22, v26, v26 quad_perm:[1,0,3,2] row_mask:0xf bank_mask:0xf
	s_nop 1
	v_add_f32_dpp v22, v22, v22 quad_perm:[2,3,0,1] row_mask:0xf bank_mask:0xf
	s_nop 1
	v_add_f32_dpp v22, v22, v22 row_half_mirror row_mask:0xf bank_mask:0xf
	s_nop 1
	v_add_f32_dpp v22, v22, v22 row_mirror row_mask:0xf bank_mask:0xf
	ds_swizzle_b32 v23, v22 offset:swizzle(SWAP,16)
	s_waitcnt lgkmcnt(0)
	v_add_f32_e32 v10, v10, v11
	v_fmamk_f32 v10, v10, 0x3c000000, v254
	s_nop 0
	s_nop 0
	s_nop 0
	s_nop 1
	s_nop 1
	s_nop 0
	v_rsq_f32_e32 v14, v10
	s_nop 0
	v_mul_f32_e32 v11, v12, v14
	v_mul_f32_e32 v12, v13, v14
	v_mul_f32_e32 v11, v5, v11
	v_mul_f32_e32 v12, v7, v12
	v_add_u32_e32 v10, 0x8000, v2
	v_cvt_pk_bf16_f32 v12, v11, v12
	v_mov_b32_e32 v11, v3
	v_lshl_add_u64 v[10:11], v[10:11], 1, s[6:7]
	global_store_short v[10:11], v12, off offset:768
	v_add_u32_e32 v10, 0x8020, v2
	v_mov_b32_e32 v11, v3
	v_lshl_add_u64 v[10:11], v[10:11], 1, s[6:7]
	global_store_short_d16_hi v[10:11], v12, off offset:768
	v_mul_f32_e32 v10, v15, v14
	v_mul_f32_e32 v9, v9, v14
	v_mul_f32_e32 v10, v4, v10
	v_mul_f32_e32 v9, v6, v9
	v_cvt_pk_bf16_f32 v9, v10, v9
	v_add_u32_e32 v10, 0x8040, v2
	v_mov_b32_e32 v11, v3
	v_lshl_add_u64 v[10:11], v[10:11], 1, s[6:7]
	global_store_short v[10:11], v9, off offset:768
	v_add_u32_e32 v10, 0x8060, v2
	v_mov_b32_e32 v11, v3
	v_lshl_add_u64 v[10:11], v[10:11], 1, s[6:7]
	global_store_short_d16_hi v[10:11], v9, off offset:768
	v_add_f32_e32 v22, v22, v23
	v_fmamk_f32 v22, v22, 0x3c000000, v254
	s_nop 0
	s_nop 0
	s_nop 0
	s_nop 1
	s_nop 1
	s_nop 0
	v_rsq_f32_e32 v26, v22
	s_nop 0
	v_mul_f32_e32 v23, v24, v26
	v_mul_f32_e32 v24, v25, v26
	v_mul_f32_e32 v23, v5, v23
	v_mul_f32_e32 v24, v7, v24
	v_add_u32_e32 v22, 0x9000, v2
	v_cvt_pk_bf16_f32 v24, v23, v24
	v_mov_b32_e32 v23, v3
	v_lshl_add_u64 v[22:23], v[22:23], 1, s[6:7]
	global_store_short v[22:23], v24, off offset:768
	v_add_u32_e32 v22, 0x9020, v2
	v_mov_b32_e32 v23, v3
	v_lshl_add_u64 v[22:23], v[22:23], 1, s[6:7]
	global_store_short_d16_hi v[22:23], v24, off offset:768
	v_mul_f32_e32 v22, v27, v26
	v_mul_f32_e32 v21, v21, v26
	v_mul_f32_e32 v22, v4, v22
	v_mul_f32_e32 v21, v6, v21
	v_cvt_pk_bf16_f32 v21, v22, v21
	v_add_u32_e32 v22, 0x9040, v2
	v_mov_b32_e32 v23, v3
	v_lshl_add_u64 v[22:23], v[22:23], 1, s[6:7]
	global_store_short v[22:23], v21, off offset:768
	v_add_u32_e32 v22, 0x9060, v2
	v_mov_b32_e32 v23, v3
	v_lshl_add_u64 v[22:23], v[22:23], 1, s[6:7]
	global_store_short_d16_hi v[22:23], v21, off offset:768
	ds_read_b32 v9, v8 offset:40
	ds_read2st64_b32 v[10:11], v1 offset0:6 offset1:22
	ds_read_b32 v21, v8 offset:44
	ds_read2st64_b32 v[22:23], v1 offset0:7 offset1:23
	s_waitcnt lgkmcnt(0)
	v_fma_f32 v12, v74, v9, -v10
	v_fma_f32 v13, v106, v9, -v11
	ds_read2st64_b32 v[10:11], v1 offset0:38 offset1:54
	v_mul_f32_e32 v14, v13, v13
	v_fmac_f32_e32 v14, v12, v12
	v_fma_f32 v24, v75, v21, -v22
	v_fma_f32 v25, v107, v21, -v23
	ds_read2st64_b32 v[22:23], v1 offset0:39 offset1:55
	v_mul_f32_e32 v26, v25, v25
	v_fmac_f32_e32 v26, v24, v24
	s_waitcnt lgkmcnt(0)
	v_fma_f32 v15, v122, v9, -v10
	v_fmac_f32_e32 v14, v15, v15
	v_fma_f32 v9, v138, v9, -v11
	v_fmac_f32_e32 v14, v9, v9
	s_nop 1
	v_add_f32_dpp v10, v14, v14 quad_perm:[1,0,3,2] row_mask:0xf bank_mask:0xf
	s_nop 1
	v_add_f32_dpp v10, v10, v10 quad_perm:[2,3,0,1] row_mask:0xf bank_mask:0xf
	s_nop 1
	v_add_f32_dpp v10, v10, v10 row_half_mirror row_mask:0xf bank_mask:0xf
	s_nop 1
	v_add_f32_dpp v10, v10, v10 row_mirror row_mask:0xf bank_mask:0xf
	ds_swizzle_b32 v11, v10 offset:swizzle(SWAP,16)
	v_fma_f32 v27, v123, v21, -v22
	v_fmac_f32_e32 v26, v27, v27
	v_fma_f32 v21, v139, v21, -v23
	v_fmac_f32_e32 v26, v21, v21
	s_nop 1
	v_add_f32_dpp v22, v26, v26 quad_perm:[1,0,3,2] row_mask:0xf bank_mask:0xf
	s_nop 1
	v_add_f32_dpp v22, v22, v22 quad_perm:[2,3,0,1] row_mask:0xf bank_mask:0xf
	s_nop 1
	v_add_f32_dpp v22, v22, v22 row_half_mirror row_mask:0xf bank_mask:0xf
	s_nop 1
	v_add_f32_dpp v22, v22, v22 row_mirror row_mask:0xf bank_mask:0xf
	ds_swizzle_b32 v23, v22 offset:swizzle(SWAP,16)
	s_waitcnt lgkmcnt(0)
	v_add_f32_e32 v10, v10, v11
	v_fmamk_f32 v10, v10, 0x3c000000, v254
	s_nop 0
	s_nop 0
	s_nop 0
	s_nop 1
	s_nop 1
	s_nop 0
	v_rsq_f32_e32 v14, v10
	s_nop 0
	v_mul_f32_e32 v11, v12, v14
	v_mul_f32_e32 v12, v13, v14
	v_mul_f32_e32 v11, v5, v11
	v_mul_f32_e32 v12, v7, v12
	v_add_u32_e32 v10, 0xa000, v2
	v_cvt_pk_bf16_f32 v12, v11, v12
	v_mov_b32_e32 v11, v3
	v_lshl_add_u64 v[10:11], v[10:11], 1, s[6:7]
	global_store_short v[10:11], v12, off offset:768
	v_add_u32_e32 v10, 0xa020, v2
	v_mov_b32_e32 v11, v3
	v_lshl_add_u64 v[10:11], v[10:11], 1, s[6:7]
	global_store_short_d16_hi v[10:11], v12, off offset:768
	v_mul_f32_e32 v10, v15, v14
	v_mul_f32_e32 v9, v9, v14
	v_mul_f32_e32 v10, v4, v10
	v_mul_f32_e32 v9, v6, v9
	v_cvt_pk_bf16_f32 v9, v10, v9
	v_add_u32_e32 v10, 0xa040, v2
	v_mov_b32_e32 v11, v3
	v_lshl_add_u64 v[10:11], v[10:11], 1, s[6:7]
	global_store_short v[10:11], v9, off offset:768
	v_add_u32_e32 v10, 0xa060, v2
	v_mov_b32_e32 v11, v3
	v_lshl_add_u64 v[10:11], v[10:11], 1, s[6:7]
	global_store_short_d16_hi v[10:11], v9, off offset:768
	v_add_f32_e32 v22, v22, v23
	v_fmamk_f32 v22, v22, 0x3c000000, v254
	s_nop 0
	s_nop 0
	s_nop 0
	s_nop 1
	s_nop 1
	s_nop 0
	v_rsq_f32_e32 v26, v22
	s_nop 0
	v_mul_f32_e32 v23, v24, v26
	v_mul_f32_e32 v24, v25, v26
	v_mul_f32_e32 v23, v5, v23
	v_mul_f32_e32 v24, v7, v24
	v_add_u32_e32 v22, 0xb000, v2
	v_cvt_pk_bf16_f32 v24, v23, v24
	v_mov_b32_e32 v23, v3
	v_lshl_add_u64 v[22:23], v[22:23], 1, s[6:7]
	global_store_short v[22:23], v24, off offset:768
	v_add_u32_e32 v22, 0xb020, v2
	v_mov_b32_e32 v23, v3
	v_lshl_add_u64 v[22:23], v[22:23], 1, s[6:7]
	global_store_short_d16_hi v[22:23], v24, off offset:768
	v_mul_f32_e32 v22, v27, v26
	v_mul_f32_e32 v21, v21, v26
	v_mul_f32_e32 v22, v4, v22
	v_mul_f32_e32 v21, v6, v21
	v_cvt_pk_bf16_f32 v21, v22, v21
	v_add_u32_e32 v22, 0xb040, v2
	v_mov_b32_e32 v23, v3
	v_lshl_add_u64 v[22:23], v[22:23], 1, s[6:7]
	global_store_short v[22:23], v21, off offset:768
	v_add_u32_e32 v22, 0xb060, v2
	v_mov_b32_e32 v23, v3
	v_lshl_add_u64 v[22:23], v[22:23], 1, s[6:7]
	global_store_short_d16_hi v[22:23], v21, off offset:768
	ds_read_b32 v9, v8 offset:64
	ds_read2st64_b32 v[10:11], v1 offset0:8 offset1:24
	ds_read_b32 v21, v8 offset:68
	ds_read2st64_b32 v[22:23], v1 offset0:9 offset1:25
	s_waitcnt lgkmcnt(0)
	v_fma_f32 v12, v76, v9, -v10
	v_fma_f32 v13, v108, v9, -v11
	ds_read2st64_b32 v[10:11], v1 offset0:40 offset1:56
	v_mul_f32_e32 v14, v13, v13
	v_fmac_f32_e32 v14, v12, v12
	v_fma_f32 v24, v77, v21, -v22
	v_fma_f32 v25, v109, v21, -v23
	ds_read2st64_b32 v[22:23], v1 offset0:41 offset1:57
	v_mul_f32_e32 v26, v25, v25
	v_fmac_f32_e32 v26, v24, v24
	s_waitcnt lgkmcnt(0)
	v_fma_f32 v15, v124, v9, -v10
	v_fmac_f32_e32 v14, v15, v15
	v_fma_f32 v9, v140, v9, -v11
	v_fmac_f32_e32 v14, v9, v9
	s_nop 1
	v_add_f32_dpp v10, v14, v14 quad_perm:[1,0,3,2] row_mask:0xf bank_mask:0xf
	s_nop 1
	v_add_f32_dpp v10, v10, v10 quad_perm:[2,3,0,1] row_mask:0xf bank_mask:0xf
	s_nop 1
	v_add_f32_dpp v10, v10, v10 row_half_mirror row_mask:0xf bank_mask:0xf
	s_nop 1
	v_add_f32_dpp v10, v10, v10 row_mirror row_mask:0xf bank_mask:0xf
	ds_swizzle_b32 v11, v10 offset:swizzle(SWAP,16)
	v_fma_f32 v27, v125, v21, -v22
	v_fmac_f32_e32 v26, v27, v27
	v_fma_f32 v21, v141, v21, -v23
	v_fmac_f32_e32 v26, v21, v21
	s_nop 1
	v_add_f32_dpp v22, v26, v26 quad_perm:[1,0,3,2] row_mask:0xf bank_mask:0xf
	s_nop 1
	v_add_f32_dpp v22, v22, v22 quad_perm:[2,3,0,1] row_mask:0xf bank_mask:0xf
	s_nop 1
	v_add_f32_dpp v22, v22, v22 row_half_mirror row_mask:0xf bank_mask:0xf
	s_nop 1
	v_add_f32_dpp v22, v22, v22 row_mirror row_mask:0xf bank_mask:0xf
	ds_swizzle_b32 v23, v22 offset:swizzle(SWAP,16)
	s_waitcnt lgkmcnt(0)
	v_add_f32_e32 v10, v10, v11
	v_fmamk_f32 v10, v10, 0x3c000000, v254
	s_nop 0
	s_nop 0
	s_nop 0
	s_nop 1
	s_nop 1
	s_nop 0
	v_rsq_f32_e32 v14, v10
	s_nop 0
	v_mul_f32_e32 v11, v12, v14
	v_mul_f32_e32 v12, v13, v14
	v_mul_f32_e32 v11, v5, v11
	v_mul_f32_e32 v12, v7, v12
	v_add_u32_e32 v10, 0x10000, v2
	v_cvt_pk_bf16_f32 v12, v11, v12
	v_mov_b32_e32 v11, v3
	v_lshl_add_u64 v[10:11], v[10:11], 1, s[6:7]
	global_store_short v[10:11], v12, off offset:768
	v_add_u32_e32 v10, 0x10020, v2
	v_mov_b32_e32 v11, v3
	v_lshl_add_u64 v[10:11], v[10:11], 1, s[6:7]
	global_store_short_d16_hi v[10:11], v12, off offset:768
	v_mul_f32_e32 v10, v15, v14
	v_mul_f32_e32 v9, v9, v14
	v_mul_f32_e32 v10, v4, v10
	v_mul_f32_e32 v9, v6, v9
	v_cvt_pk_bf16_f32 v9, v10, v9
	v_add_u32_e32 v10, 0x10040, v2
	v_mov_b32_e32 v11, v3
	v_lshl_add_u64 v[10:11], v[10:11], 1, s[6:7]
	global_store_short v[10:11], v9, off offset:768
	v_add_u32_e32 v10, 0x10060, v2
	v_mov_b32_e32 v11, v3
	v_lshl_add_u64 v[10:11], v[10:11], 1, s[6:7]
	global_store_short_d16_hi v[10:11], v9, off offset:768
	v_add_f32_e32 v22, v22, v23
	v_fmamk_f32 v22, v22, 0x3c000000, v254
	s_nop 0
	s_nop 0
	s_nop 0
	s_nop 1
	s_nop 1
	s_nop 0
	v_rsq_f32_e32 v26, v22
	s_nop 0
	v_mul_f32_e32 v23, v24, v26
	v_mul_f32_e32 v24, v25, v26
	v_mul_f32_e32 v23, v5, v23
	v_mul_f32_e32 v24, v7, v24
	v_add_u32_e32 v22, 0x11000, v2
	v_cvt_pk_bf16_f32 v24, v23, v24
	v_mov_b32_e32 v23, v3
	v_lshl_add_u64 v[22:23], v[22:23], 1, s[6:7]
	global_store_short v[22:23], v24, off offset:768
	v_add_u32_e32 v22, 0x11020, v2
	v_mov_b32_e32 v23, v3
	v_lshl_add_u64 v[22:23], v[22:23], 1, s[6:7]
	global_store_short_d16_hi v[22:23], v24, off offset:768
	v_mul_f32_e32 v22, v27, v26
	v_mul_f32_e32 v21, v21, v26
	v_mul_f32_e32 v22, v4, v22
	v_mul_f32_e32 v21, v6, v21
	v_cvt_pk_bf16_f32 v21, v22, v21
	v_add_u32_e32 v22, 0x11040, v2
	v_mov_b32_e32 v23, v3
	v_lshl_add_u64 v[22:23], v[22:23], 1, s[6:7]
	global_store_short v[22:23], v21, off offset:768
	v_add_u32_e32 v22, 0x11060, v2
	v_mov_b32_e32 v23, v3
	v_lshl_add_u64 v[22:23], v[22:23], 1, s[6:7]
	global_store_short_d16_hi v[22:23], v21, off offset:768
	ds_read_b32 v9, v8 offset:72
	ds_read2st64_b32 v[10:11], v1 offset0:10 offset1:26
	ds_read_b32 v21, v8 offset:76
	ds_read2st64_b32 v[22:23], v1 offset0:11 offset1:27
	s_waitcnt lgkmcnt(0)
	v_fma_f32 v12, v78, v9, -v10
	v_fma_f32 v13, v110, v9, -v11
	ds_read2st64_b32 v[10:11], v1 offset0:42 offset1:58
	v_mul_f32_e32 v14, v13, v13
	v_fmac_f32_e32 v14, v12, v12
	v_fma_f32 v24, v79, v21, -v22
	v_fma_f32 v25, v111, v21, -v23
	ds_read2st64_b32 v[22:23], v1 offset0:43 offset1:59
	v_mul_f32_e32 v26, v25, v25
	v_fmac_f32_e32 v26, v24, v24
	s_waitcnt lgkmcnt(0)
	v_fma_f32 v15, v126, v9, -v10
	v_fmac_f32_e32 v14, v15, v15
	v_fma_f32 v9, v142, v9, -v11
	v_fmac_f32_e32 v14, v9, v9
	s_nop 1
	v_add_f32_dpp v10, v14, v14 quad_perm:[1,0,3,2] row_mask:0xf bank_mask:0xf
	s_nop 1
	v_add_f32_dpp v10, v10, v10 quad_perm:[2,3,0,1] row_mask:0xf bank_mask:0xf
	s_nop 1
	v_add_f32_dpp v10, v10, v10 row_half_mirror row_mask:0xf bank_mask:0xf
	s_nop 1
	v_add_f32_dpp v10, v10, v10 row_mirror row_mask:0xf bank_mask:0xf
	ds_swizzle_b32 v11, v10 offset:swizzle(SWAP,16)
	v_fma_f32 v27, v127, v21, -v22
	v_fmac_f32_e32 v26, v27, v27
	v_fma_f32 v21, v143, v21, -v23
	v_fmac_f32_e32 v26, v21, v21
	s_nop 1
	v_add_f32_dpp v22, v26, v26 quad_perm:[1,0,3,2] row_mask:0xf bank_mask:0xf
	s_nop 1
	v_add_f32_dpp v22, v22, v22 quad_perm:[2,3,0,1] row_mask:0xf bank_mask:0xf
	s_nop 1
	v_add_f32_dpp v22, v22, v22 row_half_mirror row_mask:0xf bank_mask:0xf
	s_nop 1
	v_add_f32_dpp v22, v22, v22 row_mirror row_mask:0xf bank_mask:0xf
	ds_swizzle_b32 v23, v22 offset:swizzle(SWAP,16)
	s_waitcnt lgkmcnt(0)
	v_add_f32_e32 v10, v10, v11
	v_fmamk_f32 v10, v10, 0x3c000000, v254
	s_nop 0
	s_nop 0
	s_nop 0
	s_nop 1
	s_nop 1
	s_nop 0
	v_rsq_f32_e32 v14, v10
	s_nop 0
	v_mul_f32_e32 v11, v12, v14
	v_mul_f32_e32 v12, v13, v14
	v_mul_f32_e32 v11, v5, v11
	v_mul_f32_e32 v12, v7, v12
	v_add_u32_e32 v10, 0x12000, v2
	v_cvt_pk_bf16_f32 v12, v11, v12
	v_mov_b32_e32 v11, v3
	v_lshl_add_u64 v[10:11], v[10:11], 1, s[6:7]
	global_store_short v[10:11], v12, off offset:768
	v_add_u32_e32 v10, 0x12020, v2
	v_mov_b32_e32 v11, v3
	v_lshl_add_u64 v[10:11], v[10:11], 1, s[6:7]
	global_store_short_d16_hi v[10:11], v12, off offset:768
	v_mul_f32_e32 v10, v15, v14
	v_mul_f32_e32 v9, v9, v14
	v_mul_f32_e32 v10, v4, v10
	v_mul_f32_e32 v9, v6, v9
	v_cvt_pk_bf16_f32 v9, v10, v9
	v_add_u32_e32 v10, 0x12040, v2
	v_mov_b32_e32 v11, v3
	v_lshl_add_u64 v[10:11], v[10:11], 1, s[6:7]
	global_store_short v[10:11], v9, off offset:768
	v_add_u32_e32 v10, 0x12060, v2
	v_mov_b32_e32 v11, v3
	v_lshl_add_u64 v[10:11], v[10:11], 1, s[6:7]
	global_store_short_d16_hi v[10:11], v9, off offset:768
	v_add_f32_e32 v22, v22, v23
	v_fmamk_f32 v22, v22, 0x3c000000, v254
	s_nop 0
	s_nop 0
	s_nop 0
	s_nop 1
	s_nop 1
	s_nop 0
	v_rsq_f32_e32 v26, v22
	s_nop 0
	v_mul_f32_e32 v23, v24, v26
	v_mul_f32_e32 v24, v25, v26
	v_mul_f32_e32 v23, v5, v23
	v_mul_f32_e32 v24, v7, v24
	v_add_u32_e32 v22, 0x13000, v2
	v_cvt_pk_bf16_f32 v24, v23, v24
	v_mov_b32_e32 v23, v3
	v_lshl_add_u64 v[22:23], v[22:23], 1, s[6:7]
	global_store_short v[22:23], v24, off offset:768
	v_add_u32_e32 v22, 0x13020, v2
	v_mov_b32_e32 v23, v3
	v_lshl_add_u64 v[22:23], v[22:23], 1, s[6:7]
	global_store_short_d16_hi v[22:23], v24, off offset:768
	v_mul_f32_e32 v22, v27, v26
	v_mul_f32_e32 v21, v21, v26
	v_mul_f32_e32 v22, v4, v22
	v_mul_f32_e32 v21, v6, v21
	v_cvt_pk_bf16_f32 v21, v22, v21
	v_add_u32_e32 v22, 0x13040, v2
	v_mov_b32_e32 v23, v3
	v_lshl_add_u64 v[22:23], v[22:23], 1, s[6:7]
	global_store_short v[22:23], v21, off offset:768
	v_add_u32_e32 v22, 0x13060, v2
	v_mov_b32_e32 v23, v3
	v_lshl_add_u64 v[22:23], v[22:23], 1, s[6:7]
	global_store_short_d16_hi v[22:23], v21, off offset:768
	ds_read_b32 v9, v8 offset:96
	ds_read2st64_b32 v[10:11], v1 offset0:12 offset1:28
	ds_read_b32 v21, v8 offset:100
	ds_read2st64_b32 v[22:23], v1 offset0:13 offset1:29
	s_waitcnt lgkmcnt(0)
	v_fma_f32 v12, v80, v9, -v10
	v_fma_f32 v13, v112, v9, -v11
	ds_read2st64_b32 v[10:11], v1 offset0:44 offset1:60
	v_mul_f32_e32 v14, v13, v13
	v_fmac_f32_e32 v14, v12, v12
	v_fma_f32 v24, v81, v21, -v22
	v_fma_f32 v25, v113, v21, -v23
	ds_read2st64_b32 v[22:23], v1 offset0:45 offset1:61
	v_mul_f32_e32 v26, v25, v25
	v_fmac_f32_e32 v26, v24, v24
	s_waitcnt lgkmcnt(0)
	v_fma_f32 v15, v128, v9, -v10
	v_fmac_f32_e32 v14, v15, v15
	v_fma_f32 v9, v144, v9, -v11
	v_fmac_f32_e32 v14, v9, v9
	s_nop 1
	v_add_f32_dpp v10, v14, v14 quad_perm:[1,0,3,2] row_mask:0xf bank_mask:0xf
	s_nop 1
	v_add_f32_dpp v10, v10, v10 quad_perm:[2,3,0,1] row_mask:0xf bank_mask:0xf
	s_nop 1
	v_add_f32_dpp v10, v10, v10 row_half_mirror row_mask:0xf bank_mask:0xf
	s_nop 1
	v_add_f32_dpp v10, v10, v10 row_mirror row_mask:0xf bank_mask:0xf
	ds_swizzle_b32 v11, v10 offset:swizzle(SWAP,16)
	v_fma_f32 v27, v129, v21, -v22
	v_fmac_f32_e32 v26, v27, v27
	v_fma_f32 v21, v145, v21, -v23
	v_fmac_f32_e32 v26, v21, v21
	s_nop 1
	v_add_f32_dpp v22, v26, v26 quad_perm:[1,0,3,2] row_mask:0xf bank_mask:0xf
	s_nop 1
	v_add_f32_dpp v22, v22, v22 quad_perm:[2,3,0,1] row_mask:0xf bank_mask:0xf
	s_nop 1
	v_add_f32_dpp v22, v22, v22 row_half_mirror row_mask:0xf bank_mask:0xf
	s_nop 1
	v_add_f32_dpp v22, v22, v22 row_mirror row_mask:0xf bank_mask:0xf
	ds_swizzle_b32 v23, v22 offset:swizzle(SWAP,16)
	s_waitcnt lgkmcnt(0)
	v_add_f32_e32 v10, v10, v11
	v_fmamk_f32 v10, v10, 0x3c000000, v254
	s_nop 0
	s_nop 0
	s_nop 0
	s_nop 1
	s_nop 1
	s_nop 0
	v_rsq_f32_e32 v14, v10
	s_nop 0
	v_mul_f32_e32 v11, v12, v14
	v_mul_f32_e32 v12, v13, v14
	v_mul_f32_e32 v11, v5, v11
	v_mul_f32_e32 v12, v7, v12
	v_add_u32_e32 v10, 0x18000, v2
	v_cvt_pk_bf16_f32 v12, v11, v12
	v_mov_b32_e32 v11, v3
	v_lshl_add_u64 v[10:11], v[10:11], 1, s[6:7]
	global_store_short v[10:11], v12, off offset:768
	v_add_u32_e32 v10, 0x18020, v2
	v_mov_b32_e32 v11, v3
	v_lshl_add_u64 v[10:11], v[10:11], 1, s[6:7]
	global_store_short_d16_hi v[10:11], v12, off offset:768
	v_mul_f32_e32 v10, v15, v14
	v_mul_f32_e32 v9, v9, v14
	v_mul_f32_e32 v10, v4, v10
	v_mul_f32_e32 v9, v6, v9
	v_cvt_pk_bf16_f32 v9, v10, v9
	v_add_u32_e32 v10, 0x18040, v2
	v_mov_b32_e32 v11, v3
	v_lshl_add_u64 v[10:11], v[10:11], 1, s[6:7]
	global_store_short v[10:11], v9, off offset:768
	v_add_u32_e32 v10, 0x18060, v2
	v_mov_b32_e32 v11, v3
	v_lshl_add_u64 v[10:11], v[10:11], 1, s[6:7]
	global_store_short_d16_hi v[10:11], v9, off offset:768
	v_add_f32_e32 v22, v22, v23
	v_fmamk_f32 v22, v22, 0x3c000000, v254
	s_nop 0
	s_nop 0
	s_nop 0
	s_nop 1
	s_nop 1
	s_nop 0
	v_rsq_f32_e32 v26, v22
	s_nop 0
	v_mul_f32_e32 v23, v24, v26
	v_mul_f32_e32 v24, v25, v26
	v_mul_f32_e32 v23, v5, v23
	v_mul_f32_e32 v24, v7, v24
	v_add_u32_e32 v22, 0x19000, v2
	v_cvt_pk_bf16_f32 v24, v23, v24
	v_mov_b32_e32 v23, v3
	v_lshl_add_u64 v[22:23], v[22:23], 1, s[6:7]
	global_store_short v[22:23], v24, off offset:768
	v_add_u32_e32 v22, 0x19020, v2
	v_mov_b32_e32 v23, v3
	v_lshl_add_u64 v[22:23], v[22:23], 1, s[6:7]
	global_store_short_d16_hi v[22:23], v24, off offset:768
	v_mul_f32_e32 v22, v27, v26
	v_mul_f32_e32 v21, v21, v26
	v_mul_f32_e32 v22, v4, v22
	v_mul_f32_e32 v21, v6, v21
	v_cvt_pk_bf16_f32 v21, v22, v21
	v_add_u32_e32 v22, 0x19040, v2
	v_mov_b32_e32 v23, v3
	v_lshl_add_u64 v[22:23], v[22:23], 1, s[6:7]
	global_store_short v[22:23], v21, off offset:768
	v_add_u32_e32 v22, 0x19060, v2
	v_mov_b32_e32 v23, v3
	v_lshl_add_u64 v[22:23], v[22:23], 1, s[6:7]
	global_store_short_d16_hi v[22:23], v21, off offset:768
	ds_read_b32 v9, v8 offset:104
	ds_read2st64_b32 v[10:11], v1 offset0:14 offset1:30
	s_waitcnt lgkmcnt(0)
	v_fma_f32 v12, v82, v9, -v10
	v_fma_f32 v13, v114, v9, -v11
	ds_read2st64_b32 v[10:11], v1 offset0:46 offset1:62
	v_mul_f32_e32 v14, v13, v13
	v_fmac_f32_e32 v14, v12, v12
	s_waitcnt lgkmcnt(0)
	v_fma_f32 v15, v130, v9, -v10
	v_fmac_f32_e32 v14, v15, v15
	v_fma_f32 v9, v146, v9, -v11
	v_fmac_f32_e32 v14, v9, v9
	s_nop 1
	v_add_f32_dpp v10, v14, v14 quad_perm:[1,0,3,2] row_mask:0xf bank_mask:0xf
	s_nop 1
	v_add_f32_dpp v10, v10, v10 quad_perm:[2,3,0,1] row_mask:0xf bank_mask:0xf
	s_nop 1
	v_add_f32_dpp v10, v10, v10 row_half_mirror row_mask:0xf bank_mask:0xf
	s_nop 1
	v_add_f32_dpp v10, v10, v10 row_mirror row_mask:0xf bank_mask:0xf
	ds_swizzle_b32 v11, v10 offset:swizzle(SWAP,16)
	s_waitcnt lgkmcnt(0)
	v_add_f32_e32 v10, v10, v11
	v_fmamk_f32 v10, v10, 0x3c000000, v254
	v_cmp_gt_f32_e32 vcc, s90, v10
	v_mul_f32_e32 v11, 0x4f800000, v10
	s_nop 0
	v_cndmask_b32_e32 v10, v10, v11, vcc
	v_sqrt_f32_e32 v11, v10
	s_nop 0
	v_add_u32_e32 v14, -1, v11
	v_fma_f32 v16, -v14, v11, v10
	v_cmp_ge_f32_e64 s[4:5], 0, v16
	v_add_u32_e32 v16, 1, v11
	s_nop 0
	v_cndmask_b32_e64 v14, v11, v14, s[4:5]
	v_fma_f32 v11, -v16, v11, v10
	v_cmp_lt_f32_e64 s[4:5], 0, v11
	s_nop 1
	v_cndmask_b32_e64 v11, v14, v16, s[4:5]
	v_mul_f32_e32 v14, 0x37800000, v11
	v_cndmask_b32_e32 v11, v11, v14, vcc
	v_cmp_class_f32_e32 vcc, v10, v209
	s_nop 1
	v_cndmask_b32_e32 v10, v11, v10, vcc
	v_div_scale_f32 v11, s[4:5], v10, v10, 1.0
	v_rcp_f32_e32 v14, v11
	s_nop 0
	v_fma_f32 v16, -v11, v14, 1.0
	v_fmac_f32_e32 v14, v16, v14
	v_div_scale_f32 v16, vcc, 1.0, v10, 1.0
	v_mul_f32_e32 v17, v16, v14
	v_fma_f32 v18, -v11, v17, v16
	v_fmac_f32_e32 v17, v18, v14
	v_fma_f32 v11, -v11, v17, v16
	v_div_fmas_f32 v11, v11, v14, v17
	v_div_fixup_f32 v14, v11, v10, 1.0
	v_mul_f32_e32 v11, v12, v14
	v_mul_f32_e32 v12, v13, v14
	v_mul_f32_e32 v11, v5, v11
	v_mul_f32_e32 v12, v7, v12
	v_add_u32_e32 v10, 0x1a000, v2
	v_cvt_pk_bf16_f32 v12, v11, v12
	v_mov_b32_e32 v11, v3
	v_lshl_add_u64 v[10:11], v[10:11], 1, s[6:7]
	global_store_short v[10:11], v12, off offset:768
	v_add_u32_e32 v10, 0x1a020, v2
	v_mov_b32_e32 v11, v3
	v_lshl_add_u64 v[10:11], v[10:11], 1, s[6:7]
	global_store_short_d16_hi v[10:11], v12, off offset:768
	v_mul_f32_e32 v10, v15, v14
	v_mul_f32_e32 v9, v9, v14
	v_mul_f32_e32 v10, v4, v10
	v_mul_f32_e32 v9, v6, v9
	v_cvt_pk_bf16_f32 v9, v10, v9
	v_add_u32_e32 v10, 0x1a040, v2
	v_mov_b32_e32 v11, v3
	v_lshl_add_u64 v[10:11], v[10:11], 1, s[6:7]
	global_store_short v[10:11], v9, off offset:768
	v_add_u32_e32 v10, 0x1a060, v2
	v_mov_b32_e32 v11, v3
	v_lshl_add_u64 v[10:11], v[10:11], 1, s[6:7]
	global_store_short_d16_hi v[10:11], v9, off offset:768
	ds_read_b32 v10, v8 offset:108
	ds_read2st64_b32 v[8:9], v1 offset0:15 offset1:31
	s_waitcnt lgkmcnt(0)
	v_fma_f32 v11, v83, v10, -v8
	v_fma_f32 v12, v115, v10, -v9
	ds_read2st64_b32 v[8:9], v1 offset0:47 offset1:63
	v_mul_f32_e32 v13, v12, v12
	v_fmac_f32_e32 v13, v11, v11
	s_waitcnt lgkmcnt(0)
	v_fma_f32 v1, v131, v10, -v8
	v_fmac_f32_e32 v13, v1, v1
	v_fma_f32 v10, v147, v10, -v9
	v_fmac_f32_e32 v13, v10, v10
	s_nop 1
	v_add_f32_dpp v8, v13, v13 quad_perm:[1,0,3,2] row_mask:0xf bank_mask:0xf
	s_nop 1
	v_add_f32_dpp v8, v8, v8 quad_perm:[2,3,0,1] row_mask:0xf bank_mask:0xf
	s_nop 1
	v_add_f32_dpp v8, v8, v8 row_half_mirror row_mask:0xf bank_mask:0xf
	s_nop 1
	v_add_f32_dpp v8, v8, v8 row_mirror row_mask:0xf bank_mask:0xf
	ds_swizzle_b32 v9, v8 offset:swizzle(SWAP,16)
	s_waitcnt lgkmcnt(0)
	v_add_f32_e32 v8, v8, v9
	v_fmamk_f32 v8, v8, 0x3c000000, v254
	v_cmp_gt_f32_e32 vcc, s90, v8
	v_mul_f32_e32 v9, 0x4f800000, v8
	s_nop 0
	v_cndmask_b32_e32 v8, v8, v9, vcc
	v_sqrt_f32_e32 v9, v8
	s_nop 0
	v_add_u32_e32 v13, -1, v9
	v_fma_f32 v14, -v13, v9, v8
	v_cmp_ge_f32_e64 s[4:5], 0, v14
	v_add_u32_e32 v14, 1, v9
	s_nop 0
	v_cndmask_b32_e64 v13, v9, v13, s[4:5]
	v_fma_f32 v9, -v14, v9, v8
	v_cmp_lt_f32_e64 s[4:5], 0, v9
	s_nop 1
	v_cndmask_b32_e64 v9, v13, v14, s[4:5]
	v_mul_f32_e32 v13, 0x37800000, v9
	v_cndmask_b32_e32 v9, v9, v13, vcc
	v_cmp_class_f32_e32 vcc, v8, v209
	s_nop 1
	v_cndmask_b32_e32 v8, v9, v8, vcc
	v_div_scale_f32 v9, s[4:5], v8, v8, 1.0
	v_rcp_f32_e32 v13, v9
	s_nop 0
	v_fma_f32 v14, -v9, v13, 1.0
	v_fmac_f32_e32 v13, v14, v13
	v_div_scale_f32 v14, vcc, 1.0, v8, 1.0
	v_mul_f32_e32 v15, v14, v13
	v_fma_f32 v16, -v9, v15, v14
	v_fmac_f32_e32 v15, v16, v13
	v_fma_f32 v9, -v9, v15, v14
	v_div_fmas_f32 v9, v9, v13, v15
	v_div_fixup_f32 v13, v9, v8, 1.0
	v_mul_f32_e32 v9, v11, v13
	v_mul_f32_e32 v5, v5, v9
	v_mul_f32_e32 v9, v12, v13
	v_add_u32_e32 v8, 0x1b000, v2
	v_mul_f32_e32 v7, v7, v9
	v_mov_b32_e32 v9, v3
	v_lshl_add_u64 v[8:9], v[8:9], 1, s[6:7]
	v_mul_f32_e32 v1, v1, v13
	v_cvt_pk_bf16_f32 v5, v5, v7
	global_store_short v[8:9], v5, off offset:768
	v_add_u32_e32 v8, 0x1b020, v2
	v_mov_b32_e32 v9, v3
	v_mul_f32_e32 v1, v4, v1
	v_mul_f32_e32 v4, v10, v13
	v_lshl_add_u64 v[8:9], v[8:9], 1, s[6:7]
	v_mul_f32_e32 v4, v6, v4
	global_store_short_d16_hi v[8:9], v5, off offset:768
	v_cvt_pk_bf16_f32 v1, v1, v4
	v_add_u32_e32 v4, 0x1b040, v2
	v_mov_b32_e32 v5, v3
	v_lshl_add_u64 v[4:5], v[4:5], 1, s[6:7]
	global_store_short v[4:5], v1, off offset:768
	v_add_u32_e32 v4, 0x1b060, v2
	v_mov_b32_e32 v5, v3
	v_lshl_add_u64 v[4:5], v[4:5], 1, s[6:7]
	global_store_short_d16_hi v[4:5], v1, off offset:768
